# gemm256 loops: s_setprio flips around the MMA blocks removed
# speedup vs baseline: 1.0054x; 1.0054x over previous
.LBB0_738:
	s_add_i32 s31, 32, 0x10000
	v_add_u32_e32 v153, s31, v151
	ds_read_b128 v[154:157], v153
	ds_read_b128 v[158:161], v153 offset:1024
	ds_read_b128 v[162:165], v153 offset:2048
	ds_read_b128 v[166:169], v153 offset:3072
	v_lshl_add_u64 v[178:179], v[144:145], 0, s[12:13]
	s_add_i32 s30, s19, 0xc000
	v_lshl_add_u64 v[228:229], v[178:179], 0, s[38:39]
	s_mov_b32 m0, s30
	v_lshl_add_u64 v[244:245], v[142:143], 0, s[12:13]
	s_add_i32 s17, s19, 0xe000
	ds_read_b128 v[170:173], v152
	ds_read_b128 v[174:177], v152 offset:1024
	ds_read_b128 v[204:207], v152 offset:2048
	ds_read_b128 v[208:211], v152 offset:3072
	ds_read_b128 v[212:215], v152 offset:4096
	ds_read_b128 v[216:219], v152 offset:5120
	ds_read_b128 v[220:223], v152 offset:6144
	ds_read_b128 v[224:227], v152 offset:7168
	global_load_lds_dwordx4 v[228:229], off
	v_lshl_add_u64 v[228:229], v[244:245], 0, s[38:39]
	s_mov_b32 m0, s17
	s_nop 0
	global_load_lds_dwordx4 v[228:229], off
	s_waitcnt lgkmcnt(8)
	s_barrier
	s_waitcnt lgkmcnt(0)
	s_waitcnt lgkmcnt(0)
	v_mfma_f32_16x16x32_bf16 v[124:127], v[154:157], v[170:173], v[124:127]
	v_mfma_f32_16x16x32_bf16 v[120:123], v[162:165], v[170:173], v[120:123]
	v_mfma_f32_16x16x32_bf16 v[116:119], v[154:157], v[204:207], v[116:119]
	v_mfma_f32_16x16x32_bf16 v[112:115], v[162:165], v[204:207], v[112:115]
	v_mfma_f32_16x16x32_bf16 v[108:111], v[154:157], v[212:215], v[108:111]
	v_mfma_f32_16x16x32_bf16 v[104:107], v[162:165], v[212:215], v[104:107]
	v_mfma_f32_16x16x32_bf16 v[100:103], v[154:157], v[220:223], v[100:103]
	v_mfma_f32_16x16x32_bf16 v[96:99], v[162:165], v[220:223], v[96:99]
	v_mfma_f32_16x16x32_bf16 v[124:127], v[158:161], v[174:177], v[124:127]
	v_mfma_f32_16x16x32_bf16 v[120:123], v[166:169], v[174:177], v[120:123]
	v_mfma_f32_16x16x32_bf16 v[116:119], v[158:161], v[208:211], v[116:119]
	v_mfma_f32_16x16x32_bf16 v[112:115], v[166:169], v[208:211], v[112:115]
	v_mfma_f32_16x16x32_bf16 v[108:111], v[158:161], v[216:219], v[108:111]
	v_mfma_f32_16x16x32_bf16 v[104:107], v[166:169], v[216:219], v[104:107]
	v_mfma_f32_16x16x32_bf16 v[100:103], v[158:161], v[224:227], v[100:103]
	v_mfma_f32_16x16x32_bf16 v[96:99], v[166:169], v[224:227], v[96:99]
	s_barrier
	s_add_i32 s34, 32, 0x14000
	v_lshl_add_u64 v[246:247], v[148:149], 0, s[12:13]
	s_add_i32 s31, s31, s18
	v_add_u32_e32 v153, s34, v151
	v_lshl_add_u64 v[248:249], v[246:247], 0, s[88:89]
	s_mov_b32 m0, s31
	ds_read_b128 v[228:231], v153
	ds_read_b128 v[232:235], v153 offset:1024
	ds_read_b128 v[236:239], v153 offset:2048
	ds_read_b128 v[240:243], v153 offset:3072
	global_load_lds_dwordx4 v[248:249], off
	v_lshl_add_u64 v[248:249], v[146:147], 0, s[12:13]
	v_lshl_add_u64 v[188:189], v[248:249], 0, s[88:89]
	s_add_i32 m0, s31, 0x2000
	s_nop 0
	global_load_lds_dwordx4 v[188:189], off
	s_barrier
	s_waitcnt lgkmcnt(0)
	s_waitcnt lgkmcnt(0)
	v_mfma_f32_16x16x32_bf16 v[92:95], v[228:231], v[170:173], v[92:95]
	v_mfma_f32_16x16x32_bf16 v[88:91], v[236:239], v[170:173], v[88:91]
	v_mfma_f32_16x16x32_bf16 v[84:87], v[228:231], v[204:207], v[84:87]
	v_mfma_f32_16x16x32_bf16 v[80:83], v[236:239], v[204:207], v[80:83]
	v_mfma_f32_16x16x32_bf16 v[76:79], v[228:231], v[212:215], v[76:79]
	v_mfma_f32_16x16x32_bf16 v[72:75], v[236:239], v[212:215], v[72:75]
	v_mfma_f32_16x16x32_bf16 v[68:71], v[228:231], v[220:223], v[68:71]
	v_mfma_f32_16x16x32_bf16 v[64:67], v[236:239], v[220:223], v[64:67]
	v_mfma_f32_16x16x32_bf16 v[92:95], v[232:235], v[174:177], v[92:95]
	v_mfma_f32_16x16x32_bf16 v[88:91], v[240:243], v[174:177], v[88:91]
	v_mfma_f32_16x16x32_bf16 v[84:87], v[232:235], v[208:211], v[84:87]
	v_mfma_f32_16x16x32_bf16 v[80:83], v[240:243], v[208:211], v[80:83]
	v_mfma_f32_16x16x32_bf16 v[76:79], v[232:235], v[216:219], v[76:79]
	v_mfma_f32_16x16x32_bf16 v[72:75], v[240:243], v[216:219], v[72:75]
	v_mfma_f32_16x16x32_bf16 v[68:71], v[232:235], v[224:227], v[68:71]
	v_mfma_f32_16x16x32_bf16 v[64:67], v[240:243], v[224:227], v[64:67]
	s_mov_b32 m0, s19
	v_lshl_add_u64 v[188:189], v[178:179], 0, s[88:89]
	s_barrier
	ds_read_b128 v[170:173], v152 offset:16384
	ds_read_b128 v[174:177], v152 offset:17408
	ds_read_b128 v[204:207], v152 offset:18432
	ds_read_b128 v[208:211], v152 offset:19456
	ds_read_b128 v[212:215], v152 offset:20480
	ds_read_b128 v[216:219], v152 offset:21504
	ds_read_b128 v[220:223], v152 offset:22528
	ds_read_b128 v[224:227], v152 offset:23552
	global_load_lds_dwordx4 v[188:189], off
	v_lshl_add_u64 v[188:189], v[244:245], 0, s[88:89]
	s_mov_b32 m0, s22
	s_nop 0
	global_load_lds_dwordx4 v[188:189], off
	s_barrier
	s_waitcnt lgkmcnt(0)
	s_waitcnt lgkmcnt(0)
	v_mfma_f32_16x16x32_bf16 v[60:63], v[154:157], v[170:173], v[60:63]
	v_mfma_f32_16x16x32_bf16 v[56:59], v[162:165], v[170:173], v[56:59]
	v_mfma_f32_16x16x32_bf16 v[52:55], v[154:157], v[204:207], v[52:55]
	v_mfma_f32_16x16x32_bf16 v[48:51], v[162:165], v[204:207], v[48:51]
	v_mfma_f32_16x16x32_bf16 v[44:47], v[154:157], v[212:215], v[44:47]
	v_mfma_f32_16x16x32_bf16 v[40:43], v[162:165], v[212:215], v[40:43]
	v_mfma_f32_16x16x32_bf16 v[36:39], v[154:157], v[220:223], v[36:39]
	v_mfma_f32_16x16x32_bf16 v[32:35], v[162:165], v[220:223], v[32:35]
	v_mfma_f32_16x16x32_bf16 v[60:63], v[158:161], v[174:177], v[60:63]
	v_mfma_f32_16x16x32_bf16 v[56:59], v[166:169], v[174:177], v[56:59]
	v_mfma_f32_16x16x32_bf16 v[52:55], v[158:161], v[208:211], v[52:55]
	v_mfma_f32_16x16x32_bf16 v[48:51], v[166:169], v[208:211], v[48:51]
	v_mfma_f32_16x16x32_bf16 v[44:47], v[158:161], v[216:219], v[44:47]
	v_mfma_f32_16x16x32_bf16 v[40:43], v[166:169], v[216:219], v[40:43]
	v_mfma_f32_16x16x32_bf16 v[36:39], v[158:161], v[224:227], v[36:39]
	v_mfma_f32_16x16x32_bf16 v[32:35], v[166:169], v[224:227], v[32:35]
	s_barrier
	s_add_i32 s31, s34, s18
	v_lshl_add_u64 v[154:155], v[246:247], 0, s[92:93]
	s_mov_b32 m0, s31
	s_nop 0
	global_load_lds_dwordx4 v[154:155], off
	v_lshl_add_u64 v[154:155], v[248:249], 0, s[92:93]
	s_add_i32 m0, s31, 0x2000
	s_nop 0
	global_load_lds_dwordx4 v[154:155], off
	s_waitcnt vmcnt(6)
	s_barrier
	v_mfma_f32_16x16x32_bf16 v[28:31], v[228:231], v[170:173], v[28:31]
	v_mfma_f32_16x16x32_bf16 v[24:27], v[236:239], v[170:173], v[24:27]
	v_mfma_f32_16x16x32_bf16 v[20:23], v[228:231], v[204:207], v[20:23]
	v_mfma_f32_16x16x32_bf16 v[16:19], v[236:239], v[204:207], v[16:19]
	v_mfma_f32_16x16x32_bf16 v[12:15], v[228:231], v[212:215], v[12:15]
	v_mfma_f32_16x16x32_bf16 v[8:11], v[236:239], v[212:215], v[8:11]
	v_mfma_f32_16x16x32_bf16 v[4:7], v[228:231], v[220:223], v[4:7]
	v_mfma_f32_16x16x32_bf16 v[0:3], v[236:239], v[220:223], v[0:3]
	v_mfma_f32_16x16x32_bf16 v[28:31], v[232:235], v[174:177], v[28:31]
	v_mfma_f32_16x16x32_bf16 v[24:27], v[240:243], v[174:177], v[24:27]
	v_mfma_f32_16x16x32_bf16 v[20:23], v[232:235], v[208:211], v[20:23]
	v_mfma_f32_16x16x32_bf16 v[16:19], v[240:243], v[208:211], v[16:19]
	v_mfma_f32_16x16x32_bf16 v[12:15], v[232:235], v[216:219], v[12:15]
	v_mfma_f32_16x16x32_bf16 v[8:11], v[240:243], v[216:219], v[8:11]
	v_mfma_f32_16x16x32_bf16 v[4:7], v[232:235], v[224:227], v[4:7]
	v_mfma_f32_16x16x32_bf16 v[0:3], v[240:243], v[224:227], v[0:3]
	s_add_i32 s31, 32, 0x18000
	v_add_u32_e32 v153, s31, v151
	s_barrier
	ds_read_b128 v[154:157], v153
	ds_read_b128 v[158:161], v153 offset:1024
	ds_read_b128 v[162:165], v153 offset:2048
	ds_read_b128 v[166:169], v153 offset:3072
	s_mov_b32 m0, s25
	v_lshl_add_u64 v[188:189], v[178:179], 0, s[92:93]
	ds_read_b128 v[170:173], v152 offset:32768
	ds_read_b128 v[174:177], v152 offset:33792
	ds_read_b128 v[204:207], v152 offset:34816
	ds_read_b128 v[208:211], v152 offset:35840
	ds_read_b128 v[212:215], v152 offset:36864
	ds_read_b128 v[216:219], v152 offset:37888
	ds_read_b128 v[220:223], v152 offset:38912
	ds_read_b128 v[224:227], v152 offset:39936
	global_load_lds_dwordx4 v[188:189], off
	v_lshl_add_u64 v[188:189], v[244:245], 0, s[92:93]
	s_mov_b32 m0, s26
	s_nop 0
	global_load_lds_dwordx4 v[188:189], off
	s_waitcnt lgkmcnt(8)
	s_barrier
	s_waitcnt lgkmcnt(0)
	s_waitcnt lgkmcnt(0)
	v_mfma_f32_16x16x32_bf16 v[124:127], v[154:157], v[170:173], v[124:127]
	v_mfma_f32_16x16x32_bf16 v[120:123], v[162:165], v[170:173], v[120:123]
	v_mfma_f32_16x16x32_bf16 v[116:119], v[154:157], v[204:207], v[116:119]
	v_mfma_f32_16x16x32_bf16 v[112:115], v[162:165], v[204:207], v[112:115]
	v_mfma_f32_16x16x32_bf16 v[108:111], v[154:157], v[212:215], v[108:111]
	v_mfma_f32_16x16x32_bf16 v[104:107], v[162:165], v[212:215], v[104:107]
	v_mfma_f32_16x16x32_bf16 v[100:103], v[154:157], v[220:223], v[100:103]
	v_mfma_f32_16x16x32_bf16 v[96:99], v[162:165], v[220:223], v[96:99]
	v_mfma_f32_16x16x32_bf16 v[124:127], v[158:161], v[174:177], v[124:127]
	v_mfma_f32_16x16x32_bf16 v[120:123], v[166:169], v[174:177], v[120:123]
	v_mfma_f32_16x16x32_bf16 v[116:119], v[158:161], v[208:211], v[116:119]
	v_mfma_f32_16x16x32_bf16 v[112:115], v[166:169], v[208:211], v[112:115]
	v_mfma_f32_16x16x32_bf16 v[108:111], v[158:161], v[216:219], v[108:111]
	v_mfma_f32_16x16x32_bf16 v[104:107], v[166:169], v[216:219], v[104:107]
	v_mfma_f32_16x16x32_bf16 v[100:103], v[158:161], v[224:227], v[100:103]
	v_mfma_f32_16x16x32_bf16 v[96:99], v[166:169], v[224:227], v[96:99]
	s_barrier
	s_add_i32 s34, 32, 0x1c000
	s_add_i32 s31, s31, s18
	v_add_u32_e32 v153, s34, v151
	v_lshl_add_u64 v[188:189], v[246:247], 0, s[90:91]
	s_mov_b32 m0, s31
	ds_read_b128 v[228:231], v153
	ds_read_b128 v[232:235], v153 offset:1024
	ds_read_b128 v[236:239], v153 offset:2048
	ds_read_b128 v[240:243], v153 offset:3072
	global_load_lds_dwordx4 v[188:189], off
	v_lshl_add_u64 v[188:189], v[248:249], 0, s[90:91]
	s_add_i32 m0, s31, 0x2000
	s_nop 0
	global_load_lds_dwordx4 v[188:189], off
	s_barrier
	s_waitcnt lgkmcnt(0)
	s_waitcnt lgkmcnt(0)
	v_mfma_f32_16x16x32_bf16 v[92:95], v[228:231], v[170:173], v[92:95]
	v_mfma_f32_16x16x32_bf16 v[88:91], v[236:239], v[170:173], v[88:91]
	v_mfma_f32_16x16x32_bf16 v[84:87], v[228:231], v[204:207], v[84:87]
	v_mfma_f32_16x16x32_bf16 v[80:83], v[236:239], v[204:207], v[80:83]
	v_mfma_f32_16x16x32_bf16 v[76:79], v[228:231], v[212:215], v[76:79]
	v_mfma_f32_16x16x32_bf16 v[72:75], v[236:239], v[212:215], v[72:75]
	v_mfma_f32_16x16x32_bf16 v[68:71], v[228:231], v[220:223], v[68:71]
	v_mfma_f32_16x16x32_bf16 v[64:67], v[236:239], v[220:223], v[64:67]
	v_mfma_f32_16x16x32_bf16 v[92:95], v[232:235], v[174:177], v[92:95]
	v_mfma_f32_16x16x32_bf16 v[88:91], v[240:243], v[174:177], v[88:91]
	v_mfma_f32_16x16x32_bf16 v[84:87], v[232:235], v[208:211], v[84:87]
	v_mfma_f32_16x16x32_bf16 v[80:83], v[240:243], v[208:211], v[80:83]
	v_mfma_f32_16x16x32_bf16 v[76:79], v[232:235], v[216:219], v[76:79]
	v_mfma_f32_16x16x32_bf16 v[72:75], v[240:243], v[216:219], v[72:75]
	v_mfma_f32_16x16x32_bf16 v[68:71], v[232:235], v[224:227], v[68:71]
	v_mfma_f32_16x16x32_bf16 v[64:67], v[240:243], v[224:227], v[64:67]
	s_mov_b32 m0, s14
	v_lshl_add_u64 v[178:179], v[178:179], 0, s[90:91]
	s_barrier
	ds_read_b128 v[170:173], v152 offset:49152
	ds_read_b128 v[174:177], v152 offset:50176
	ds_read_b128 v[204:207], v152 offset:51200
	ds_read_b128 v[208:211], v152 offset:52224
	ds_read_b128 v[212:215], v152 offset:53248
	ds_read_b128 v[216:219], v152 offset:54272
	ds_read_b128 v[220:223], v152 offset:55296
	ds_read_b128 v[224:227], v152 offset:56320
	global_load_lds_dwordx4 v[178:179], off
	v_lshl_add_u64 v[178:179], v[244:245], 0, s[90:91]
	s_mov_b32 m0, s15
	s_nop 0
	global_load_lds_dwordx4 v[178:179], off
	s_barrier
	s_waitcnt lgkmcnt(0)
	s_waitcnt lgkmcnt(0)
	v_mfma_f32_16x16x32_bf16 v[60:63], v[154:157], v[170:173], v[60:63]
	v_mfma_f32_16x16x32_bf16 v[56:59], v[162:165], v[170:173], v[56:59]
	v_mfma_f32_16x16x32_bf16 v[52:55], v[154:157], v[204:207], v[52:55]
	v_mfma_f32_16x16x32_bf16 v[48:51], v[162:165], v[204:207], v[48:51]
	v_mfma_f32_16x16x32_bf16 v[44:47], v[154:157], v[212:215], v[44:47]
	v_mfma_f32_16x16x32_bf16 v[40:43], v[162:165], v[212:215], v[40:43]
	v_mfma_f32_16x16x32_bf16 v[36:39], v[154:157], v[220:223], v[36:39]
	v_mfma_f32_16x16x32_bf16 v[32:35], v[162:165], v[220:223], v[32:35]
	v_mfma_f32_16x16x32_bf16 v[60:63], v[158:161], v[174:177], v[60:63]
	v_mfma_f32_16x16x32_bf16 v[56:59], v[166:169], v[174:177], v[56:59]
	v_mfma_f32_16x16x32_bf16 v[52:55], v[158:161], v[208:211], v[52:55]
	v_mfma_f32_16x16x32_bf16 v[48:51], v[166:169], v[208:211], v[48:51]
	v_mfma_f32_16x16x32_bf16 v[44:47], v[158:161], v[216:219], v[44:47]
	v_mfma_f32_16x16x32_bf16 v[40:43], v[166:169], v[216:219], v[40:43]
	v_mfma_f32_16x16x32_bf16 v[36:39], v[158:161], v[224:227], v[36:39]
	v_mfma_f32_16x16x32_bf16 v[32:35], v[166:169], v[224:227], v[32:35]
	s_barrier
	s_add_i32 s31, s34, s18
	v_lshl_add_u64 v[154:155], v[246:247], 0, s[64:65]
	s_mov_b32 m0, s31
	s_nop 0
	global_load_lds_dwordx4 v[154:155], off
	v_lshl_add_u64 v[154:155], v[248:249], 0, s[64:65]
	s_add_i32 m0, s31, 0x2000
	s_nop 0
	global_load_lds_dwordx4 v[154:155], off
	s_waitcnt vmcnt(6)
	s_barrier
	v_mfma_f32_16x16x32_bf16 v[28:31], v[228:231], v[170:173], v[28:31]
	v_mfma_f32_16x16x32_bf16 v[24:27], v[236:239], v[170:173], v[24:27]
	v_mfma_f32_16x16x32_bf16 v[20:23], v[228:231], v[204:207], v[20:23]
	v_mfma_f32_16x16x32_bf16 v[16:19], v[236:239], v[204:207], v[16:19]
	v_mfma_f32_16x16x32_bf16 v[12:15], v[228:231], v[212:215], v[12:15]
	v_mfma_f32_16x16x32_bf16 v[8:11], v[236:239], v[212:215], v[8:11]
	v_mfma_f32_16x16x32_bf16 v[4:7], v[228:231], v[220:223], v[4:7]
	v_mfma_f32_16x16x32_bf16 v[0:3], v[236:239], v[220:223], v[0:3]
	v_mfma_f32_16x16x32_bf16 v[28:31], v[232:235], v[174:177], v[28:31]
	v_mfma_f32_16x16x32_bf16 v[24:27], v[240:243], v[174:177], v[24:27]
	v_mfma_f32_16x16x32_bf16 v[20:23], v[232:235], v[208:211], v[20:23]
	v_mfma_f32_16x16x32_bf16 v[16:19], v[240:243], v[208:211], v[16:19]
	v_mfma_f32_16x16x32_bf16 v[12:15], v[232:235], v[216:219], v[12:15]
	v_mfma_f32_16x16x32_bf16 v[8:11], v[240:243], v[216:219], v[8:11]
	v_mfma_f32_16x16x32_bf16 v[4:7], v[232:235], v[224:227], v[4:7]
	v_mfma_f32_16x16x32_bf16 v[0:3], v[240:243], v[224:227], v[0:3]
	s_add_i32 s16, s16, 2
	s_add_u32 s12, s12, 0x100
	s_addc_u32 s13, s13, 0
	s_cmp_lt_u32 s16, 12
	s_barrier
	s_cbranch_scc1 .LBB0_738
	s_add_u32 s12, s6, 0x40780
	v_add_u32_e32 v153, 32, v151
	s_addc_u32 s13, s7, 0
	s_mov_b32 m0, s30
	v_add_u32_e32 v158, 0x10000, v153
	v_lshl_add_u64 v[178:179], s[12:13], 0, v[128:129]
	ds_read_b128 v[142:145], v158
	ds_read_b128 v[146:149], v158 offset:1024
	ds_read_b128 v[154:157], v158 offset:2048
	ds_read_b128 v[158:161], v158 offset:3072
	ds_read_b128 v[162:165], v152
	ds_read_b128 v[166:169], v152 offset:1024
	ds_read_b128 v[170:173], v152 offset:2048
	ds_read_b128 v[174:177], v152 offset:3072
	ds_read_b128 v[204:207], v152 offset:4096
	ds_read_b128 v[208:211], v152 offset:5120
	ds_read_b128 v[212:215], v152 offset:6144
	ds_read_b128 v[216:219], v152 offset:7168
	global_load_lds_dwordx4 v[178:179], off
	v_lshl_add_u64 v[178:179], s[12:13], 0, v[134:135]
	s_mov_b32 m0, s17
	s_nop 0
	global_load_lds_dwordx4 v[178:179], off
	s_barrier
	s_waitcnt lgkmcnt(0)
	s_waitcnt lgkmcnt(0)
	v_mfma_f32_16x16x32_bf16 v[124:127], v[142:145], v[162:165], v[124:127]
	v_mfma_f32_16x16x32_bf16 v[120:123], v[154:157], v[162:165], v[120:123]
	v_mfma_f32_16x16x32_bf16 v[116:119], v[142:145], v[170:173], v[116:119]
	v_mfma_f32_16x16x32_bf16 v[112:115], v[154:157], v[170:173], v[112:115]
	v_mfma_f32_16x16x32_bf16 v[108:111], v[142:145], v[204:207], v[108:111]
	v_mfma_f32_16x16x32_bf16 v[104:107], v[154:157], v[204:207], v[104:107]
	v_mfma_f32_16x16x32_bf16 v[100:103], v[142:145], v[212:215], v[100:103]
	v_mfma_f32_16x16x32_bf16 v[96:99], v[154:157], v[212:215], v[96:99]
	v_mfma_f32_16x16x32_bf16 v[124:127], v[146:149], v[166:169], v[124:127]
	v_mfma_f32_16x16x32_bf16 v[120:123], v[158:161], v[166:169], v[120:123]
	v_mfma_f32_16x16x32_bf16 v[116:119], v[146:149], v[174:177], v[116:119]
	v_mfma_f32_16x16x32_bf16 v[112:115], v[158:161], v[174:177], v[112:115]
	v_mfma_f32_16x16x32_bf16 v[108:111], v[146:149], v[208:211], v[108:111]
	v_mfma_f32_16x16x32_bf16 v[104:107], v[158:161], v[208:211], v[104:107]
	v_mfma_f32_16x16x32_bf16 v[100:103], v[146:149], v[216:219], v[100:103]
	v_mfma_f32_16x16x32_bf16 v[96:99], v[158:161], v[216:219], v[96:99]
	v_add_u32_e32 v178, 0x14000, v153
	s_barrier
	ds_read_b128 v[220:223], v178
	ds_read_b128 v[224:227], v178 offset:1024
	ds_read_b128 v[228:231], v178 offset:2048
	ds_read_b128 v[232:235], v178 offset:3072
	s_barrier
	s_waitcnt lgkmcnt(0)
	s_waitcnt lgkmcnt(0)
	v_mfma_f32_16x16x32_bf16 v[92:95], v[220:223], v[162:165], v[92:95]
	v_mfma_f32_16x16x32_bf16 v[88:91], v[228:231], v[162:165], v[88:91]
	v_mfma_f32_16x16x32_bf16 v[84:87], v[220:223], v[170:173], v[84:87]
	v_mfma_f32_16x16x32_bf16 v[80:83], v[228:231], v[170:173], v[80:83]
	v_mfma_f32_16x16x32_bf16 v[76:79], v[220:223], v[204:207], v[76:79]
	v_mfma_f32_16x16x32_bf16 v[72:75], v[228:231], v[204:207], v[72:75]
	v_mfma_f32_16x16x32_bf16 v[68:71], v[220:223], v[212:215], v[68:71]
	v_mfma_f32_16x16x32_bf16 v[64:67], v[228:231], v[212:215], v[64:67]
	v_mfma_f32_16x16x32_bf16 v[92:95], v[224:227], v[166:169], v[92:95]
	v_mfma_f32_16x16x32_bf16 v[88:91], v[232:235], v[166:169], v[88:91]
	v_mfma_f32_16x16x32_bf16 v[84:87], v[224:227], v[174:177], v[84:87]
	v_mfma_f32_16x16x32_bf16 v[80:83], v[232:235], v[174:177], v[80:83]
	v_mfma_f32_16x16x32_bf16 v[76:79], v[224:227], v[208:211], v[76:79]
	v_mfma_f32_16x16x32_bf16 v[72:75], v[232:235], v[208:211], v[72:75]
	v_mfma_f32_16x16x32_bf16 v[68:71], v[224:227], v[216:219], v[68:71]
	v_mfma_f32_16x16x32_bf16 v[64:67], v[232:235], v[216:219], v[64:67]
	s_barrier
	ds_read_b128 v[162:165], v152 offset:16384
	ds_read_b128 v[166:169], v152 offset:17408
	ds_read_b128 v[170:173], v152 offset:18432
	ds_read_b128 v[174:177], v152 offset:19456
	ds_read_b128 v[204:207], v152 offset:20480
	ds_read_b128 v[208:211], v152 offset:21504
	ds_read_b128 v[212:215], v152 offset:22528
	ds_read_b128 v[216:219], v152 offset:23552
	s_waitcnt vmcnt(4)
	s_barrier
	s_waitcnt lgkmcnt(0)
	s_waitcnt lgkmcnt(0)
	v_mfma_f32_16x16x32_bf16 v[60:63], v[142:145], v[162:165], v[60:63]
	v_mfma_f32_16x16x32_bf16 v[56:59], v[154:157], v[162:165], v[56:59]
	v_mfma_f32_16x16x32_bf16 v[52:55], v[142:145], v[170:173], v[52:55]
	v_mfma_f32_16x16x32_bf16 v[48:51], v[154:157], v[170:173], v[48:51]
	v_mfma_f32_16x16x32_bf16 v[44:47], v[142:145], v[204:207], v[44:47]
	v_mfma_f32_16x16x32_bf16 v[40:43], v[154:157], v[204:207], v[40:43]
	v_mfma_f32_16x16x32_bf16 v[36:39], v[142:145], v[212:215], v[36:39]
	v_mfma_f32_16x16x32_bf16 v[32:35], v[154:157], v[212:215], v[32:35]
	v_mfma_f32_16x16x32_bf16 v[60:63], v[146:149], v[166:169], v[60:63]
	v_mfma_f32_16x16x32_bf16 v[56:59], v[158:161], v[166:169], v[56:59]
	v_mfma_f32_16x16x32_bf16 v[52:55], v[146:149], v[174:177], v[52:55]
	v_mfma_f32_16x16x32_bf16 v[48:51], v[158:161], v[174:177], v[48:51]
	v_mfma_f32_16x16x32_bf16 v[44:47], v[146:149], v[208:211], v[44:47]
	v_mfma_f32_16x16x32_bf16 v[40:43], v[158:161], v[208:211], v[40:43]
	v_mfma_f32_16x16x32_bf16 v[36:39], v[146:149], v[216:219], v[36:39]
	v_mfma_f32_16x16x32_bf16 v[32:35], v[158:161], v[216:219], v[32:35]
	v_mfma_f32_16x16x32_bf16 v[28:31], v[220:223], v[162:165], v[28:31]
	v_mfma_f32_16x16x32_bf16 v[24:27], v[228:231], v[162:165], v[24:27]
	v_mfma_f32_16x16x32_bf16 v[20:23], v[220:223], v[170:173], v[20:23]
	v_mfma_f32_16x16x32_bf16 v[16:19], v[228:231], v[170:173], v[16:19]
	v_mfma_f32_16x16x32_bf16 v[12:15], v[220:223], v[204:207], v[12:15]
	v_mfma_f32_16x16x32_bf16 v[8:11], v[228:231], v[204:207], v[8:11]
	v_mfma_f32_16x16x32_bf16 v[4:7], v[220:223], v[212:215], v[4:7]
	v_mfma_f32_16x16x32_bf16 v[0:3], v[228:231], v[212:215], v[0:3]
	v_mfma_f32_16x16x32_bf16 v[28:31], v[224:227], v[166:169], v[28:31]
	v_mfma_f32_16x16x32_bf16 v[24:27], v[232:235], v[166:169], v[24:27]
	v_mfma_f32_16x16x32_bf16 v[20:23], v[224:227], v[174:177], v[20:23]
	v_mfma_f32_16x16x32_bf16 v[16:19], v[232:235], v[174:177], v[16:19]
	v_mfma_f32_16x16x32_bf16 v[12:15], v[224:227], v[208:211], v[12:15]
	v_mfma_f32_16x16x32_bf16 v[8:11], v[232:235], v[208:211], v[8:11]
	v_mfma_f32_16x16x32_bf16 v[4:7], v[224:227], v[216:219], v[4:7]
	v_mfma_f32_16x16x32_bf16 v[0:3], v[232:235], v[216:219], v[0:3]
	v_add_u32_e32 v158, 0x18000, v153
	s_barrier
	ds_read_b128 v[142:145], v158
	ds_read_b128 v[146:149], v158 offset:1024
	ds_read_b128 v[154:157], v158 offset:2048
	ds_read_b128 v[158:161], v158 offset:3072
	ds_read_b128 v[162:165], v152 offset:32768
	ds_read_b128 v[166:169], v152 offset:33792
	ds_read_b128 v[170:173], v152 offset:34816
	ds_read_b128 v[174:177], v152 offset:35840
	ds_read_b128 v[204:207], v152 offset:36864
	ds_read_b128 v[208:211], v152 offset:37888
	ds_read_b128 v[212:215], v152 offset:38912
	ds_read_b128 v[216:219], v152 offset:39936
	s_waitcnt vmcnt(2)
	s_barrier
	s_waitcnt lgkmcnt(0)
	s_waitcnt lgkmcnt(0)
	v_mfma_f32_16x16x32_bf16 v[124:127], v[142:145], v[162:165], v[124:127]
	v_mfma_f32_16x16x32_bf16 v[120:123], v[154:157], v[162:165], v[120:123]
	v_mfma_f32_16x16x32_bf16 v[116:119], v[142:145], v[170:173], v[116:119]
	v_mfma_f32_16x16x32_bf16 v[112:115], v[154:157], v[170:173], v[112:115]
	v_mfma_f32_16x16x32_bf16 v[108:111], v[142:145], v[204:207], v[108:111]
	v_mfma_f32_16x16x32_bf16 v[104:107], v[154:157], v[204:207], v[104:107]
	v_mfma_f32_16x16x32_bf16 v[100:103], v[142:145], v[212:215], v[100:103]
	v_mfma_f32_16x16x32_bf16 v[96:99], v[154:157], v[212:215], v[96:99]
	v_mfma_f32_16x16x32_bf16 v[124:127], v[146:149], v[166:169], v[124:127]
	v_mfma_f32_16x16x32_bf16 v[120:123], v[158:161], v[166:169], v[120:123]
	v_mfma_f32_16x16x32_bf16 v[116:119], v[146:149], v[174:177], v[116:119]
	v_mfma_f32_16x16x32_bf16 v[112:115], v[158:161], v[174:177], v[112:115]
	v_mfma_f32_16x16x32_bf16 v[108:111], v[146:149], v[208:211], v[108:111]
	v_mfma_f32_16x16x32_bf16 v[104:107], v[158:161], v[208:211], v[104:107]
	v_mfma_f32_16x16x32_bf16 v[100:103], v[146:149], v[216:219], v[100:103]
	v_mfma_f32_16x16x32_bf16 v[96:99], v[158:161], v[216:219], v[96:99]
	v_add_u32_e32 v153, 0x1c000, v153
	s_barrier
	ds_read_b128 v[220:223], v153
	ds_read_b128 v[224:227], v153 offset:1024
	ds_read_b128 v[228:231], v153 offset:2048
	ds_read_b128 v[232:235], v153 offset:3072
	s_waitcnt vmcnt(0)
	s_barrier
	s_waitcnt lgkmcnt(0)
	s_waitcnt lgkmcnt(0)
	v_mfma_f32_16x16x32_bf16 v[92:95], v[220:223], v[162:165], v[92:95]
	v_mfma_f32_16x16x32_bf16 v[88:91], v[228:231], v[162:165], v[88:91]
	v_mfma_f32_16x16x32_bf16 v[84:87], v[220:223], v[170:173], v[84:87]
	v_mfma_f32_16x16x32_bf16 v[80:83], v[228:231], v[170:173], v[80:83]
	v_mfma_f32_16x16x32_bf16 v[76:79], v[220:223], v[204:207], v[76:79]
	v_mfma_f32_16x16x32_bf16 v[72:75], v[228:231], v[204:207], v[72:75]
	v_mfma_f32_16x16x32_bf16 v[68:71], v[220:223], v[212:215], v[68:71]
	v_mfma_f32_16x16x32_bf16 v[64:67], v[228:231], v[212:215], v[64:67]
	v_mfma_f32_16x16x32_bf16 v[92:95], v[224:227], v[166:169], v[92:95]
	v_mfma_f32_16x16x32_bf16 v[88:91], v[232:235], v[166:169], v[88:91]
	v_mfma_f32_16x16x32_bf16 v[84:87], v[224:227], v[174:177], v[84:87]
	v_mfma_f32_16x16x32_bf16 v[80:83], v[232:235], v[174:177], v[80:83]
	v_mfma_f32_16x16x32_bf16 v[76:79], v[224:227], v[208:211], v[76:79]
	v_mfma_f32_16x16x32_bf16 v[72:75], v[232:235], v[208:211], v[72:75]
	v_mfma_f32_16x16x32_bf16 v[68:71], v[224:227], v[216:219], v[68:71]
	v_mfma_f32_16x16x32_bf16 v[64:67], v[232:235], v[216:219], v[64:67]
	s_barrier
	ds_read_b128 v[162:165], v152 offset:49152
	ds_read_b128 v[166:169], v152 offset:50176
	ds_read_b128 v[170:173], v152 offset:51200
	ds_read_b128 v[174:177], v152 offset:52224
	ds_read_b128 v[204:207], v152 offset:53248
	ds_read_b128 v[208:211], v152 offset:54272
	ds_read_b128 v[212:215], v152 offset:55296
	ds_read_b128 v[216:219], v152 offset:56320
	s_barrier
	s_waitcnt lgkmcnt(0)
	s_waitcnt lgkmcnt(0)
	v_mfma_f32_16x16x32_bf16 v[60:63], v[142:145], v[162:165], v[60:63]
	v_mfma_f32_16x16x32_bf16 v[56:59], v[154:157], v[162:165], v[56:59]
	v_mfma_f32_16x16x32_bf16 v[52:55], v[142:145], v[170:173], v[52:55]
	v_mfma_f32_16x16x32_bf16 v[48:51], v[154:157], v[170:173], v[48:51]
	v_mfma_f32_16x16x32_bf16 v[44:47], v[142:145], v[204:207], v[44:47]
	v_mfma_f32_16x16x32_bf16 v[40:43], v[154:157], v[204:207], v[40:43]
	v_mfma_f32_16x16x32_bf16 v[36:39], v[142:145], v[212:215], v[36:39]
	v_mfma_f32_16x16x32_bf16 v[32:35], v[154:157], v[212:215], v[32:35]
	v_mfma_f32_16x16x32_bf16 v[60:63], v[146:149], v[166:169], v[60:63]
	v_mfma_f32_16x16x32_bf16 v[56:59], v[158:161], v[166:169], v[56:59]
	v_mfma_f32_16x16x32_bf16 v[52:55], v[146:149], v[174:177], v[52:55]
	v_mfma_f32_16x16x32_bf16 v[48:51], v[158:161], v[174:177], v[48:51]
	v_mfma_f32_16x16x32_bf16 v[44:47], v[146:149], v[208:211], v[44:47]
	v_mfma_f32_16x16x32_bf16 v[40:43], v[158:161], v[208:211], v[40:43]
	v_mfma_f32_16x16x32_bf16 v[36:39], v[146:149], v[216:219], v[36:39]
	v_mfma_f32_16x16x32_bf16 v[32:35], v[158:161], v[216:219], v[32:35]
	v_mfma_f32_16x16x32_bf16 v[28:31], v[220:223], v[162:165], v[28:31]
	v_mfma_f32_16x16x32_bf16 v[24:27], v[228:231], v[162:165], v[24:27]
	v_mfma_f32_16x16x32_bf16 v[20:23], v[220:223], v[170:173], v[20:23]
	v_mfma_f32_16x16x32_bf16 v[16:19], v[228:231], v[170:173], v[16:19]
	v_mfma_f32_16x16x32_bf16 v[12:15], v[220:223], v[204:207], v[12:15]
	v_mfma_f32_16x16x32_bf16 v[8:11], v[228:231], v[204:207], v[8:11]
	v_mfma_f32_16x16x32_bf16 v[4:7], v[220:223], v[212:215], v[4:7]
	v_mfma_f32_16x16x32_bf16 v[0:3], v[228:231], v[212:215], v[0:3]
	v_mfma_f32_16x16x32_bf16 v[28:31], v[224:227], v[166:169], v[28:31]
	v_mfma_f32_16x16x32_bf16 v[24:27], v[232:235], v[166:169], v[24:27]
	v_mfma_f32_16x16x32_bf16 v[20:23], v[224:227], v[174:177], v[20:23]
	v_mfma_f32_16x16x32_bf16 v[16:19], v[232:235], v[174:177], v[16:19]
	v_mfma_f32_16x16x32_bf16 v[12:15], v[224:227], v[208:211], v[12:15]
	v_mfma_f32_16x16x32_bf16 v[8:11], v[232:235], v[208:211], v[8:11]
	v_mfma_f32_16x16x32_bf16 v[4:7], v[224:227], v[216:219], v[4:7]
	v_mfma_f32_16x16x32_bf16 v[0:3], v[232:235], v[216:219], v[0:3]
	s_barrier
	s_and_saveexec_b64 s[12:13], s[2:3]
	s_cbranch_execz .LBB0_741
	s_barrier

.LBB0_803:
	s_add_i32 s31, 32, 0x10000
	v_add_u32_e32 v151, s31, v148
	ds_read_b128 v[152:155], v151
	ds_read_b128 v[156:159], v151 offset:1024
	ds_read_b128 v[160:163], v151 offset:2048
	ds_read_b128 v[164:167], v151 offset:3072
	v_lshl_add_u64 v[188:189], v[144:145], 0, s[6:7]
	s_add_i32 s30, s17, 0xc000
	v_lshl_add_u64 v[224:225], v[188:189], 0, s[38:39]
	s_mov_b32 m0, s30
	v_lshl_add_u64 v[240:241], v[146:147], 0, s[6:7]
	s_add_i32 s29, s17, 0xe000
	ds_read_b128 v[168:171], v150
	ds_read_b128 v[172:175], v150 offset:1024
	ds_read_b128 v[176:179], v150 offset:2048
	ds_read_b128 v[204:207], v150 offset:3072
	ds_read_b128 v[208:211], v150 offset:4096
	ds_read_b128 v[212:215], v150 offset:5120
	ds_read_b128 v[216:219], v150 offset:6144
	ds_read_b128 v[220:223], v150 offset:7168
	global_load_lds_dwordx4 v[224:225], off
	v_lshl_add_u64 v[224:225], v[240:241], 0, s[38:39]
	s_mov_b32 m0, s29
	s_nop 0
	global_load_lds_dwordx4 v[224:225], off
	s_waitcnt lgkmcnt(8)
	s_barrier
	s_waitcnt lgkmcnt(0)
	s_waitcnt lgkmcnt(0)
	v_mfma_f32_16x16x32_bf16 v[124:127], v[152:155], v[168:171], v[124:127]
	v_mfma_f32_16x16x32_bf16 v[120:123], v[160:163], v[168:171], v[120:123]
	v_mfma_f32_16x16x32_bf16 v[116:119], v[152:155], v[176:179], v[116:119]
	v_mfma_f32_16x16x32_bf16 v[112:115], v[160:163], v[176:179], v[112:115]
	v_mfma_f32_16x16x32_bf16 v[108:111], v[152:155], v[208:211], v[108:111]
	v_mfma_f32_16x16x32_bf16 v[104:107], v[160:163], v[208:211], v[104:107]
	v_mfma_f32_16x16x32_bf16 v[100:103], v[152:155], v[216:219], v[100:103]
	v_mfma_f32_16x16x32_bf16 v[96:99], v[160:163], v[216:219], v[96:99]
	v_mfma_f32_16x16x32_bf16 v[124:127], v[156:159], v[172:175], v[124:127]
	v_mfma_f32_16x16x32_bf16 v[120:123], v[164:167], v[172:175], v[120:123]
	v_mfma_f32_16x16x32_bf16 v[116:119], v[156:159], v[204:207], v[116:119]
	v_mfma_f32_16x16x32_bf16 v[112:115], v[164:167], v[204:207], v[112:115]
	v_mfma_f32_16x16x32_bf16 v[108:111], v[156:159], v[212:215], v[108:111]
	v_mfma_f32_16x16x32_bf16 v[104:107], v[164:167], v[212:215], v[104:107]
	v_mfma_f32_16x16x32_bf16 v[100:103], v[156:159], v[220:223], v[100:103]
	v_mfma_f32_16x16x32_bf16 v[96:99], v[164:167], v[220:223], v[96:99]
	s_barrier
	s_add_i32 s34, 32, 0x14000
	v_lshl_add_u64 v[242:243], v[140:141], 0, s[6:7]
	s_add_i32 s31, s31, s16
	v_add_u32_e32 v151, s34, v148
	v_lshl_add_u64 v[244:245], v[242:243], 0, s[88:89]
	s_mov_b32 m0, s31
	ds_read_b128 v[224:227], v151
	ds_read_b128 v[228:231], v151 offset:1024
	ds_read_b128 v[232:235], v151 offset:2048
	ds_read_b128 v[236:239], v151 offset:3072
	global_load_lds_dwordx4 v[244:245], off
	v_lshl_add_u64 v[244:245], v[142:143], 0, s[6:7]
	v_lshl_add_u64 v[246:247], v[244:245], 0, s[88:89]
	s_add_i32 m0, s31, 0x2000
	s_nop 0
	global_load_lds_dwordx4 v[246:247], off
	s_barrier
	s_waitcnt lgkmcnt(0)
	s_waitcnt lgkmcnt(0)
	v_mfma_f32_16x16x32_bf16 v[92:95], v[224:227], v[168:171], v[92:95]
	v_mfma_f32_16x16x32_bf16 v[88:91], v[232:235], v[168:171], v[88:91]
	v_mfma_f32_16x16x32_bf16 v[84:87], v[224:227], v[176:179], v[84:87]
	v_mfma_f32_16x16x32_bf16 v[80:83], v[232:235], v[176:179], v[80:83]
	v_mfma_f32_16x16x32_bf16 v[76:79], v[224:227], v[208:211], v[76:79]
	v_mfma_f32_16x16x32_bf16 v[72:75], v[232:235], v[208:211], v[72:75]
	v_mfma_f32_16x16x32_bf16 v[68:71], v[224:227], v[216:219], v[68:71]
	v_mfma_f32_16x16x32_bf16 v[64:67], v[232:235], v[216:219], v[64:67]
	v_mfma_f32_16x16x32_bf16 v[92:95], v[228:231], v[172:175], v[92:95]
	v_mfma_f32_16x16x32_bf16 v[88:91], v[236:239], v[172:175], v[88:91]
	v_mfma_f32_16x16x32_bf16 v[84:87], v[228:231], v[204:207], v[84:87]
	v_mfma_f32_16x16x32_bf16 v[80:83], v[236:239], v[204:207], v[80:83]
	v_mfma_f32_16x16x32_bf16 v[76:79], v[228:231], v[212:215], v[76:79]
	v_mfma_f32_16x16x32_bf16 v[72:75], v[236:239], v[212:215], v[72:75]
	v_mfma_f32_16x16x32_bf16 v[68:71], v[228:231], v[220:223], v[68:71]
	v_mfma_f32_16x16x32_bf16 v[64:67], v[236:239], v[220:223], v[64:67]
	s_mov_b32 m0, s17
	v_lshl_add_u64 v[246:247], v[188:189], 0, s[88:89]
	s_barrier
	ds_read_b128 v[168:171], v150 offset:16384
	ds_read_b128 v[172:175], v150 offset:17408
	ds_read_b128 v[176:179], v150 offset:18432
	ds_read_b128 v[204:207], v150 offset:19456
	ds_read_b128 v[208:211], v150 offset:20480
	ds_read_b128 v[212:215], v150 offset:21504
	ds_read_b128 v[216:219], v150 offset:22528
	ds_read_b128 v[220:223], v150 offset:23552
	global_load_lds_dwordx4 v[246:247], off
	v_lshl_add_u64 v[246:247], v[240:241], 0, s[88:89]
	s_mov_b32 m0, s20
	s_nop 0
	global_load_lds_dwordx4 v[246:247], off
	s_barrier
	s_waitcnt lgkmcnt(0)
	s_waitcnt lgkmcnt(0)
	v_mfma_f32_16x16x32_bf16 v[60:63], v[152:155], v[168:171], v[60:63]
	v_mfma_f32_16x16x32_bf16 v[56:59], v[160:163], v[168:171], v[56:59]
	v_mfma_f32_16x16x32_bf16 v[52:55], v[152:155], v[176:179], v[52:55]
	v_mfma_f32_16x16x32_bf16 v[48:51], v[160:163], v[176:179], v[48:51]
	v_mfma_f32_16x16x32_bf16 v[44:47], v[152:155], v[208:211], v[44:47]
	v_mfma_f32_16x16x32_bf16 v[40:43], v[160:163], v[208:211], v[40:43]
	v_mfma_f32_16x16x32_bf16 v[36:39], v[152:155], v[216:219], v[36:39]
	v_mfma_f32_16x16x32_bf16 v[32:35], v[160:163], v[216:219], v[32:35]
	v_mfma_f32_16x16x32_bf16 v[60:63], v[156:159], v[172:175], v[60:63]
	v_mfma_f32_16x16x32_bf16 v[56:59], v[164:167], v[172:175], v[56:59]
	v_mfma_f32_16x16x32_bf16 v[52:55], v[156:159], v[204:207], v[52:55]
	v_mfma_f32_16x16x32_bf16 v[48:51], v[164:167], v[204:207], v[48:51]
	v_mfma_f32_16x16x32_bf16 v[44:47], v[156:159], v[212:215], v[44:47]
	v_mfma_f32_16x16x32_bf16 v[40:43], v[164:167], v[212:215], v[40:43]
	v_mfma_f32_16x16x32_bf16 v[36:39], v[156:159], v[220:223], v[36:39]
	v_mfma_f32_16x16x32_bf16 v[32:35], v[164:167], v[220:223], v[32:35]
	s_barrier
	s_add_i32 s31, s34, s16
	v_lshl_add_u64 v[152:153], v[242:243], 0, s[48:49]
	s_mov_b32 m0, s31
	s_nop 0
	global_load_lds_dwordx4 v[152:153], off
	v_lshl_add_u64 v[152:153], v[244:245], 0, s[48:49]
	s_add_i32 m0, s31, 0x2000
	s_nop 0
	global_load_lds_dwordx4 v[152:153], off
	s_waitcnt vmcnt(6)
	s_barrier
	v_mfma_f32_16x16x32_bf16 v[28:31], v[224:227], v[168:171], v[28:31]
	v_mfma_f32_16x16x32_bf16 v[24:27], v[232:235], v[168:171], v[24:27]
	v_mfma_f32_16x16x32_bf16 v[20:23], v[224:227], v[176:179], v[20:23]
	v_mfma_f32_16x16x32_bf16 v[16:19], v[232:235], v[176:179], v[16:19]
	v_mfma_f32_16x16x32_bf16 v[12:15], v[224:227], v[208:211], v[12:15]
	v_mfma_f32_16x16x32_bf16 v[8:11], v[232:235], v[208:211], v[8:11]
	v_mfma_f32_16x16x32_bf16 v[4:7], v[224:227], v[216:219], v[4:7]
	v_mfma_f32_16x16x32_bf16 v[0:3], v[232:235], v[216:219], v[0:3]
	v_mfma_f32_16x16x32_bf16 v[28:31], v[228:231], v[172:175], v[28:31]
	v_mfma_f32_16x16x32_bf16 v[24:27], v[236:239], v[172:175], v[24:27]
	v_mfma_f32_16x16x32_bf16 v[20:23], v[228:231], v[204:207], v[20:23]
	v_mfma_f32_16x16x32_bf16 v[16:19], v[236:239], v[204:207], v[16:19]
	v_mfma_f32_16x16x32_bf16 v[12:15], v[228:231], v[212:215], v[12:15]
	v_mfma_f32_16x16x32_bf16 v[8:11], v[236:239], v[212:215], v[8:11]
	v_mfma_f32_16x16x32_bf16 v[4:7], v[228:231], v[220:223], v[4:7]
	v_mfma_f32_16x16x32_bf16 v[0:3], v[236:239], v[220:223], v[0:3]
	s_add_i32 s31, 32, 0x18000
	v_add_u32_e32 v151, s31, v148
	s_barrier
	ds_read_b128 v[152:155], v151
	ds_read_b128 v[156:159], v151 offset:1024
	ds_read_b128 v[160:163], v151 offset:2048
	ds_read_b128 v[164:167], v151 offset:3072
	s_mov_b32 m0, s23
	v_lshl_add_u64 v[224:225], v[188:189], 0, s[48:49]
	ds_read_b128 v[168:171], v150 offset:32768
	ds_read_b128 v[172:175], v150 offset:33792
	ds_read_b128 v[176:179], v150 offset:34816
	ds_read_b128 v[204:207], v150 offset:35840
	ds_read_b128 v[208:211], v150 offset:36864
	ds_read_b128 v[212:215], v150 offset:37888
	ds_read_b128 v[216:219], v150 offset:38912
	ds_read_b128 v[220:223], v150 offset:39936
	global_load_lds_dwordx4 v[224:225], off
	v_lshl_add_u64 v[224:225], v[240:241], 0, s[48:49]
	s_mov_b32 m0, s24
	s_nop 0
	global_load_lds_dwordx4 v[224:225], off
	s_waitcnt lgkmcnt(8)
	s_barrier
	s_waitcnt lgkmcnt(0)
	s_waitcnt lgkmcnt(0)
	v_mfma_f32_16x16x32_bf16 v[124:127], v[152:155], v[168:171], v[124:127]
	v_mfma_f32_16x16x32_bf16 v[120:123], v[160:163], v[168:171], v[120:123]
	v_mfma_f32_16x16x32_bf16 v[116:119], v[152:155], v[176:179], v[116:119]
	v_mfma_f32_16x16x32_bf16 v[112:115], v[160:163], v[176:179], v[112:115]
	v_mfma_f32_16x16x32_bf16 v[108:111], v[152:155], v[208:211], v[108:111]
	v_mfma_f32_16x16x32_bf16 v[104:107], v[160:163], v[208:211], v[104:107]
	v_mfma_f32_16x16x32_bf16 v[100:103], v[152:155], v[216:219], v[100:103]
	v_mfma_f32_16x16x32_bf16 v[96:99], v[160:163], v[216:219], v[96:99]
	v_mfma_f32_16x16x32_bf16 v[124:127], v[156:159], v[172:175], v[124:127]
	v_mfma_f32_16x16x32_bf16 v[120:123], v[164:167], v[172:175], v[120:123]
	v_mfma_f32_16x16x32_bf16 v[116:119], v[156:159], v[204:207], v[116:119]
	v_mfma_f32_16x16x32_bf16 v[112:115], v[164:167], v[204:207], v[112:115]
	v_mfma_f32_16x16x32_bf16 v[108:111], v[156:159], v[212:215], v[108:111]
	v_mfma_f32_16x16x32_bf16 v[104:107], v[164:167], v[212:215], v[104:107]
	v_mfma_f32_16x16x32_bf16 v[100:103], v[156:159], v[220:223], v[100:103]
	v_mfma_f32_16x16x32_bf16 v[96:99], v[164:167], v[220:223], v[96:99]
	s_barrier
	s_add_i32 s34, 32, 0x1c000
	s_add_i32 s31, s31, s16
	v_add_u32_e32 v151, s34, v148
	v_lshl_add_u64 v[246:247], v[242:243], 0, s[90:91]
	s_mov_b32 m0, s31
	ds_read_b128 v[224:227], v151
	ds_read_b128 v[228:231], v151 offset:1024
	ds_read_b128 v[232:235], v151 offset:2048
	ds_read_b128 v[236:239], v151 offset:3072
	global_load_lds_dwordx4 v[246:247], off
	v_lshl_add_u64 v[246:247], v[244:245], 0, s[90:91]
	s_add_i32 m0, s31, 0x2000
	s_nop 0
	global_load_lds_dwordx4 v[246:247], off
	s_barrier
	s_waitcnt lgkmcnt(0)
	s_waitcnt lgkmcnt(0)
	v_mfma_f32_16x16x32_bf16 v[92:95], v[224:227], v[168:171], v[92:95]
	v_mfma_f32_16x16x32_bf16 v[88:91], v[232:235], v[168:171], v[88:91]
	v_mfma_f32_16x16x32_bf16 v[84:87], v[224:227], v[176:179], v[84:87]
	v_mfma_f32_16x16x32_bf16 v[80:83], v[232:235], v[176:179], v[80:83]
	v_mfma_f32_16x16x32_bf16 v[76:79], v[224:227], v[208:211], v[76:79]
	v_mfma_f32_16x16x32_bf16 v[72:75], v[232:235], v[208:211], v[72:75]
	v_mfma_f32_16x16x32_bf16 v[68:71], v[224:227], v[216:219], v[68:71]
	v_mfma_f32_16x16x32_bf16 v[64:67], v[232:235], v[216:219], v[64:67]
	v_mfma_f32_16x16x32_bf16 v[92:95], v[228:231], v[172:175], v[92:95]
	v_mfma_f32_16x16x32_bf16 v[88:91], v[236:239], v[172:175], v[88:91]
	v_mfma_f32_16x16x32_bf16 v[84:87], v[228:231], v[204:207], v[84:87]
	v_mfma_f32_16x16x32_bf16 v[80:83], v[236:239], v[204:207], v[80:83]
	v_mfma_f32_16x16x32_bf16 v[76:79], v[228:231], v[212:215], v[76:79]
	v_mfma_f32_16x16x32_bf16 v[72:75], v[236:239], v[212:215], v[72:75]
	v_mfma_f32_16x16x32_bf16 v[68:71], v[228:231], v[220:223], v[68:71]
	v_mfma_f32_16x16x32_bf16 v[64:67], v[236:239], v[220:223], v[64:67]
	s_mov_b32 m0, s14
	v_lshl_add_u64 v[188:189], v[188:189], 0, s[90:91]
	s_barrier
	ds_read_b128 v[168:171], v150 offset:49152
	ds_read_b128 v[172:175], v150 offset:50176
	ds_read_b128 v[176:179], v150 offset:51200
	ds_read_b128 v[204:207], v150 offset:52224
	ds_read_b128 v[208:211], v150 offset:53248
	ds_read_b128 v[212:215], v150 offset:54272
	ds_read_b128 v[216:219], v150 offset:55296
	ds_read_b128 v[220:223], v150 offset:56320
	global_load_lds_dwordx4 v[188:189], off
	v_lshl_add_u64 v[188:189], v[240:241], 0, s[90:91]
	s_mov_b32 m0, s15
	s_nop 0
	global_load_lds_dwordx4 v[188:189], off
	s_barrier
	s_waitcnt lgkmcnt(0)
	s_waitcnt lgkmcnt(0)
	v_mfma_f32_16x16x32_bf16 v[60:63], v[152:155], v[168:171], v[60:63]
	v_mfma_f32_16x16x32_bf16 v[56:59], v[160:163], v[168:171], v[56:59]
	v_mfma_f32_16x16x32_bf16 v[52:55], v[152:155], v[176:179], v[52:55]
	v_mfma_f32_16x16x32_bf16 v[48:51], v[160:163], v[176:179], v[48:51]
	v_mfma_f32_16x16x32_bf16 v[44:47], v[152:155], v[208:211], v[44:47]
	v_mfma_f32_16x16x32_bf16 v[40:43], v[160:163], v[208:211], v[40:43]
	v_mfma_f32_16x16x32_bf16 v[36:39], v[152:155], v[216:219], v[36:39]
	v_mfma_f32_16x16x32_bf16 v[32:35], v[160:163], v[216:219], v[32:35]
	v_mfma_f32_16x16x32_bf16 v[60:63], v[156:159], v[172:175], v[60:63]
	v_mfma_f32_16x16x32_bf16 v[56:59], v[164:167], v[172:175], v[56:59]
	v_mfma_f32_16x16x32_bf16 v[52:55], v[156:159], v[204:207], v[52:55]
	v_mfma_f32_16x16x32_bf16 v[48:51], v[164:167], v[204:207], v[48:51]
	v_mfma_f32_16x16x32_bf16 v[44:47], v[156:159], v[212:215], v[44:47]
	v_mfma_f32_16x16x32_bf16 v[40:43], v[164:167], v[212:215], v[40:43]
	v_mfma_f32_16x16x32_bf16 v[36:39], v[156:159], v[220:223], v[36:39]
	v_mfma_f32_16x16x32_bf16 v[32:35], v[164:167], v[220:223], v[32:35]
	s_barrier
	s_add_i32 s31, s34, s16
	v_lshl_add_u64 v[152:153], v[242:243], 0, s[50:51]
	s_mov_b32 m0, s31
	s_nop 0
	global_load_lds_dwordx4 v[152:153], off
	v_lshl_add_u64 v[152:153], v[244:245], 0, s[50:51]
	s_add_i32 m0, s31, 0x2000
	s_nop 0
	global_load_lds_dwordx4 v[152:153], off
	s_waitcnt vmcnt(6)
	s_barrier
	v_mfma_f32_16x16x32_bf16 v[28:31], v[224:227], v[168:171], v[28:31]
	v_mfma_f32_16x16x32_bf16 v[24:27], v[232:235], v[168:171], v[24:27]
	v_mfma_f32_16x16x32_bf16 v[20:23], v[224:227], v[176:179], v[20:23]
	v_mfma_f32_16x16x32_bf16 v[16:19], v[232:235], v[176:179], v[16:19]
	v_mfma_f32_16x16x32_bf16 v[12:15], v[224:227], v[208:211], v[12:15]
	v_mfma_f32_16x16x32_bf16 v[8:11], v[232:235], v[208:211], v[8:11]
	v_mfma_f32_16x16x32_bf16 v[4:7], v[224:227], v[216:219], v[4:7]
	v_mfma_f32_16x16x32_bf16 v[0:3], v[232:235], v[216:219], v[0:3]
	v_mfma_f32_16x16x32_bf16 v[28:31], v[228:231], v[172:175], v[28:31]
	v_mfma_f32_16x16x32_bf16 v[24:27], v[236:239], v[172:175], v[24:27]
	v_mfma_f32_16x16x32_bf16 v[20:23], v[228:231], v[204:207], v[20:23]
	v_mfma_f32_16x16x32_bf16 v[16:19], v[236:239], v[204:207], v[16:19]
	v_mfma_f32_16x16x32_bf16 v[12:15], v[228:231], v[212:215], v[12:15]
	v_mfma_f32_16x16x32_bf16 v[8:11], v[236:239], v[212:215], v[8:11]
	v_mfma_f32_16x16x32_bf16 v[4:7], v[228:231], v[220:223], v[4:7]
	v_mfma_f32_16x16x32_bf16 v[0:3], v[236:239], v[220:223], v[0:3]
	s_add_i32 s28, s28, 2
	s_add_u32 s6, s6, 0x100
	s_addc_u32 s7, s7, 0
	s_cmp_gt_u32 s28, 39
	s_barrier
	s_cbranch_scc0 .LBB0_803
	s_add_u32 s6, s12, 0xb1580
	v_add_u32_e32 v151, 32, v148
	s_addc_u32 s7, s13, 0
	s_mov_b32 m0, s30
	v_add_u32_e32 v156, 0x10000, v151
	v_lshl_add_u64 v[188:189], s[6:7], 0, v[128:129]
	ds_read_b128 v[140:143], v156
	ds_read_b128 v[144:147], v156 offset:1024
	ds_read_b128 v[152:155], v156 offset:2048
	ds_read_b128 v[156:159], v156 offset:3072
	ds_read_b128 v[160:163], v150
	ds_read_b128 v[164:167], v150 offset:1024
	ds_read_b128 v[168:171], v150 offset:2048
	ds_read_b128 v[172:175], v150 offset:3072
	ds_read_b128 v[176:179], v150 offset:4096
	ds_read_b128 v[204:207], v150 offset:5120
	ds_read_b128 v[208:211], v150 offset:6144
	ds_read_b128 v[212:215], v150 offset:7168
	global_load_lds_dwordx4 v[188:189], off
	v_lshl_add_u64 v[188:189], s[6:7], 0, v[134:135]
	s_mov_b32 m0, s29
	s_nop 0
	global_load_lds_dwordx4 v[188:189], off
	s_barrier
	s_waitcnt lgkmcnt(0)
	s_waitcnt lgkmcnt(0)
	v_mfma_f32_16x16x32_bf16 v[124:127], v[140:143], v[160:163], v[124:127]
	v_mfma_f32_16x16x32_bf16 v[120:123], v[152:155], v[160:163], v[120:123]
	v_mfma_f32_16x16x32_bf16 v[116:119], v[140:143], v[168:171], v[116:119]
	v_mfma_f32_16x16x32_bf16 v[112:115], v[152:155], v[168:171], v[112:115]
	v_mfma_f32_16x16x32_bf16 v[108:111], v[140:143], v[176:179], v[108:111]
	v_mfma_f32_16x16x32_bf16 v[104:107], v[152:155], v[176:179], v[104:107]
	v_mfma_f32_16x16x32_bf16 v[100:103], v[140:143], v[208:211], v[100:103]
	v_mfma_f32_16x16x32_bf16 v[96:99], v[152:155], v[208:211], v[96:99]
	v_mfma_f32_16x16x32_bf16 v[124:127], v[144:147], v[164:167], v[124:127]
	v_mfma_f32_16x16x32_bf16 v[120:123], v[156:159], v[164:167], v[120:123]
	v_mfma_f32_16x16x32_bf16 v[116:119], v[144:147], v[172:175], v[116:119]
	v_mfma_f32_16x16x32_bf16 v[112:115], v[156:159], v[172:175], v[112:115]
	v_mfma_f32_16x16x32_bf16 v[108:111], v[144:147], v[204:207], v[108:111]
	v_mfma_f32_16x16x32_bf16 v[104:107], v[156:159], v[204:207], v[104:107]
	v_mfma_f32_16x16x32_bf16 v[100:103], v[144:147], v[212:215], v[100:103]
	v_mfma_f32_16x16x32_bf16 v[96:99], v[156:159], v[212:215], v[96:99]
	v_add_u32_e32 v188, 0x14000, v151
	s_barrier
	ds_read_b128 v[216:219], v188
	ds_read_b128 v[220:223], v188 offset:1024
	ds_read_b128 v[224:227], v188 offset:2048
	ds_read_b128 v[228:231], v188 offset:3072
	s_barrier
	s_waitcnt lgkmcnt(0)
	s_waitcnt lgkmcnt(0)
	v_mfma_f32_16x16x32_bf16 v[92:95], v[216:219], v[160:163], v[92:95]
	v_mfma_f32_16x16x32_bf16 v[88:91], v[224:227], v[160:163], v[88:91]
	v_mfma_f32_16x16x32_bf16 v[84:87], v[216:219], v[168:171], v[84:87]
	v_mfma_f32_16x16x32_bf16 v[80:83], v[224:227], v[168:171], v[80:83]
	v_mfma_f32_16x16x32_bf16 v[76:79], v[216:219], v[176:179], v[76:79]
	v_mfma_f32_16x16x32_bf16 v[72:75], v[224:227], v[176:179], v[72:75]
	v_mfma_f32_16x16x32_bf16 v[68:71], v[216:219], v[208:211], v[68:71]
	v_mfma_f32_16x16x32_bf16 v[64:67], v[224:227], v[208:211], v[64:67]
	v_mfma_f32_16x16x32_bf16 v[92:95], v[220:223], v[164:167], v[92:95]
	v_mfma_f32_16x16x32_bf16 v[88:91], v[228:231], v[164:167], v[88:91]
	v_mfma_f32_16x16x32_bf16 v[84:87], v[220:223], v[172:175], v[84:87]
	v_mfma_f32_16x16x32_bf16 v[80:83], v[228:231], v[172:175], v[80:83]
	v_mfma_f32_16x16x32_bf16 v[76:79], v[220:223], v[204:207], v[76:79]
	v_mfma_f32_16x16x32_bf16 v[72:75], v[228:231], v[204:207], v[72:75]
	v_mfma_f32_16x16x32_bf16 v[68:71], v[220:223], v[212:215], v[68:71]
	v_mfma_f32_16x16x32_bf16 v[64:67], v[228:231], v[212:215], v[64:67]
	s_barrier
	ds_read_b128 v[160:163], v150 offset:16384
	ds_read_b128 v[164:167], v150 offset:17408
	ds_read_b128 v[168:171], v150 offset:18432
	ds_read_b128 v[172:175], v150 offset:19456
	ds_read_b128 v[176:179], v150 offset:20480
	ds_read_b128 v[204:207], v150 offset:21504
	ds_read_b128 v[208:211], v150 offset:22528
	ds_read_b128 v[212:215], v150 offset:23552
	s_waitcnt vmcnt(4)
	s_barrier
	s_waitcnt lgkmcnt(0)
	s_waitcnt lgkmcnt(0)
	v_mfma_f32_16x16x32_bf16 v[60:63], v[140:143], v[160:163], v[60:63]
	v_mfma_f32_16x16x32_bf16 v[56:59], v[152:155], v[160:163], v[56:59]
	v_mfma_f32_16x16x32_bf16 v[52:55], v[140:143], v[168:171], v[52:55]
	v_mfma_f32_16x16x32_bf16 v[48:51], v[152:155], v[168:171], v[48:51]
	v_mfma_f32_16x16x32_bf16 v[44:47], v[140:143], v[176:179], v[44:47]
	v_mfma_f32_16x16x32_bf16 v[40:43], v[152:155], v[176:179], v[40:43]
	v_mfma_f32_16x16x32_bf16 v[36:39], v[140:143], v[208:211], v[36:39]
	v_mfma_f32_16x16x32_bf16 v[32:35], v[152:155], v[208:211], v[32:35]
	v_mfma_f32_16x16x32_bf16 v[60:63], v[144:147], v[164:167], v[60:63]
	v_mfma_f32_16x16x32_bf16 v[56:59], v[156:159], v[164:167], v[56:59]
	v_mfma_f32_16x16x32_bf16 v[52:55], v[144:147], v[172:175], v[52:55]
	v_mfma_f32_16x16x32_bf16 v[48:51], v[156:159], v[172:175], v[48:51]
	v_mfma_f32_16x16x32_bf16 v[44:47], v[144:147], v[204:207], v[44:47]
	v_mfma_f32_16x16x32_bf16 v[40:43], v[156:159], v[204:207], v[40:43]
	v_mfma_f32_16x16x32_bf16 v[36:39], v[144:147], v[212:215], v[36:39]
	v_mfma_f32_16x16x32_bf16 v[32:35], v[156:159], v[212:215], v[32:35]
	v_mfma_f32_16x16x32_bf16 v[28:31], v[216:219], v[160:163], v[28:31]
	v_mfma_f32_16x16x32_bf16 v[24:27], v[224:227], v[160:163], v[24:27]
	v_mfma_f32_16x16x32_bf16 v[20:23], v[216:219], v[168:171], v[20:23]
	v_mfma_f32_16x16x32_bf16 v[16:19], v[224:227], v[168:171], v[16:19]
	v_mfma_f32_16x16x32_bf16 v[12:15], v[216:219], v[176:179], v[12:15]
	v_mfma_f32_16x16x32_bf16 v[8:11], v[224:227], v[176:179], v[8:11]
	v_mfma_f32_16x16x32_bf16 v[4:7], v[216:219], v[208:211], v[4:7]
	v_mfma_f32_16x16x32_bf16 v[0:3], v[224:227], v[208:211], v[0:3]
	v_mfma_f32_16x16x32_bf16 v[28:31], v[220:223], v[164:167], v[28:31]
	v_mfma_f32_16x16x32_bf16 v[24:27], v[228:231], v[164:167], v[24:27]
	v_mfma_f32_16x16x32_bf16 v[20:23], v[220:223], v[172:175], v[20:23]
	v_mfma_f32_16x16x32_bf16 v[16:19], v[228:231], v[172:175], v[16:19]
	v_mfma_f32_16x16x32_bf16 v[12:15], v[220:223], v[204:207], v[12:15]
	v_mfma_f32_16x16x32_bf16 v[8:11], v[228:231], v[204:207], v[8:11]
	v_mfma_f32_16x16x32_bf16 v[4:7], v[220:223], v[212:215], v[4:7]
	v_mfma_f32_16x16x32_bf16 v[0:3], v[228:231], v[212:215], v[0:3]
	v_add_u32_e32 v156, 0x18000, v151
	s_barrier
	ds_read_b128 v[140:143], v156
	ds_read_b128 v[144:147], v156 offset:1024
	ds_read_b128 v[152:155], v156 offset:2048
	ds_read_b128 v[156:159], v156 offset:3072
	ds_read_b128 v[160:163], v150 offset:32768
	ds_read_b128 v[164:167], v150 offset:33792
	ds_read_b128 v[168:171], v150 offset:34816
	ds_read_b128 v[172:175], v150 offset:35840
	ds_read_b128 v[176:179], v150 offset:36864
	ds_read_b128 v[204:207], v150 offset:37888
	ds_read_b128 v[208:211], v150 offset:38912
	ds_read_b128 v[212:215], v150 offset:39936
	s_waitcnt vmcnt(2)
	s_barrier
	s_waitcnt lgkmcnt(0)
	s_waitcnt lgkmcnt(0)
	v_mfma_f32_16x16x32_bf16 v[124:127], v[140:143], v[160:163], v[124:127]
	v_mfma_f32_16x16x32_bf16 v[120:123], v[152:155], v[160:163], v[120:123]
	v_mfma_f32_16x16x32_bf16 v[116:119], v[140:143], v[168:171], v[116:119]
	v_mfma_f32_16x16x32_bf16 v[112:115], v[152:155], v[168:171], v[112:115]
	v_mfma_f32_16x16x32_bf16 v[108:111], v[140:143], v[176:179], v[108:111]
	v_mfma_f32_16x16x32_bf16 v[104:107], v[152:155], v[176:179], v[104:107]
	v_mfma_f32_16x16x32_bf16 v[100:103], v[140:143], v[208:211], v[100:103]
	v_mfma_f32_16x16x32_bf16 v[96:99], v[152:155], v[208:211], v[96:99]
	v_mfma_f32_16x16x32_bf16 v[124:127], v[144:147], v[164:167], v[124:127]
	v_mfma_f32_16x16x32_bf16 v[120:123], v[156:159], v[164:167], v[120:123]
	v_mfma_f32_16x16x32_bf16 v[116:119], v[144:147], v[172:175], v[116:119]
	v_mfma_f32_16x16x32_bf16 v[112:115], v[156:159], v[172:175], v[112:115]
	v_mfma_f32_16x16x32_bf16 v[108:111], v[144:147], v[204:207], v[108:111]
	v_mfma_f32_16x16x32_bf16 v[104:107], v[156:159], v[204:207], v[104:107]
	v_mfma_f32_16x16x32_bf16 v[100:103], v[144:147], v[212:215], v[100:103]
	v_mfma_f32_16x16x32_bf16 v[96:99], v[156:159], v[212:215], v[96:99]
	v_add_u32_e32 v151, 0x1c000, v151
	s_barrier
	ds_read_b128 v[216:219], v151
	ds_read_b128 v[220:223], v151 offset:1024
	ds_read_b128 v[224:227], v151 offset:2048
	ds_read_b128 v[228:231], v151 offset:3072
	s_waitcnt vmcnt(0)
	s_barrier
	s_waitcnt lgkmcnt(0)
	s_waitcnt lgkmcnt(0)
	v_mfma_f32_16x16x32_bf16 v[92:95], v[216:219], v[160:163], v[92:95]
	v_mfma_f32_16x16x32_bf16 v[88:91], v[224:227], v[160:163], v[88:91]
	v_mfma_f32_16x16x32_bf16 v[84:87], v[216:219], v[168:171], v[84:87]
	v_mfma_f32_16x16x32_bf16 v[80:83], v[224:227], v[168:171], v[80:83]
	v_mfma_f32_16x16x32_bf16 v[76:79], v[216:219], v[176:179], v[76:79]
	v_mfma_f32_16x16x32_bf16 v[72:75], v[224:227], v[176:179], v[72:75]
	v_mfma_f32_16x16x32_bf16 v[68:71], v[216:219], v[208:211], v[68:71]
	v_mfma_f32_16x16x32_bf16 v[64:67], v[224:227], v[208:211], v[64:67]
	v_mfma_f32_16x16x32_bf16 v[92:95], v[220:223], v[164:167], v[92:95]
	v_mfma_f32_16x16x32_bf16 v[88:91], v[228:231], v[164:167], v[88:91]
	v_mfma_f32_16x16x32_bf16 v[84:87], v[220:223], v[172:175], v[84:87]
	v_mfma_f32_16x16x32_bf16 v[80:83], v[228:231], v[172:175], v[80:83]
	v_mfma_f32_16x16x32_bf16 v[76:79], v[220:223], v[204:207], v[76:79]
	v_mfma_f32_16x16x32_bf16 v[72:75], v[228:231], v[204:207], v[72:75]
	v_mfma_f32_16x16x32_bf16 v[68:71], v[220:223], v[212:215], v[68:71]
	v_mfma_f32_16x16x32_bf16 v[64:67], v[228:231], v[212:215], v[64:67]
	s_barrier
	ds_read_b128 v[160:163], v150 offset:49152
	ds_read_b128 v[164:167], v150 offset:50176
	ds_read_b128 v[168:171], v150 offset:51200
	ds_read_b128 v[172:175], v150 offset:52224
	ds_read_b128 v[176:179], v150 offset:53248
	ds_read_b128 v[204:207], v150 offset:54272
	ds_read_b128 v[208:211], v150 offset:55296
	ds_read_b128 v[212:215], v150 offset:56320
	s_barrier
	s_waitcnt lgkmcnt(0)
	s_waitcnt lgkmcnt(0)
	v_mfma_f32_16x16x32_bf16 v[60:63], v[140:143], v[160:163], v[60:63]
	v_mfma_f32_16x16x32_bf16 v[56:59], v[152:155], v[160:163], v[56:59]
	v_mfma_f32_16x16x32_bf16 v[52:55], v[140:143], v[168:171], v[52:55]
	v_mfma_f32_16x16x32_bf16 v[48:51], v[152:155], v[168:171], v[48:51]
	v_mfma_f32_16x16x32_bf16 v[44:47], v[140:143], v[176:179], v[44:47]
	v_mfma_f32_16x16x32_bf16 v[40:43], v[152:155], v[176:179], v[40:43]
	v_mfma_f32_16x16x32_bf16 v[36:39], v[140:143], v[208:211], v[36:39]
	v_mfma_f32_16x16x32_bf16 v[32:35], v[152:155], v[208:211], v[32:35]
	v_mfma_f32_16x16x32_bf16 v[60:63], v[144:147], v[164:167], v[60:63]
	v_mfma_f32_16x16x32_bf16 v[56:59], v[156:159], v[164:167], v[56:59]
	v_mfma_f32_16x16x32_bf16 v[52:55], v[144:147], v[172:175], v[52:55]
	v_mfma_f32_16x16x32_bf16 v[48:51], v[156:159], v[172:175], v[48:51]
	v_mfma_f32_16x16x32_bf16 v[44:47], v[144:147], v[204:207], v[44:47]
	v_mfma_f32_16x16x32_bf16 v[40:43], v[156:159], v[204:207], v[40:43]
	v_mfma_f32_16x16x32_bf16 v[36:39], v[144:147], v[212:215], v[36:39]
	v_mfma_f32_16x16x32_bf16 v[32:35], v[156:159], v[212:215], v[32:35]
	v_mfma_f32_16x16x32_bf16 v[28:31], v[216:219], v[160:163], v[28:31]
	v_mfma_f32_16x16x32_bf16 v[24:27], v[224:227], v[160:163], v[24:27]
	v_mfma_f32_16x16x32_bf16 v[20:23], v[216:219], v[168:171], v[20:23]
	v_mfma_f32_16x16x32_bf16 v[16:19], v[224:227], v[168:171], v[16:19]
	v_mfma_f32_16x16x32_bf16 v[12:15], v[216:219], v[176:179], v[12:15]
	v_mfma_f32_16x16x32_bf16 v[8:11], v[224:227], v[176:179], v[8:11]
	v_mfma_f32_16x16x32_bf16 v[4:7], v[216:219], v[208:211], v[4:7]
	v_mfma_f32_16x16x32_bf16 v[0:3], v[224:227], v[208:211], v[0:3]
	v_mfma_f32_16x16x32_bf16 v[28:31], v[220:223], v[164:167], v[28:31]
	v_mfma_f32_16x16x32_bf16 v[24:27], v[228:231], v[164:167], v[24:27]
	v_mfma_f32_16x16x32_bf16 v[20:23], v[220:223], v[172:175], v[20:23]
	v_mfma_f32_16x16x32_bf16 v[16:19], v[228:231], v[172:175], v[16:19]
	v_mfma_f32_16x16x32_bf16 v[12:15], v[220:223], v[204:207], v[12:15]
	v_mfma_f32_16x16x32_bf16 v[8:11], v[228:231], v[204:207], v[8:11]
	v_mfma_f32_16x16x32_bf16 v[4:7], v[220:223], v[212:215], v[4:7]
	v_mfma_f32_16x16x32_bf16 v[0:3], v[228:231], v[212:215], v[0:3]
	s_barrier
	s_and_saveexec_b64 s[6:7], s[4:5]
	s_cbranch_execz .LBB0_806
	s_barrier

.LBB0_940:
	s_add_i32 s16, 32, 0x10000
	v_add_u32_e32 v153, s16, v151
	ds_read_b128 v[154:157], v153
	ds_read_b128 v[158:161], v153 offset:1024
	ds_read_b128 v[162:165], v153 offset:2048
	ds_read_b128 v[166:169], v153 offset:3072
	v_lshl_add_u64 v[178:179], v[144:145], 0, s[6:7]
	s_add_i32 s15, s21, 0xc000
	v_lshl_add_u64 v[188:189], v[178:179], 0, s[30:31]
	s_mov_b32 m0, s15
	ds_read_b128 v[170:173], v152
	ds_read_b128 v[174:177], v152 offset:1024
	ds_read_b128 v[204:207], v152 offset:2048
	ds_read_b128 v[208:211], v152 offset:3072
	ds_read_b128 v[212:215], v152 offset:4096
	ds_read_b128 v[216:219], v152 offset:5120
	ds_read_b128 v[220:223], v152 offset:6144
	ds_read_b128 v[224:227], v152 offset:7168
	global_load_lds_dwordx4 v[188:189], off
	v_lshl_add_u64 v[188:189], v[142:143], 0, s[6:7]
	s_add_i32 s14, s21, 0xe000
	v_lshl_add_u64 v[228:229], v[188:189], 0, s[30:31]
	s_mov_b32 m0, s14
	s_nop 0
	global_load_lds_dwordx4 v[228:229], off
	s_waitcnt lgkmcnt(8)
	s_barrier
	s_waitcnt lgkmcnt(0)
	s_waitcnt lgkmcnt(0)
	v_mfma_f32_16x16x32_bf16 v[124:127], v[154:157], v[170:173], v[124:127]
	v_mfma_f32_16x16x32_bf16 v[120:123], v[162:165], v[170:173], v[120:123]
	v_mfma_f32_16x16x32_bf16 v[116:119], v[154:157], v[204:207], v[116:119]
	v_mfma_f32_16x16x32_bf16 v[112:115], v[162:165], v[204:207], v[112:115]
	v_mfma_f32_16x16x32_bf16 v[108:111], v[154:157], v[212:215], v[108:111]
	v_mfma_f32_16x16x32_bf16 v[104:107], v[162:165], v[212:215], v[104:107]
	v_mfma_f32_16x16x32_bf16 v[100:103], v[154:157], v[220:223], v[100:103]
	v_mfma_f32_16x16x32_bf16 v[96:99], v[162:165], v[220:223], v[96:99]
	v_mfma_f32_16x16x32_bf16 v[124:127], v[158:161], v[174:177], v[124:127]
	v_mfma_f32_16x16x32_bf16 v[120:123], v[166:169], v[174:177], v[120:123]
	v_mfma_f32_16x16x32_bf16 v[116:119], v[158:161], v[208:211], v[116:119]
	v_mfma_f32_16x16x32_bf16 v[112:115], v[166:169], v[208:211], v[112:115]
	v_mfma_f32_16x16x32_bf16 v[108:111], v[158:161], v[216:219], v[108:111]
	v_mfma_f32_16x16x32_bf16 v[104:107], v[166:169], v[216:219], v[104:107]
	v_mfma_f32_16x16x32_bf16 v[100:103], v[158:161], v[224:227], v[100:103]
	v_mfma_f32_16x16x32_bf16 v[96:99], v[166:169], v[224:227], v[96:99]
	s_barrier
	s_add_i32 s17, 32, 0x14000
	v_lshl_add_u64 v[244:245], v[148:149], 0, s[6:7]
	s_add_i32 s16, s16, s20
	v_add_u32_e32 v153, s17, v151
	v_lshl_add_u64 v[246:247], v[244:245], 0, s[88:89]
	s_mov_b32 m0, s16
	ds_read_b128 v[228:231], v153
	ds_read_b128 v[232:235], v153 offset:1024
	ds_read_b128 v[236:239], v153 offset:2048
	ds_read_b128 v[240:243], v153 offset:3072
	global_load_lds_dwordx4 v[246:247], off
	v_lshl_add_u64 v[246:247], v[146:147], 0, s[6:7]
	v_lshl_add_u64 v[248:249], v[246:247], 0, s[88:89]
	s_add_i32 m0, s16, 0x2000
	s_nop 0
	global_load_lds_dwordx4 v[248:249], off
	s_barrier
	s_waitcnt lgkmcnt(0)
	s_waitcnt lgkmcnt(0)
	v_mfma_f32_16x16x32_bf16 v[92:95], v[228:231], v[170:173], v[92:95]
	v_mfma_f32_16x16x32_bf16 v[88:91], v[236:239], v[170:173], v[88:91]
	v_mfma_f32_16x16x32_bf16 v[84:87], v[228:231], v[204:207], v[84:87]
	v_mfma_f32_16x16x32_bf16 v[80:83], v[236:239], v[204:207], v[80:83]
	v_mfma_f32_16x16x32_bf16 v[76:79], v[228:231], v[212:215], v[76:79]
	v_mfma_f32_16x16x32_bf16 v[72:75], v[236:239], v[212:215], v[72:75]
	v_mfma_f32_16x16x32_bf16 v[68:71], v[228:231], v[220:223], v[68:71]
	v_mfma_f32_16x16x32_bf16 v[64:67], v[236:239], v[220:223], v[64:67]
	v_mfma_f32_16x16x32_bf16 v[92:95], v[232:235], v[174:177], v[92:95]
	v_mfma_f32_16x16x32_bf16 v[88:91], v[240:243], v[174:177], v[88:91]
	v_mfma_f32_16x16x32_bf16 v[84:87], v[232:235], v[208:211], v[84:87]
	v_mfma_f32_16x16x32_bf16 v[80:83], v[240:243], v[208:211], v[80:83]
	v_mfma_f32_16x16x32_bf16 v[76:79], v[232:235], v[216:219], v[76:79]
	v_mfma_f32_16x16x32_bf16 v[72:75], v[240:243], v[216:219], v[72:75]
	v_mfma_f32_16x16x32_bf16 v[68:71], v[232:235], v[224:227], v[68:71]
	v_mfma_f32_16x16x32_bf16 v[64:67], v[240:243], v[224:227], v[64:67]
	s_mov_b32 m0, s21
	v_lshl_add_u64 v[248:249], v[178:179], 0, s[88:89]
	s_barrier
	ds_read_b128 v[170:173], v152 offset:16384
	ds_read_b128 v[174:177], v152 offset:17408
	ds_read_b128 v[204:207], v152 offset:18432
	ds_read_b128 v[208:211], v152 offset:19456
	ds_read_b128 v[212:215], v152 offset:20480
	ds_read_b128 v[216:219], v152 offset:21504
	ds_read_b128 v[220:223], v152 offset:22528
	ds_read_b128 v[224:227], v152 offset:23552
	global_load_lds_dwordx4 v[248:249], off
	v_lshl_add_u64 v[248:249], v[188:189], 0, s[88:89]
	s_mov_b32 m0, s24
	s_nop 0
	global_load_lds_dwordx4 v[248:249], off
	s_barrier
	s_waitcnt lgkmcnt(0)
	s_waitcnt lgkmcnt(0)
	v_mfma_f32_16x16x32_bf16 v[60:63], v[154:157], v[170:173], v[60:63]
	v_mfma_f32_16x16x32_bf16 v[56:59], v[162:165], v[170:173], v[56:59]
	v_mfma_f32_16x16x32_bf16 v[52:55], v[154:157], v[204:207], v[52:55]
	v_mfma_f32_16x16x32_bf16 v[48:51], v[162:165], v[204:207], v[48:51]
	v_mfma_f32_16x16x32_bf16 v[44:47], v[154:157], v[212:215], v[44:47]
	v_mfma_f32_16x16x32_bf16 v[40:43], v[162:165], v[212:215], v[40:43]
	v_mfma_f32_16x16x32_bf16 v[36:39], v[154:157], v[220:223], v[36:39]
	v_mfma_f32_16x16x32_bf16 v[32:35], v[162:165], v[220:223], v[32:35]
	v_mfma_f32_16x16x32_bf16 v[60:63], v[158:161], v[174:177], v[60:63]
	v_mfma_f32_16x16x32_bf16 v[56:59], v[166:169], v[174:177], v[56:59]
	v_mfma_f32_16x16x32_bf16 v[52:55], v[158:161], v[208:211], v[52:55]
	v_mfma_f32_16x16x32_bf16 v[48:51], v[166:169], v[208:211], v[48:51]
	v_mfma_f32_16x16x32_bf16 v[44:47], v[158:161], v[216:219], v[44:47]
	v_mfma_f32_16x16x32_bf16 v[40:43], v[166:169], v[216:219], v[40:43]
	v_mfma_f32_16x16x32_bf16 v[36:39], v[158:161], v[224:227], v[36:39]
	v_mfma_f32_16x16x32_bf16 v[32:35], v[166:169], v[224:227], v[32:35]
	s_barrier
	s_add_i32 s16, s17, s20
	v_lshl_add_u64 v[154:155], v[244:245], 0, s[92:93]
	s_mov_b32 m0, s16
	s_nop 0
	global_load_lds_dwordx4 v[154:155], off
	v_lshl_add_u64 v[154:155], v[246:247], 0, s[92:93]
	s_add_i32 m0, s16, 0x2000
	s_nop 0
	global_load_lds_dwordx4 v[154:155], off
	s_waitcnt vmcnt(6)
	s_barrier
	v_mfma_f32_16x16x32_bf16 v[28:31], v[228:231], v[170:173], v[28:31]
	v_mfma_f32_16x16x32_bf16 v[24:27], v[236:239], v[170:173], v[24:27]
	v_mfma_f32_16x16x32_bf16 v[20:23], v[228:231], v[204:207], v[20:23]
	v_mfma_f32_16x16x32_bf16 v[16:19], v[236:239], v[204:207], v[16:19]
	v_mfma_f32_16x16x32_bf16 v[12:15], v[228:231], v[212:215], v[12:15]
	v_mfma_f32_16x16x32_bf16 v[8:11], v[236:239], v[212:215], v[8:11]
	v_mfma_f32_16x16x32_bf16 v[4:7], v[228:231], v[220:223], v[4:7]
	v_mfma_f32_16x16x32_bf16 v[0:3], v[236:239], v[220:223], v[0:3]
	v_mfma_f32_16x16x32_bf16 v[28:31], v[232:235], v[174:177], v[28:31]
	v_mfma_f32_16x16x32_bf16 v[24:27], v[240:243], v[174:177], v[24:27]
	v_mfma_f32_16x16x32_bf16 v[20:23], v[232:235], v[208:211], v[20:23]
	v_mfma_f32_16x16x32_bf16 v[16:19], v[240:243], v[208:211], v[16:19]
	v_mfma_f32_16x16x32_bf16 v[12:15], v[232:235], v[216:219], v[12:15]
	v_mfma_f32_16x16x32_bf16 v[8:11], v[240:243], v[216:219], v[8:11]
	v_mfma_f32_16x16x32_bf16 v[4:7], v[232:235], v[224:227], v[4:7]
	v_mfma_f32_16x16x32_bf16 v[0:3], v[240:243], v[224:227], v[0:3]
	s_add_i32 s16, 32, 0x18000
	v_add_u32_e32 v153, s16, v151
	s_barrier
	ds_read_b128 v[154:157], v153
	ds_read_b128 v[158:161], v153 offset:1024
	ds_read_b128 v[162:165], v153 offset:2048
	ds_read_b128 v[166:169], v153 offset:3072
	s_mov_b32 m0, s27
	v_lshl_add_u64 v[228:229], v[178:179], 0, s[92:93]
	ds_read_b128 v[170:173], v152 offset:32768
	ds_read_b128 v[174:177], v152 offset:33792
	ds_read_b128 v[204:207], v152 offset:34816
	ds_read_b128 v[208:211], v152 offset:35840
	ds_read_b128 v[212:215], v152 offset:36864
	ds_read_b128 v[216:219], v152 offset:37888
	ds_read_b128 v[220:223], v152 offset:38912
	ds_read_b128 v[224:227], v152 offset:39936
	global_load_lds_dwordx4 v[228:229], off
	v_lshl_add_u64 v[228:229], v[188:189], 0, s[92:93]
	s_mov_b32 m0, s28
	s_nop 0
	global_load_lds_dwordx4 v[228:229], off
	s_waitcnt lgkmcnt(8)
	s_barrier
	s_waitcnt lgkmcnt(0)
	s_waitcnt lgkmcnt(0)
	v_mfma_f32_16x16x32_bf16 v[124:127], v[154:157], v[170:173], v[124:127]
	v_mfma_f32_16x16x32_bf16 v[120:123], v[162:165], v[170:173], v[120:123]
	v_mfma_f32_16x16x32_bf16 v[116:119], v[154:157], v[204:207], v[116:119]
	v_mfma_f32_16x16x32_bf16 v[112:115], v[162:165], v[204:207], v[112:115]
	v_mfma_f32_16x16x32_bf16 v[108:111], v[154:157], v[212:215], v[108:111]
	v_mfma_f32_16x16x32_bf16 v[104:107], v[162:165], v[212:215], v[104:107]
	v_mfma_f32_16x16x32_bf16 v[100:103], v[154:157], v[220:223], v[100:103]
	v_mfma_f32_16x16x32_bf16 v[96:99], v[162:165], v[220:223], v[96:99]
	v_mfma_f32_16x16x32_bf16 v[124:127], v[158:161], v[174:177], v[124:127]
	v_mfma_f32_16x16x32_bf16 v[120:123], v[166:169], v[174:177], v[120:123]
	v_mfma_f32_16x16x32_bf16 v[116:119], v[158:161], v[208:211], v[116:119]
	v_mfma_f32_16x16x32_bf16 v[112:115], v[166:169], v[208:211], v[112:115]
	v_mfma_f32_16x16x32_bf16 v[108:111], v[158:161], v[216:219], v[108:111]
	v_mfma_f32_16x16x32_bf16 v[104:107], v[166:169], v[216:219], v[104:107]
	v_mfma_f32_16x16x32_bf16 v[100:103], v[158:161], v[224:227], v[100:103]
	v_mfma_f32_16x16x32_bf16 v[96:99], v[166:169], v[224:227], v[96:99]
	s_barrier
	s_add_i32 s17, 32, 0x1c000
	s_add_i32 s16, s16, s20
	v_add_u32_e32 v153, s17, v151
	v_lshl_add_u64 v[248:249], v[244:245], 0, s[90:91]
	s_mov_b32 m0, s16
	ds_read_b128 v[228:231], v153
	ds_read_b128 v[232:235], v153 offset:1024
	ds_read_b128 v[236:239], v153 offset:2048
	ds_read_b128 v[240:243], v153 offset:3072
	global_load_lds_dwordx4 v[248:249], off
	v_lshl_add_u64 v[248:249], v[246:247], 0, s[90:91]
	s_add_i32 m0, s16, 0x2000
	s_nop 0
	global_load_lds_dwordx4 v[248:249], off
	s_barrier
	s_waitcnt lgkmcnt(0)
	s_waitcnt lgkmcnt(0)
	v_mfma_f32_16x16x32_bf16 v[92:95], v[228:231], v[170:173], v[92:95]
	v_mfma_f32_16x16x32_bf16 v[88:91], v[236:239], v[170:173], v[88:91]
	v_mfma_f32_16x16x32_bf16 v[84:87], v[228:231], v[204:207], v[84:87]
	v_mfma_f32_16x16x32_bf16 v[80:83], v[236:239], v[204:207], v[80:83]
	v_mfma_f32_16x16x32_bf16 v[76:79], v[228:231], v[212:215], v[76:79]
	v_mfma_f32_16x16x32_bf16 v[72:75], v[236:239], v[212:215], v[72:75]
	v_mfma_f32_16x16x32_bf16 v[68:71], v[228:231], v[220:223], v[68:71]
	v_mfma_f32_16x16x32_bf16 v[64:67], v[236:239], v[220:223], v[64:67]
	v_mfma_f32_16x16x32_bf16 v[92:95], v[232:235], v[174:177], v[92:95]
	v_mfma_f32_16x16x32_bf16 v[88:91], v[240:243], v[174:177], v[88:91]
	v_mfma_f32_16x16x32_bf16 v[84:87], v[232:235], v[208:211], v[84:87]
	v_mfma_f32_16x16x32_bf16 v[80:83], v[240:243], v[208:211], v[80:83]
	v_mfma_f32_16x16x32_bf16 v[76:79], v[232:235], v[216:219], v[76:79]
	v_mfma_f32_16x16x32_bf16 v[72:75], v[240:243], v[216:219], v[72:75]
	v_mfma_f32_16x16x32_bf16 v[68:71], v[232:235], v[224:227], v[68:71]
	v_mfma_f32_16x16x32_bf16 v[64:67], v[240:243], v[224:227], v[64:67]
	s_mov_b32 m0, s9
	v_lshl_add_u64 v[178:179], v[178:179], 0, s[90:91]
	s_barrier
	ds_read_b128 v[170:173], v152 offset:49152
	ds_read_b128 v[174:177], v152 offset:50176
	ds_read_b128 v[204:207], v152 offset:51200
	ds_read_b128 v[208:211], v152 offset:52224
	ds_read_b128 v[212:215], v152 offset:53248
	ds_read_b128 v[216:219], v152 offset:54272
	ds_read_b128 v[220:223], v152 offset:55296
	ds_read_b128 v[224:227], v152 offset:56320
	global_load_lds_dwordx4 v[178:179], off
	v_lshl_add_u64 v[178:179], v[188:189], 0, s[90:91]
	s_mov_b32 m0, s12
	s_nop 0
	global_load_lds_dwordx4 v[178:179], off
	s_barrier
	s_waitcnt lgkmcnt(0)
	s_waitcnt lgkmcnt(0)
	v_mfma_f32_16x16x32_bf16 v[60:63], v[154:157], v[170:173], v[60:63]
	v_mfma_f32_16x16x32_bf16 v[56:59], v[162:165], v[170:173], v[56:59]
	v_mfma_f32_16x16x32_bf16 v[52:55], v[154:157], v[204:207], v[52:55]
	v_mfma_f32_16x16x32_bf16 v[48:51], v[162:165], v[204:207], v[48:51]
	v_mfma_f32_16x16x32_bf16 v[44:47], v[154:157], v[212:215], v[44:47]
	v_mfma_f32_16x16x32_bf16 v[40:43], v[162:165], v[212:215], v[40:43]
	v_mfma_f32_16x16x32_bf16 v[36:39], v[154:157], v[220:223], v[36:39]
	v_mfma_f32_16x16x32_bf16 v[32:35], v[162:165], v[220:223], v[32:35]
	v_mfma_f32_16x16x32_bf16 v[60:63], v[158:161], v[174:177], v[60:63]
	v_mfma_f32_16x16x32_bf16 v[56:59], v[166:169], v[174:177], v[56:59]
	v_mfma_f32_16x16x32_bf16 v[52:55], v[158:161], v[208:211], v[52:55]
	v_mfma_f32_16x16x32_bf16 v[48:51], v[166:169], v[208:211], v[48:51]
	v_mfma_f32_16x16x32_bf16 v[44:47], v[158:161], v[216:219], v[44:47]
	v_mfma_f32_16x16x32_bf16 v[40:43], v[166:169], v[216:219], v[40:43]
	v_mfma_f32_16x16x32_bf16 v[36:39], v[158:161], v[224:227], v[36:39]
	v_mfma_f32_16x16x32_bf16 v[32:35], v[166:169], v[224:227], v[32:35]
	s_barrier
	s_add_i32 s16, s17, s20
	v_lshl_add_u64 v[154:155], v[244:245], 0, s[34:35]
	s_mov_b32 m0, s16
	s_nop 0
	global_load_lds_dwordx4 v[154:155], off
	v_lshl_add_u64 v[154:155], v[246:247], 0, s[34:35]
	s_add_i32 m0, s16, 0x2000
	s_nop 0
	global_load_lds_dwordx4 v[154:155], off
	s_waitcnt vmcnt(6)
	s_barrier
	v_mfma_f32_16x16x32_bf16 v[28:31], v[228:231], v[170:173], v[28:31]
	v_mfma_f32_16x16x32_bf16 v[24:27], v[236:239], v[170:173], v[24:27]
	v_mfma_f32_16x16x32_bf16 v[20:23], v[228:231], v[204:207], v[20:23]
	v_mfma_f32_16x16x32_bf16 v[16:19], v[236:239], v[204:207], v[16:19]
	v_mfma_f32_16x16x32_bf16 v[12:15], v[228:231], v[212:215], v[12:15]
	v_mfma_f32_16x16x32_bf16 v[8:11], v[236:239], v[212:215], v[8:11]
	v_mfma_f32_16x16x32_bf16 v[4:7], v[228:231], v[220:223], v[4:7]
	v_mfma_f32_16x16x32_bf16 v[0:3], v[236:239], v[220:223], v[0:3]
	v_mfma_f32_16x16x32_bf16 v[28:31], v[232:235], v[174:177], v[28:31]
	v_mfma_f32_16x16x32_bf16 v[24:27], v[240:243], v[174:177], v[24:27]
	v_mfma_f32_16x16x32_bf16 v[20:23], v[232:235], v[208:211], v[20:23]
	v_mfma_f32_16x16x32_bf16 v[16:19], v[240:243], v[208:211], v[16:19]
	v_mfma_f32_16x16x32_bf16 v[12:15], v[232:235], v[216:219], v[12:15]
	v_mfma_f32_16x16x32_bf16 v[8:11], v[240:243], v[216:219], v[8:11]
	v_mfma_f32_16x16x32_bf16 v[4:7], v[232:235], v[224:227], v[4:7]
	v_mfma_f32_16x16x32_bf16 v[0:3], v[240:243], v[224:227], v[0:3]
	s_add_i32 s13, s13, 2
	s_add_u32 s6, s6, 0x100
	s_addc_u32 s7, s7, 0
	s_cmp_lt_u32 s13, 12
	s_barrier
	s_cbranch_scc1 .LBB0_940
	s_add_u32 s6, s10, 0x40780
	v_add_u32_e32 v153, 32, v151
	s_addc_u32 s7, s11, 0
	s_mov_b32 m0, s15
	v_add_u32_e32 v158, 0x10000, v153
	v_lshl_add_u64 v[178:179], s[6:7], 0, v[136:137]
	ds_read_b128 v[142:145], v158
	ds_read_b128 v[146:149], v158 offset:1024
	ds_read_b128 v[154:157], v158 offset:2048
	ds_read_b128 v[158:161], v158 offset:3072
	ds_read_b128 v[162:165], v152
	ds_read_b128 v[166:169], v152 offset:1024
	ds_read_b128 v[170:173], v152 offset:2048
	ds_read_b128 v[174:177], v152 offset:3072
	ds_read_b128 v[204:207], v152 offset:4096
	ds_read_b128 v[208:211], v152 offset:5120
	ds_read_b128 v[212:215], v152 offset:6144
	ds_read_b128 v[216:219], v152 offset:7168
	global_load_lds_dwordx4 v[178:179], off
	v_lshl_add_u64 v[178:179], s[6:7], 0, v[134:135]
	s_mov_b32 m0, s14
	s_nop 0
	global_load_lds_dwordx4 v[178:179], off
	s_barrier
	s_waitcnt lgkmcnt(0)
	s_waitcnt lgkmcnt(0)
	v_mfma_f32_16x16x32_bf16 v[124:127], v[142:145], v[162:165], v[124:127]
	v_mfma_f32_16x16x32_bf16 v[120:123], v[154:157], v[162:165], v[120:123]
	v_mfma_f32_16x16x32_bf16 v[116:119], v[142:145], v[170:173], v[116:119]
	v_mfma_f32_16x16x32_bf16 v[112:115], v[154:157], v[170:173], v[112:115]
	v_mfma_f32_16x16x32_bf16 v[108:111], v[142:145], v[204:207], v[108:111]
	v_mfma_f32_16x16x32_bf16 v[104:107], v[154:157], v[204:207], v[104:107]
	v_mfma_f32_16x16x32_bf16 v[100:103], v[142:145], v[212:215], v[100:103]
	v_mfma_f32_16x16x32_bf16 v[96:99], v[154:157], v[212:215], v[96:99]
	v_mfma_f32_16x16x32_bf16 v[124:127], v[146:149], v[166:169], v[124:127]
	v_mfma_f32_16x16x32_bf16 v[120:123], v[158:161], v[166:169], v[120:123]
	v_mfma_f32_16x16x32_bf16 v[116:119], v[146:149], v[174:177], v[116:119]
	v_mfma_f32_16x16x32_bf16 v[112:115], v[158:161], v[174:177], v[112:115]
	v_mfma_f32_16x16x32_bf16 v[108:111], v[146:149], v[208:211], v[108:111]
	v_mfma_f32_16x16x32_bf16 v[104:107], v[158:161], v[208:211], v[104:107]
	v_mfma_f32_16x16x32_bf16 v[100:103], v[146:149], v[216:219], v[100:103]
	v_mfma_f32_16x16x32_bf16 v[96:99], v[158:161], v[216:219], v[96:99]
	v_add_u32_e32 v178, 0x14000, v153
	s_barrier
	ds_read_b128 v[220:223], v178
	ds_read_b128 v[224:227], v178 offset:1024
	ds_read_b128 v[228:231], v178 offset:2048
	ds_read_b128 v[232:235], v178 offset:3072
	s_barrier
	s_waitcnt lgkmcnt(0)
	s_waitcnt lgkmcnt(0)
	v_mfma_f32_16x16x32_bf16 v[92:95], v[220:223], v[162:165], v[92:95]
	v_mfma_f32_16x16x32_bf16 v[88:91], v[228:231], v[162:165], v[88:91]
	v_mfma_f32_16x16x32_bf16 v[84:87], v[220:223], v[170:173], v[84:87]
	v_mfma_f32_16x16x32_bf16 v[80:83], v[228:231], v[170:173], v[80:83]
	v_mfma_f32_16x16x32_bf16 v[76:79], v[220:223], v[204:207], v[76:79]
	v_mfma_f32_16x16x32_bf16 v[72:75], v[228:231], v[204:207], v[72:75]
	v_mfma_f32_16x16x32_bf16 v[68:71], v[220:223], v[212:215], v[68:71]
	v_mfma_f32_16x16x32_bf16 v[64:67], v[228:231], v[212:215], v[64:67]
	v_mfma_f32_16x16x32_bf16 v[92:95], v[224:227], v[166:169], v[92:95]
	v_mfma_f32_16x16x32_bf16 v[88:91], v[232:235], v[166:169], v[88:91]
	v_mfma_f32_16x16x32_bf16 v[84:87], v[224:227], v[174:177], v[84:87]
	v_mfma_f32_16x16x32_bf16 v[80:83], v[232:235], v[174:177], v[80:83]
	v_mfma_f32_16x16x32_bf16 v[76:79], v[224:227], v[208:211], v[76:79]
	v_mfma_f32_16x16x32_bf16 v[72:75], v[232:235], v[208:211], v[72:75]
	v_mfma_f32_16x16x32_bf16 v[68:71], v[224:227], v[216:219], v[68:71]
	v_mfma_f32_16x16x32_bf16 v[64:67], v[232:235], v[216:219], v[64:67]
	s_barrier
	ds_read_b128 v[162:165], v152 offset:16384
	ds_read_b128 v[166:169], v152 offset:17408
	ds_read_b128 v[170:173], v152 offset:18432
	ds_read_b128 v[174:177], v152 offset:19456
	ds_read_b128 v[204:207], v152 offset:20480
	ds_read_b128 v[208:211], v152 offset:21504
	ds_read_b128 v[212:215], v152 offset:22528
	ds_read_b128 v[216:219], v152 offset:23552
	s_waitcnt vmcnt(4)
	s_barrier
	s_waitcnt lgkmcnt(0)
	s_waitcnt lgkmcnt(0)
	v_mfma_f32_16x16x32_bf16 v[60:63], v[142:145], v[162:165], v[60:63]
	v_mfma_f32_16x16x32_bf16 v[56:59], v[154:157], v[162:165], v[56:59]
	v_mfma_f32_16x16x32_bf16 v[52:55], v[142:145], v[170:173], v[52:55]
	v_mfma_f32_16x16x32_bf16 v[48:51], v[154:157], v[170:173], v[48:51]
	v_mfma_f32_16x16x32_bf16 v[44:47], v[142:145], v[204:207], v[44:47]
	v_mfma_f32_16x16x32_bf16 v[40:43], v[154:157], v[204:207], v[40:43]
	v_mfma_f32_16x16x32_bf16 v[36:39], v[142:145], v[212:215], v[36:39]
	v_mfma_f32_16x16x32_bf16 v[32:35], v[154:157], v[212:215], v[32:35]
	v_mfma_f32_16x16x32_bf16 v[60:63], v[146:149], v[166:169], v[60:63]
	v_mfma_f32_16x16x32_bf16 v[56:59], v[158:161], v[166:169], v[56:59]
	v_mfma_f32_16x16x32_bf16 v[52:55], v[146:149], v[174:177], v[52:55]
	v_mfma_f32_16x16x32_bf16 v[48:51], v[158:161], v[174:177], v[48:51]
	v_mfma_f32_16x16x32_bf16 v[44:47], v[146:149], v[208:211], v[44:47]
	v_mfma_f32_16x16x32_bf16 v[40:43], v[158:161], v[208:211], v[40:43]
	v_mfma_f32_16x16x32_bf16 v[36:39], v[146:149], v[216:219], v[36:39]
	v_mfma_f32_16x16x32_bf16 v[32:35], v[158:161], v[216:219], v[32:35]
	v_mfma_f32_16x16x32_bf16 v[28:31], v[220:223], v[162:165], v[28:31]
	v_mfma_f32_16x16x32_bf16 v[24:27], v[228:231], v[162:165], v[24:27]
	v_mfma_f32_16x16x32_bf16 v[20:23], v[220:223], v[170:173], v[20:23]
	v_mfma_f32_16x16x32_bf16 v[16:19], v[228:231], v[170:173], v[16:19]
	v_mfma_f32_16x16x32_bf16 v[12:15], v[220:223], v[204:207], v[12:15]
	v_mfma_f32_16x16x32_bf16 v[8:11], v[228:231], v[204:207], v[8:11]
	v_mfma_f32_16x16x32_bf16 v[4:7], v[220:223], v[212:215], v[4:7]
	v_mfma_f32_16x16x32_bf16 v[0:3], v[228:231], v[212:215], v[0:3]
	v_mfma_f32_16x16x32_bf16 v[28:31], v[224:227], v[166:169], v[28:31]
	v_mfma_f32_16x16x32_bf16 v[24:27], v[232:235], v[166:169], v[24:27]
	v_mfma_f32_16x16x32_bf16 v[20:23], v[224:227], v[174:177], v[20:23]
	v_mfma_f32_16x16x32_bf16 v[16:19], v[232:235], v[174:177], v[16:19]
	v_mfma_f32_16x16x32_bf16 v[12:15], v[224:227], v[208:211], v[12:15]
	v_mfma_f32_16x16x32_bf16 v[8:11], v[232:235], v[208:211], v[8:11]
	v_mfma_f32_16x16x32_bf16 v[4:7], v[224:227], v[216:219], v[4:7]
	v_mfma_f32_16x16x32_bf16 v[0:3], v[232:235], v[216:219], v[0:3]
	v_add_u32_e32 v158, 0x18000, v153
	s_barrier
	ds_read_b128 v[142:145], v158
	ds_read_b128 v[146:149], v158 offset:1024
	ds_read_b128 v[154:157], v158 offset:2048
	ds_read_b128 v[158:161], v158 offset:3072
	ds_read_b128 v[162:165], v152 offset:32768
	ds_read_b128 v[166:169], v152 offset:33792
	ds_read_b128 v[170:173], v152 offset:34816
	ds_read_b128 v[174:177], v152 offset:35840
	ds_read_b128 v[204:207], v152 offset:36864
	ds_read_b128 v[208:211], v152 offset:37888
	ds_read_b128 v[212:215], v152 offset:38912
	ds_read_b128 v[216:219], v152 offset:39936
	s_waitcnt vmcnt(2)
	s_barrier
	s_waitcnt lgkmcnt(0)
	s_waitcnt lgkmcnt(0)
	v_mfma_f32_16x16x32_bf16 v[124:127], v[142:145], v[162:165], v[124:127]
	v_mfma_f32_16x16x32_bf16 v[120:123], v[154:157], v[162:165], v[120:123]
	v_mfma_f32_16x16x32_bf16 v[116:119], v[142:145], v[170:173], v[116:119]
	v_mfma_f32_16x16x32_bf16 v[112:115], v[154:157], v[170:173], v[112:115]
	v_mfma_f32_16x16x32_bf16 v[108:111], v[142:145], v[204:207], v[108:111]
	v_mfma_f32_16x16x32_bf16 v[104:107], v[154:157], v[204:207], v[104:107]
	v_mfma_f32_16x16x32_bf16 v[100:103], v[142:145], v[212:215], v[100:103]
	v_mfma_f32_16x16x32_bf16 v[96:99], v[154:157], v[212:215], v[96:99]
	v_mfma_f32_16x16x32_bf16 v[124:127], v[146:149], v[166:169], v[124:127]
	v_mfma_f32_16x16x32_bf16 v[120:123], v[158:161], v[166:169], v[120:123]
	v_mfma_f32_16x16x32_bf16 v[116:119], v[146:149], v[174:177], v[116:119]
	v_mfma_f32_16x16x32_bf16 v[112:115], v[158:161], v[174:177], v[112:115]
	v_mfma_f32_16x16x32_bf16 v[108:111], v[146:149], v[208:211], v[108:111]
	v_mfma_f32_16x16x32_bf16 v[104:107], v[158:161], v[208:211], v[104:107]
	v_mfma_f32_16x16x32_bf16 v[100:103], v[146:149], v[216:219], v[100:103]
	v_mfma_f32_16x16x32_bf16 v[96:99], v[158:161], v[216:219], v[96:99]
	v_add_u32_e32 v153, 0x1c000, v153
	s_barrier
	ds_read_b128 v[220:223], v153
	ds_read_b128 v[224:227], v153 offset:1024
	ds_read_b128 v[228:231], v153 offset:2048
	ds_read_b128 v[232:235], v153 offset:3072
	s_waitcnt vmcnt(0)
	s_barrier
	s_waitcnt lgkmcnt(0)
	s_waitcnt lgkmcnt(0)
	v_mfma_f32_16x16x32_bf16 v[92:95], v[220:223], v[162:165], v[92:95]
	v_mfma_f32_16x16x32_bf16 v[88:91], v[228:231], v[162:165], v[88:91]
	v_mfma_f32_16x16x32_bf16 v[84:87], v[220:223], v[170:173], v[84:87]
	v_mfma_f32_16x16x32_bf16 v[80:83], v[228:231], v[170:173], v[80:83]
	v_mfma_f32_16x16x32_bf16 v[76:79], v[220:223], v[204:207], v[76:79]
	v_mfma_f32_16x16x32_bf16 v[72:75], v[228:231], v[204:207], v[72:75]
	v_mfma_f32_16x16x32_bf16 v[68:71], v[220:223], v[212:215], v[68:71]
	v_mfma_f32_16x16x32_bf16 v[64:67], v[228:231], v[212:215], v[64:67]
	v_mfma_f32_16x16x32_bf16 v[92:95], v[224:227], v[166:169], v[92:95]
	v_mfma_f32_16x16x32_bf16 v[88:91], v[232:235], v[166:169], v[88:91]
	v_mfma_f32_16x16x32_bf16 v[84:87], v[224:227], v[174:177], v[84:87]
	v_mfma_f32_16x16x32_bf16 v[80:83], v[232:235], v[174:177], v[80:83]
	v_mfma_f32_16x16x32_bf16 v[76:79], v[224:227], v[208:211], v[76:79]
	v_mfma_f32_16x16x32_bf16 v[72:75], v[232:235], v[208:211], v[72:75]
	v_mfma_f32_16x16x32_bf16 v[68:71], v[224:227], v[216:219], v[68:71]
	v_mfma_f32_16x16x32_bf16 v[64:67], v[232:235], v[216:219], v[64:67]
	s_barrier
	ds_read_b128 v[162:165], v152 offset:49152
	ds_read_b128 v[166:169], v152 offset:50176
	ds_read_b128 v[170:173], v152 offset:51200
	ds_read_b128 v[174:177], v152 offset:52224
	ds_read_b128 v[204:207], v152 offset:53248
	ds_read_b128 v[208:211], v152 offset:54272
	ds_read_b128 v[212:215], v152 offset:55296
	ds_read_b128 v[216:219], v152 offset:56320
	s_barrier
	s_waitcnt lgkmcnt(0)
	s_waitcnt lgkmcnt(0)
	v_mfma_f32_16x16x32_bf16 v[60:63], v[142:145], v[162:165], v[60:63]
	v_mfma_f32_16x16x32_bf16 v[56:59], v[154:157], v[162:165], v[56:59]
	v_mfma_f32_16x16x32_bf16 v[52:55], v[142:145], v[170:173], v[52:55]
	v_mfma_f32_16x16x32_bf16 v[48:51], v[154:157], v[170:173], v[48:51]
	v_mfma_f32_16x16x32_bf16 v[44:47], v[142:145], v[204:207], v[44:47]
	v_mfma_f32_16x16x32_bf16 v[40:43], v[154:157], v[204:207], v[40:43]
	v_mfma_f32_16x16x32_bf16 v[36:39], v[142:145], v[212:215], v[36:39]
	v_mfma_f32_16x16x32_bf16 v[32:35], v[154:157], v[212:215], v[32:35]
	v_mfma_f32_16x16x32_bf16 v[60:63], v[146:149], v[166:169], v[60:63]
	v_mfma_f32_16x16x32_bf16 v[56:59], v[158:161], v[166:169], v[56:59]
	v_mfma_f32_16x16x32_bf16 v[52:55], v[146:149], v[174:177], v[52:55]
	v_mfma_f32_16x16x32_bf16 v[48:51], v[158:161], v[174:177], v[48:51]
	v_mfma_f32_16x16x32_bf16 v[44:47], v[146:149], v[208:211], v[44:47]
	v_mfma_f32_16x16x32_bf16 v[40:43], v[158:161], v[208:211], v[40:43]
	v_mfma_f32_16x16x32_bf16 v[36:39], v[146:149], v[216:219], v[36:39]
	v_mfma_f32_16x16x32_bf16 v[32:35], v[158:161], v[216:219], v[32:35]
	v_mfma_f32_16x16x32_bf16 v[28:31], v[220:223], v[162:165], v[28:31]
	v_mfma_f32_16x16x32_bf16 v[24:27], v[228:231], v[162:165], v[24:27]
	v_mfma_f32_16x16x32_bf16 v[20:23], v[220:223], v[170:173], v[20:23]
	v_mfma_f32_16x16x32_bf16 v[16:19], v[228:231], v[170:173], v[16:19]
	v_mfma_f32_16x16x32_bf16 v[12:15], v[220:223], v[204:207], v[12:15]
	v_mfma_f32_16x16x32_bf16 v[8:11], v[228:231], v[204:207], v[8:11]
	v_mfma_f32_16x16x32_bf16 v[4:7], v[220:223], v[212:215], v[4:7]
	v_mfma_f32_16x16x32_bf16 v[0:3], v[228:231], v[212:215], v[0:3]
	v_mfma_f32_16x16x32_bf16 v[28:31], v[224:227], v[166:169], v[28:31]
	v_mfma_f32_16x16x32_bf16 v[24:27], v[232:235], v[166:169], v[24:27]
	v_mfma_f32_16x16x32_bf16 v[20:23], v[224:227], v[174:177], v[20:23]
	v_mfma_f32_16x16x32_bf16 v[16:19], v[232:235], v[174:177], v[16:19]
	v_mfma_f32_16x16x32_bf16 v[12:15], v[224:227], v[208:211], v[12:15]
	v_mfma_f32_16x16x32_bf16 v[8:11], v[232:235], v[208:211], v[8:11]
	v_mfma_f32_16x16x32_bf16 v[4:7], v[224:227], v[216:219], v[4:7]
	v_mfma_f32_16x16x32_bf16 v[0:3], v[232:235], v[216:219], v[0:3]
	s_barrier
	s_and_saveexec_b64 s[6:7], s[4:5]
	s_cbranch_execz .LBB0_943
	s_barrier

.LBB0_1835:
	s_add_i32 s28, 32, 0x10000
	v_add_u32_e32 v151, s28, v148
	ds_read_b128 v[152:155], v151
	ds_read_b128 v[156:159], v151 offset:1024
	ds_read_b128 v[160:163], v151 offset:2048
	ds_read_b128 v[164:167], v151 offset:3072
	v_lshl_add_u64 v[188:189], v[144:145], 0, s[8:9]
	s_add_i32 s27, s15, 0xc000
	v_lshl_add_u64 v[224:225], v[188:189], 0, s[30:31]
	s_mov_b32 m0, s27
	v_lshl_add_u64 v[240:241], v[146:147], 0, s[8:9]
	s_add_i32 s13, s15, 0xe000
	ds_read_b128 v[168:171], v150
	ds_read_b128 v[172:175], v150 offset:1024
	ds_read_b128 v[176:179], v150 offset:2048
	ds_read_b128 v[204:207], v150 offset:3072
	ds_read_b128 v[208:211], v150 offset:4096
	ds_read_b128 v[212:215], v150 offset:5120
	ds_read_b128 v[216:219], v150 offset:6144
	ds_read_b128 v[220:223], v150 offset:7168
	global_load_lds_dwordx4 v[224:225], off
	v_lshl_add_u64 v[224:225], v[240:241], 0, s[30:31]
	s_mov_b32 m0, s13
	s_nop 0
	global_load_lds_dwordx4 v[224:225], off
	s_waitcnt lgkmcnt(8)
	s_barrier
	s_waitcnt lgkmcnt(0)
	s_waitcnt lgkmcnt(0)
	v_mfma_f32_16x16x32_bf16 v[124:127], v[152:155], v[168:171], v[124:127]
	v_mfma_f32_16x16x32_bf16 v[120:123], v[160:163], v[168:171], v[120:123]
	v_mfma_f32_16x16x32_bf16 v[116:119], v[152:155], v[176:179], v[116:119]
	v_mfma_f32_16x16x32_bf16 v[112:115], v[160:163], v[176:179], v[112:115]
	v_mfma_f32_16x16x32_bf16 v[108:111], v[152:155], v[208:211], v[108:111]
	v_mfma_f32_16x16x32_bf16 v[104:107], v[160:163], v[208:211], v[104:107]
	v_mfma_f32_16x16x32_bf16 v[100:103], v[152:155], v[216:219], v[100:103]
	v_mfma_f32_16x16x32_bf16 v[96:99], v[160:163], v[216:219], v[96:99]
	v_mfma_f32_16x16x32_bf16 v[124:127], v[156:159], v[172:175], v[124:127]
	v_mfma_f32_16x16x32_bf16 v[120:123], v[164:167], v[172:175], v[120:123]
	v_mfma_f32_16x16x32_bf16 v[116:119], v[156:159], v[204:207], v[116:119]
	v_mfma_f32_16x16x32_bf16 v[112:115], v[164:167], v[204:207], v[112:115]
	v_mfma_f32_16x16x32_bf16 v[108:111], v[156:159], v[212:215], v[108:111]
	v_mfma_f32_16x16x32_bf16 v[104:107], v[164:167], v[212:215], v[104:107]
	v_mfma_f32_16x16x32_bf16 v[100:103], v[156:159], v[220:223], v[100:103]
	v_mfma_f32_16x16x32_bf16 v[96:99], v[164:167], v[220:223], v[96:99]
	s_barrier
	s_add_i32 s29, 32, 0x14000
	v_lshl_add_u64 v[242:243], v[140:141], 0, s[8:9]
	s_add_i32 s28, s28, s14
	v_add_u32_e32 v151, s29, v148
	v_lshl_add_u64 v[244:245], v[242:243], 0, s[88:89]
	s_mov_b32 m0, s28
	ds_read_b128 v[224:227], v151
	ds_read_b128 v[228:231], v151 offset:1024
	ds_read_b128 v[232:235], v151 offset:2048
	ds_read_b128 v[236:239], v151 offset:3072
	global_load_lds_dwordx4 v[244:245], off
	v_lshl_add_u64 v[244:245], v[142:143], 0, s[8:9]
	v_lshl_add_u64 v[246:247], v[244:245], 0, s[88:89]
	s_add_i32 m0, s28, 0x2000
	s_nop 0
	global_load_lds_dwordx4 v[246:247], off
	s_barrier
	s_waitcnt lgkmcnt(0)
	s_waitcnt lgkmcnt(0)
	v_mfma_f32_16x16x32_bf16 v[92:95], v[224:227], v[168:171], v[92:95]
	v_mfma_f32_16x16x32_bf16 v[88:91], v[232:235], v[168:171], v[88:91]
	v_mfma_f32_16x16x32_bf16 v[84:87], v[224:227], v[176:179], v[84:87]
	v_mfma_f32_16x16x32_bf16 v[80:83], v[232:235], v[176:179], v[80:83]
	v_mfma_f32_16x16x32_bf16 v[76:79], v[224:227], v[208:211], v[76:79]
	v_mfma_f32_16x16x32_bf16 v[72:75], v[232:235], v[208:211], v[72:75]
	v_mfma_f32_16x16x32_bf16 v[68:71], v[224:227], v[216:219], v[68:71]
	v_mfma_f32_16x16x32_bf16 v[64:67], v[232:235], v[216:219], v[64:67]
	v_mfma_f32_16x16x32_bf16 v[92:95], v[228:231], v[172:175], v[92:95]
	v_mfma_f32_16x16x32_bf16 v[88:91], v[236:239], v[172:175], v[88:91]
	v_mfma_f32_16x16x32_bf16 v[84:87], v[228:231], v[204:207], v[84:87]
	v_mfma_f32_16x16x32_bf16 v[80:83], v[236:239], v[204:207], v[80:83]
	v_mfma_f32_16x16x32_bf16 v[76:79], v[228:231], v[212:215], v[76:79]
	v_mfma_f32_16x16x32_bf16 v[72:75], v[236:239], v[212:215], v[72:75]
	v_mfma_f32_16x16x32_bf16 v[68:71], v[228:231], v[220:223], v[68:71]
	v_mfma_f32_16x16x32_bf16 v[64:67], v[236:239], v[220:223], v[64:67]
	s_mov_b32 m0, s15
	v_lshl_add_u64 v[246:247], v[188:189], 0, s[88:89]
	s_barrier
	ds_read_b128 v[168:171], v150 offset:16384
	ds_read_b128 v[172:175], v150 offset:17408
	ds_read_b128 v[176:179], v150 offset:18432
	ds_read_b128 v[204:207], v150 offset:19456
	ds_read_b128 v[208:211], v150 offset:20480
	ds_read_b128 v[212:215], v150 offset:21504
	ds_read_b128 v[216:219], v150 offset:22528
	ds_read_b128 v[220:223], v150 offset:23552
	global_load_lds_dwordx4 v[246:247], off
	v_lshl_add_u64 v[246:247], v[240:241], 0, s[88:89]
	s_mov_b32 m0, s18
	s_nop 0
	global_load_lds_dwordx4 v[246:247], off
	s_barrier
	s_waitcnt lgkmcnt(0)
	s_waitcnt lgkmcnt(0)
	v_mfma_f32_16x16x32_bf16 v[60:63], v[152:155], v[168:171], v[60:63]
	v_mfma_f32_16x16x32_bf16 v[56:59], v[160:163], v[168:171], v[56:59]
	v_mfma_f32_16x16x32_bf16 v[52:55], v[152:155], v[176:179], v[52:55]
	v_mfma_f32_16x16x32_bf16 v[48:51], v[160:163], v[176:179], v[48:51]
	v_mfma_f32_16x16x32_bf16 v[44:47], v[152:155], v[208:211], v[44:47]
	v_mfma_f32_16x16x32_bf16 v[40:43], v[160:163], v[208:211], v[40:43]
	v_mfma_f32_16x16x32_bf16 v[36:39], v[152:155], v[216:219], v[36:39]
	v_mfma_f32_16x16x32_bf16 v[32:35], v[160:163], v[216:219], v[32:35]
	v_mfma_f32_16x16x32_bf16 v[60:63], v[156:159], v[172:175], v[60:63]
	v_mfma_f32_16x16x32_bf16 v[56:59], v[164:167], v[172:175], v[56:59]
	v_mfma_f32_16x16x32_bf16 v[52:55], v[156:159], v[204:207], v[52:55]
	v_mfma_f32_16x16x32_bf16 v[48:51], v[164:167], v[204:207], v[48:51]
	v_mfma_f32_16x16x32_bf16 v[44:47], v[156:159], v[212:215], v[44:47]
	v_mfma_f32_16x16x32_bf16 v[40:43], v[164:167], v[212:215], v[40:43]
	v_mfma_f32_16x16x32_bf16 v[36:39], v[156:159], v[220:223], v[36:39]
	v_mfma_f32_16x16x32_bf16 v[32:35], v[164:167], v[220:223], v[32:35]
	s_barrier
	s_add_i32 s28, s29, s14
	v_lshl_add_u64 v[152:153], v[242:243], 0, s[92:93]
	s_mov_b32 m0, s28
	s_nop 0
	global_load_lds_dwordx4 v[152:153], off
	v_lshl_add_u64 v[152:153], v[244:245], 0, s[92:93]
	s_add_i32 m0, s28, 0x2000
	s_nop 0
	global_load_lds_dwordx4 v[152:153], off
	s_waitcnt vmcnt(6)
	s_barrier
	v_mfma_f32_16x16x32_bf16 v[28:31], v[224:227], v[168:171], v[28:31]
	v_mfma_f32_16x16x32_bf16 v[24:27], v[232:235], v[168:171], v[24:27]
	v_mfma_f32_16x16x32_bf16 v[20:23], v[224:227], v[176:179], v[20:23]
	v_mfma_f32_16x16x32_bf16 v[16:19], v[232:235], v[176:179], v[16:19]
	v_mfma_f32_16x16x32_bf16 v[12:15], v[224:227], v[208:211], v[12:15]
	v_mfma_f32_16x16x32_bf16 v[8:11], v[232:235], v[208:211], v[8:11]
	v_mfma_f32_16x16x32_bf16 v[4:7], v[224:227], v[216:219], v[4:7]
	v_mfma_f32_16x16x32_bf16 v[0:3], v[232:235], v[216:219], v[0:3]
	v_mfma_f32_16x16x32_bf16 v[28:31], v[228:231], v[172:175], v[28:31]
	v_mfma_f32_16x16x32_bf16 v[24:27], v[236:239], v[172:175], v[24:27]
	v_mfma_f32_16x16x32_bf16 v[20:23], v[228:231], v[204:207], v[20:23]
	v_mfma_f32_16x16x32_bf16 v[16:19], v[236:239], v[204:207], v[16:19]
	v_mfma_f32_16x16x32_bf16 v[12:15], v[228:231], v[212:215], v[12:15]
	v_mfma_f32_16x16x32_bf16 v[8:11], v[236:239], v[212:215], v[8:11]
	v_mfma_f32_16x16x32_bf16 v[4:7], v[228:231], v[220:223], v[4:7]
	v_mfma_f32_16x16x32_bf16 v[0:3], v[236:239], v[220:223], v[0:3]
	s_add_i32 s28, 32, 0x18000
	v_add_u32_e32 v151, s28, v148
	s_barrier
	ds_read_b128 v[152:155], v151
	ds_read_b128 v[156:159], v151 offset:1024
	ds_read_b128 v[160:163], v151 offset:2048
	ds_read_b128 v[164:167], v151 offset:3072
	s_mov_b32 m0, s21
	v_lshl_add_u64 v[224:225], v[188:189], 0, s[92:93]
	ds_read_b128 v[168:171], v150 offset:32768
	ds_read_b128 v[172:175], v150 offset:33792
	ds_read_b128 v[176:179], v150 offset:34816
	ds_read_b128 v[204:207], v150 offset:35840
	ds_read_b128 v[208:211], v150 offset:36864
	ds_read_b128 v[212:215], v150 offset:37888
	ds_read_b128 v[216:219], v150 offset:38912
	ds_read_b128 v[220:223], v150 offset:39936
	global_load_lds_dwordx4 v[224:225], off
	v_lshl_add_u64 v[224:225], v[240:241], 0, s[92:93]
	s_mov_b32 m0, s23
	s_nop 0
	global_load_lds_dwordx4 v[224:225], off
	s_waitcnt lgkmcnt(8)
	s_barrier
	s_waitcnt lgkmcnt(0)
	s_waitcnt lgkmcnt(0)
	v_mfma_f32_16x16x32_bf16 v[124:127], v[152:155], v[168:171], v[124:127]
	v_mfma_f32_16x16x32_bf16 v[120:123], v[160:163], v[168:171], v[120:123]
	v_mfma_f32_16x16x32_bf16 v[116:119], v[152:155], v[176:179], v[116:119]
	v_mfma_f32_16x16x32_bf16 v[112:115], v[160:163], v[176:179], v[112:115]
	v_mfma_f32_16x16x32_bf16 v[108:111], v[152:155], v[208:211], v[108:111]
	v_mfma_f32_16x16x32_bf16 v[104:107], v[160:163], v[208:211], v[104:107]
	v_mfma_f32_16x16x32_bf16 v[100:103], v[152:155], v[216:219], v[100:103]
	v_mfma_f32_16x16x32_bf16 v[96:99], v[160:163], v[216:219], v[96:99]
	v_mfma_f32_16x16x32_bf16 v[124:127], v[156:159], v[172:175], v[124:127]
	v_mfma_f32_16x16x32_bf16 v[120:123], v[164:167], v[172:175], v[120:123]
	v_mfma_f32_16x16x32_bf16 v[116:119], v[156:159], v[204:207], v[116:119]
	v_mfma_f32_16x16x32_bf16 v[112:115], v[164:167], v[204:207], v[112:115]
	v_mfma_f32_16x16x32_bf16 v[108:111], v[156:159], v[212:215], v[108:111]
	v_mfma_f32_16x16x32_bf16 v[104:107], v[164:167], v[212:215], v[104:107]
	v_mfma_f32_16x16x32_bf16 v[100:103], v[156:159], v[220:223], v[100:103]
	v_mfma_f32_16x16x32_bf16 v[96:99], v[164:167], v[220:223], v[96:99]
	s_barrier
	s_add_i32 s29, 32, 0x1c000
	s_add_i32 s28, s28, s14
	v_add_u32_e32 v151, s29, v148
	v_lshl_add_u64 v[246:247], v[242:243], 0, s[90:91]
	s_mov_b32 m0, s28
	ds_read_b128 v[224:227], v151
	ds_read_b128 v[228:231], v151 offset:1024
	ds_read_b128 v[232:235], v151 offset:2048
	ds_read_b128 v[236:239], v151 offset:3072
	global_load_lds_dwordx4 v[246:247], off
	v_lshl_add_u64 v[246:247], v[244:245], 0, s[90:91]
	s_add_i32 m0, s28, 0x2000
	s_nop 0
	global_load_lds_dwordx4 v[246:247], off
	s_barrier
	s_waitcnt lgkmcnt(0)
	s_waitcnt lgkmcnt(0)
	v_mfma_f32_16x16x32_bf16 v[92:95], v[224:227], v[168:171], v[92:95]
	v_mfma_f32_16x16x32_bf16 v[88:91], v[232:235], v[168:171], v[88:91]
	v_mfma_f32_16x16x32_bf16 v[84:87], v[224:227], v[176:179], v[84:87]
	v_mfma_f32_16x16x32_bf16 v[80:83], v[232:235], v[176:179], v[80:83]
	v_mfma_f32_16x16x32_bf16 v[76:79], v[224:227], v[208:211], v[76:79]
	v_mfma_f32_16x16x32_bf16 v[72:75], v[232:235], v[208:211], v[72:75]
	v_mfma_f32_16x16x32_bf16 v[68:71], v[224:227], v[216:219], v[68:71]
	v_mfma_f32_16x16x32_bf16 v[64:67], v[232:235], v[216:219], v[64:67]
	v_mfma_f32_16x16x32_bf16 v[92:95], v[228:231], v[172:175], v[92:95]
	v_mfma_f32_16x16x32_bf16 v[88:91], v[236:239], v[172:175], v[88:91]
	v_mfma_f32_16x16x32_bf16 v[84:87], v[228:231], v[204:207], v[84:87]
	v_mfma_f32_16x16x32_bf16 v[80:83], v[236:239], v[204:207], v[80:83]
	v_mfma_f32_16x16x32_bf16 v[76:79], v[228:231], v[212:215], v[76:79]
	v_mfma_f32_16x16x32_bf16 v[72:75], v[236:239], v[212:215], v[72:75]
	v_mfma_f32_16x16x32_bf16 v[68:71], v[228:231], v[220:223], v[68:71]
	v_mfma_f32_16x16x32_bf16 v[64:67], v[236:239], v[220:223], v[64:67]
	s_mov_b32 m0, s10
	v_lshl_add_u64 v[188:189], v[188:189], 0, s[90:91]
	s_barrier
	ds_read_b128 v[168:171], v150 offset:49152
	ds_read_b128 v[172:175], v150 offset:50176
	ds_read_b128 v[176:179], v150 offset:51200
	ds_read_b128 v[204:207], v150 offset:52224
	ds_read_b128 v[208:211], v150 offset:53248
	ds_read_b128 v[212:215], v150 offset:54272
	ds_read_b128 v[216:219], v150 offset:55296
	ds_read_b128 v[220:223], v150 offset:56320
	global_load_lds_dwordx4 v[188:189], off
	v_lshl_add_u64 v[188:189], v[240:241], 0, s[90:91]
	s_mov_b32 m0, s11
	s_nop 0
	global_load_lds_dwordx4 v[188:189], off
	s_barrier
	s_waitcnt lgkmcnt(0)
	s_waitcnt lgkmcnt(0)
	v_mfma_f32_16x16x32_bf16 v[60:63], v[152:155], v[168:171], v[60:63]
	v_mfma_f32_16x16x32_bf16 v[56:59], v[160:163], v[168:171], v[56:59]
	v_mfma_f32_16x16x32_bf16 v[52:55], v[152:155], v[176:179], v[52:55]
	v_mfma_f32_16x16x32_bf16 v[48:51], v[160:163], v[176:179], v[48:51]
	v_mfma_f32_16x16x32_bf16 v[44:47], v[152:155], v[208:211], v[44:47]
	v_mfma_f32_16x16x32_bf16 v[40:43], v[160:163], v[208:211], v[40:43]
	v_mfma_f32_16x16x32_bf16 v[36:39], v[152:155], v[216:219], v[36:39]
	v_mfma_f32_16x16x32_bf16 v[32:35], v[160:163], v[216:219], v[32:35]
	v_mfma_f32_16x16x32_bf16 v[60:63], v[156:159], v[172:175], v[60:63]
	v_mfma_f32_16x16x32_bf16 v[56:59], v[164:167], v[172:175], v[56:59]
	v_mfma_f32_16x16x32_bf16 v[52:55], v[156:159], v[204:207], v[52:55]
	v_mfma_f32_16x16x32_bf16 v[48:51], v[164:167], v[204:207], v[48:51]
	v_mfma_f32_16x16x32_bf16 v[44:47], v[156:159], v[212:215], v[44:47]
	v_mfma_f32_16x16x32_bf16 v[40:43], v[164:167], v[212:215], v[40:43]
	v_mfma_f32_16x16x32_bf16 v[36:39], v[156:159], v[220:223], v[36:39]
	v_mfma_f32_16x16x32_bf16 v[32:35], v[164:167], v[220:223], v[32:35]
	s_barrier
	s_add_i32 s28, s29, s14
	v_lshl_add_u64 v[152:153], v[242:243], 0, s[34:35]
	s_mov_b32 m0, s28
	s_nop 0
	global_load_lds_dwordx4 v[152:153], off
	v_lshl_add_u64 v[152:153], v[244:245], 0, s[34:35]
	s_add_i32 m0, s28, 0x2000
	s_nop 0
	global_load_lds_dwordx4 v[152:153], off
	s_waitcnt vmcnt(6)
	s_barrier
	v_mfma_f32_16x16x32_bf16 v[28:31], v[224:227], v[168:171], v[28:31]
	v_mfma_f32_16x16x32_bf16 v[24:27], v[232:235], v[168:171], v[24:27]
	v_mfma_f32_16x16x32_bf16 v[20:23], v[224:227], v[176:179], v[20:23]
	v_mfma_f32_16x16x32_bf16 v[16:19], v[232:235], v[176:179], v[16:19]
	v_mfma_f32_16x16x32_bf16 v[12:15], v[224:227], v[208:211], v[12:15]
	v_mfma_f32_16x16x32_bf16 v[8:11], v[232:235], v[208:211], v[8:11]
	v_mfma_f32_16x16x32_bf16 v[4:7], v[224:227], v[216:219], v[4:7]
	v_mfma_f32_16x16x32_bf16 v[0:3], v[232:235], v[216:219], v[0:3]
	v_mfma_f32_16x16x32_bf16 v[28:31], v[228:231], v[172:175], v[28:31]
	v_mfma_f32_16x16x32_bf16 v[24:27], v[236:239], v[172:175], v[24:27]
	v_mfma_f32_16x16x32_bf16 v[20:23], v[228:231], v[204:207], v[20:23]
	v_mfma_f32_16x16x32_bf16 v[16:19], v[236:239], v[204:207], v[16:19]
	v_mfma_f32_16x16x32_bf16 v[12:15], v[228:231], v[212:215], v[12:15]
	v_mfma_f32_16x16x32_bf16 v[8:11], v[236:239], v[212:215], v[8:11]
	v_mfma_f32_16x16x32_bf16 v[4:7], v[228:231], v[220:223], v[4:7]
	v_mfma_f32_16x16x32_bf16 v[0:3], v[236:239], v[220:223], v[0:3]
	s_add_i32 s12, s12, 2
	s_add_u32 s8, s8, 0x100
	s_addc_u32 s9, s9, 0
	s_cmp_gt_u32 s12, 11
	s_barrier
	s_cbranch_scc0 .LBB0_1835
	s_add_u32 s8, s6, 0x40780
	v_add_u32_e32 v151, 32, v148
	s_addc_u32 s9, s7, 0
	s_mov_b32 m0, s27
	v_add_u32_e32 v156, 0x10000, v151
	v_lshl_add_u64 v[188:189], s[8:9], 0, v[128:129]
	ds_read_b128 v[140:143], v156
	ds_read_b128 v[144:147], v156 offset:1024
	ds_read_b128 v[152:155], v156 offset:2048
	ds_read_b128 v[156:159], v156 offset:3072
	ds_read_b128 v[160:163], v150
	ds_read_b128 v[164:167], v150 offset:1024
	ds_read_b128 v[168:171], v150 offset:2048
	ds_read_b128 v[172:175], v150 offset:3072
	ds_read_b128 v[176:179], v150 offset:4096
	ds_read_b128 v[204:207], v150 offset:5120
	ds_read_b128 v[208:211], v150 offset:6144
	ds_read_b128 v[212:215], v150 offset:7168
	global_load_lds_dwordx4 v[188:189], off
	v_lshl_add_u64 v[188:189], s[8:9], 0, v[134:135]
	s_mov_b32 m0, s13
	s_nop 0
	global_load_lds_dwordx4 v[188:189], off
	s_barrier
	s_waitcnt lgkmcnt(0)
	s_waitcnt lgkmcnt(0)
	v_mfma_f32_16x16x32_bf16 v[124:127], v[140:143], v[160:163], v[124:127]
	v_mfma_f32_16x16x32_bf16 v[120:123], v[152:155], v[160:163], v[120:123]
	v_mfma_f32_16x16x32_bf16 v[116:119], v[140:143], v[168:171], v[116:119]
	v_mfma_f32_16x16x32_bf16 v[112:115], v[152:155], v[168:171], v[112:115]
	v_mfma_f32_16x16x32_bf16 v[108:111], v[140:143], v[176:179], v[108:111]
	v_mfma_f32_16x16x32_bf16 v[104:107], v[152:155], v[176:179], v[104:107]
	v_mfma_f32_16x16x32_bf16 v[100:103], v[140:143], v[208:211], v[100:103]
	v_mfma_f32_16x16x32_bf16 v[96:99], v[152:155], v[208:211], v[96:99]
	v_mfma_f32_16x16x32_bf16 v[124:127], v[144:147], v[164:167], v[124:127]
	v_mfma_f32_16x16x32_bf16 v[120:123], v[156:159], v[164:167], v[120:123]
	v_mfma_f32_16x16x32_bf16 v[116:119], v[144:147], v[172:175], v[116:119]
	v_mfma_f32_16x16x32_bf16 v[112:115], v[156:159], v[172:175], v[112:115]
	v_mfma_f32_16x16x32_bf16 v[108:111], v[144:147], v[204:207], v[108:111]
	v_mfma_f32_16x16x32_bf16 v[104:107], v[156:159], v[204:207], v[104:107]
	v_mfma_f32_16x16x32_bf16 v[100:103], v[144:147], v[212:215], v[100:103]
	v_mfma_f32_16x16x32_bf16 v[96:99], v[156:159], v[212:215], v[96:99]
	v_add_u32_e32 v188, 0x14000, v151
	s_barrier
	ds_read_b128 v[216:219], v188
	ds_read_b128 v[220:223], v188 offset:1024
	ds_read_b128 v[224:227], v188 offset:2048
	ds_read_b128 v[228:231], v188 offset:3072
	s_barrier
	s_waitcnt lgkmcnt(0)
	s_waitcnt lgkmcnt(0)
	v_mfma_f32_16x16x32_bf16 v[92:95], v[216:219], v[160:163], v[92:95]
	v_mfma_f32_16x16x32_bf16 v[88:91], v[224:227], v[160:163], v[88:91]
	v_mfma_f32_16x16x32_bf16 v[84:87], v[216:219], v[168:171], v[84:87]
	v_mfma_f32_16x16x32_bf16 v[80:83], v[224:227], v[168:171], v[80:83]
	v_mfma_f32_16x16x32_bf16 v[76:79], v[216:219], v[176:179], v[76:79]
	v_mfma_f32_16x16x32_bf16 v[72:75], v[224:227], v[176:179], v[72:75]
	v_mfma_f32_16x16x32_bf16 v[68:71], v[216:219], v[208:211], v[68:71]
	v_mfma_f32_16x16x32_bf16 v[64:67], v[224:227], v[208:211], v[64:67]
	v_mfma_f32_16x16x32_bf16 v[92:95], v[220:223], v[164:167], v[92:95]
	v_mfma_f32_16x16x32_bf16 v[88:91], v[228:231], v[164:167], v[88:91]
	v_mfma_f32_16x16x32_bf16 v[84:87], v[220:223], v[172:175], v[84:87]
	v_mfma_f32_16x16x32_bf16 v[80:83], v[228:231], v[172:175], v[80:83]
	v_mfma_f32_16x16x32_bf16 v[76:79], v[220:223], v[204:207], v[76:79]
	v_mfma_f32_16x16x32_bf16 v[72:75], v[228:231], v[204:207], v[72:75]
	v_mfma_f32_16x16x32_bf16 v[68:71], v[220:223], v[212:215], v[68:71]
	v_mfma_f32_16x16x32_bf16 v[64:67], v[228:231], v[212:215], v[64:67]
	s_barrier
	ds_read_b128 v[160:163], v150 offset:16384
	ds_read_b128 v[164:167], v150 offset:17408
	ds_read_b128 v[168:171], v150 offset:18432
	ds_read_b128 v[172:175], v150 offset:19456
	ds_read_b128 v[176:179], v150 offset:20480
	ds_read_b128 v[204:207], v150 offset:21504
	ds_read_b128 v[208:211], v150 offset:22528
	ds_read_b128 v[212:215], v150 offset:23552
	s_waitcnt vmcnt(4)
	s_barrier
	s_waitcnt lgkmcnt(0)
	s_waitcnt lgkmcnt(0)
	v_mfma_f32_16x16x32_bf16 v[60:63], v[140:143], v[160:163], v[60:63]
	v_mfma_f32_16x16x32_bf16 v[56:59], v[152:155], v[160:163], v[56:59]
	v_mfma_f32_16x16x32_bf16 v[52:55], v[140:143], v[168:171], v[52:55]
	v_mfma_f32_16x16x32_bf16 v[48:51], v[152:155], v[168:171], v[48:51]
	v_mfma_f32_16x16x32_bf16 v[44:47], v[140:143], v[176:179], v[44:47]
	v_mfma_f32_16x16x32_bf16 v[40:43], v[152:155], v[176:179], v[40:43]
	v_mfma_f32_16x16x32_bf16 v[36:39], v[140:143], v[208:211], v[36:39]
	v_mfma_f32_16x16x32_bf16 v[32:35], v[152:155], v[208:211], v[32:35]
	v_mfma_f32_16x16x32_bf16 v[60:63], v[144:147], v[164:167], v[60:63]
	v_mfma_f32_16x16x32_bf16 v[56:59], v[156:159], v[164:167], v[56:59]
	v_mfma_f32_16x16x32_bf16 v[52:55], v[144:147], v[172:175], v[52:55]
	v_mfma_f32_16x16x32_bf16 v[48:51], v[156:159], v[172:175], v[48:51]
	v_mfma_f32_16x16x32_bf16 v[44:47], v[144:147], v[204:207], v[44:47]
	v_mfma_f32_16x16x32_bf16 v[40:43], v[156:159], v[204:207], v[40:43]
	v_mfma_f32_16x16x32_bf16 v[36:39], v[144:147], v[212:215], v[36:39]
	v_mfma_f32_16x16x32_bf16 v[32:35], v[156:159], v[212:215], v[32:35]
	v_mfma_f32_16x16x32_bf16 v[28:31], v[216:219], v[160:163], v[28:31]
	v_mfma_f32_16x16x32_bf16 v[24:27], v[224:227], v[160:163], v[24:27]
	v_mfma_f32_16x16x32_bf16 v[20:23], v[216:219], v[168:171], v[20:23]
	v_mfma_f32_16x16x32_bf16 v[16:19], v[224:227], v[168:171], v[16:19]
	v_mfma_f32_16x16x32_bf16 v[12:15], v[216:219], v[176:179], v[12:15]
	v_mfma_f32_16x16x32_bf16 v[8:11], v[224:227], v[176:179], v[8:11]
	v_mfma_f32_16x16x32_bf16 v[4:7], v[216:219], v[208:211], v[4:7]
	v_mfma_f32_16x16x32_bf16 v[0:3], v[224:227], v[208:211], v[0:3]
	v_mfma_f32_16x16x32_bf16 v[28:31], v[220:223], v[164:167], v[28:31]
	v_mfma_f32_16x16x32_bf16 v[24:27], v[228:231], v[164:167], v[24:27]
	v_mfma_f32_16x16x32_bf16 v[20:23], v[220:223], v[172:175], v[20:23]
	v_mfma_f32_16x16x32_bf16 v[16:19], v[228:231], v[172:175], v[16:19]
	v_mfma_f32_16x16x32_bf16 v[12:15], v[220:223], v[204:207], v[12:15]
	v_mfma_f32_16x16x32_bf16 v[8:11], v[228:231], v[204:207], v[8:11]
	v_mfma_f32_16x16x32_bf16 v[4:7], v[220:223], v[212:215], v[4:7]
	v_mfma_f32_16x16x32_bf16 v[0:3], v[228:231], v[212:215], v[0:3]
	v_add_u32_e32 v156, 0x18000, v151
	s_barrier
	ds_read_b128 v[140:143], v156
	ds_read_b128 v[144:147], v156 offset:1024
	ds_read_b128 v[152:155], v156 offset:2048
	ds_read_b128 v[156:159], v156 offset:3072
	ds_read_b128 v[160:163], v150 offset:32768
	ds_read_b128 v[164:167], v150 offset:33792
	ds_read_b128 v[168:171], v150 offset:34816
	ds_read_b128 v[172:175], v150 offset:35840
	ds_read_b128 v[176:179], v150 offset:36864
	ds_read_b128 v[204:207], v150 offset:37888
	ds_read_b128 v[208:211], v150 offset:38912
	ds_read_b128 v[212:215], v150 offset:39936
	s_waitcnt vmcnt(2)
	s_barrier
	s_waitcnt lgkmcnt(0)
	s_waitcnt lgkmcnt(0)
	v_mfma_f32_16x16x32_bf16 v[124:127], v[140:143], v[160:163], v[124:127]
	v_mfma_f32_16x16x32_bf16 v[120:123], v[152:155], v[160:163], v[120:123]
	v_mfma_f32_16x16x32_bf16 v[116:119], v[140:143], v[168:171], v[116:119]
	v_mfma_f32_16x16x32_bf16 v[112:115], v[152:155], v[168:171], v[112:115]
	v_mfma_f32_16x16x32_bf16 v[108:111], v[140:143], v[176:179], v[108:111]
	v_mfma_f32_16x16x32_bf16 v[104:107], v[152:155], v[176:179], v[104:107]
	v_mfma_f32_16x16x32_bf16 v[100:103], v[140:143], v[208:211], v[100:103]
	v_mfma_f32_16x16x32_bf16 v[96:99], v[152:155], v[208:211], v[96:99]
	v_mfma_f32_16x16x32_bf16 v[124:127], v[144:147], v[164:167], v[124:127]
	v_mfma_f32_16x16x32_bf16 v[120:123], v[156:159], v[164:167], v[120:123]
	v_mfma_f32_16x16x32_bf16 v[116:119], v[144:147], v[172:175], v[116:119]
	v_mfma_f32_16x16x32_bf16 v[112:115], v[156:159], v[172:175], v[112:115]
	v_mfma_f32_16x16x32_bf16 v[108:111], v[144:147], v[204:207], v[108:111]
	v_mfma_f32_16x16x32_bf16 v[104:107], v[156:159], v[204:207], v[104:107]
	v_mfma_f32_16x16x32_bf16 v[100:103], v[144:147], v[212:215], v[100:103]
	v_mfma_f32_16x16x32_bf16 v[96:99], v[156:159], v[212:215], v[96:99]
	v_add_u32_e32 v151, 0x1c000, v151
	s_barrier
	ds_read_b128 v[216:219], v151
	ds_read_b128 v[220:223], v151 offset:1024
	ds_read_b128 v[224:227], v151 offset:2048
	ds_read_b128 v[228:231], v151 offset:3072
	s_waitcnt vmcnt(0)
	s_barrier
	s_waitcnt lgkmcnt(0)
	s_waitcnt lgkmcnt(0)
	v_mfma_f32_16x16x32_bf16 v[92:95], v[216:219], v[160:163], v[92:95]
	v_mfma_f32_16x16x32_bf16 v[88:91], v[224:227], v[160:163], v[88:91]
	v_mfma_f32_16x16x32_bf16 v[84:87], v[216:219], v[168:171], v[84:87]
	v_mfma_f32_16x16x32_bf16 v[80:83], v[224:227], v[168:171], v[80:83]
	v_mfma_f32_16x16x32_bf16 v[76:79], v[216:219], v[176:179], v[76:79]
	v_mfma_f32_16x16x32_bf16 v[72:75], v[224:227], v[176:179], v[72:75]
	v_mfma_f32_16x16x32_bf16 v[68:71], v[216:219], v[208:211], v[68:71]
	v_mfma_f32_16x16x32_bf16 v[64:67], v[224:227], v[208:211], v[64:67]
	v_mfma_f32_16x16x32_bf16 v[92:95], v[220:223], v[164:167], v[92:95]
	v_mfma_f32_16x16x32_bf16 v[88:91], v[228:231], v[164:167], v[88:91]
	v_mfma_f32_16x16x32_bf16 v[84:87], v[220:223], v[172:175], v[84:87]
	v_mfma_f32_16x16x32_bf16 v[80:83], v[228:231], v[172:175], v[80:83]
	v_mfma_f32_16x16x32_bf16 v[76:79], v[220:223], v[204:207], v[76:79]
	v_mfma_f32_16x16x32_bf16 v[72:75], v[228:231], v[204:207], v[72:75]
	v_mfma_f32_16x16x32_bf16 v[68:71], v[220:223], v[212:215], v[68:71]
	v_mfma_f32_16x16x32_bf16 v[64:67], v[228:231], v[212:215], v[64:67]
	s_barrier
	ds_read_b128 v[160:163], v150 offset:49152
	ds_read_b128 v[164:167], v150 offset:50176
	ds_read_b128 v[168:171], v150 offset:51200
	ds_read_b128 v[172:175], v150 offset:52224
	ds_read_b128 v[176:179], v150 offset:53248
	ds_read_b128 v[204:207], v150 offset:54272
	ds_read_b128 v[208:211], v150 offset:55296
	ds_read_b128 v[212:215], v150 offset:56320
	s_barrier
	s_waitcnt lgkmcnt(0)
	s_waitcnt lgkmcnt(0)
	v_mfma_f32_16x16x32_bf16 v[60:63], v[140:143], v[160:163], v[60:63]
	v_mfma_f32_16x16x32_bf16 v[56:59], v[152:155], v[160:163], v[56:59]
	v_mfma_f32_16x16x32_bf16 v[52:55], v[140:143], v[168:171], v[52:55]
	v_mfma_f32_16x16x32_bf16 v[48:51], v[152:155], v[168:171], v[48:51]
	v_mfma_f32_16x16x32_bf16 v[44:47], v[140:143], v[176:179], v[44:47]
	v_mfma_f32_16x16x32_bf16 v[40:43], v[152:155], v[176:179], v[40:43]
	v_mfma_f32_16x16x32_bf16 v[36:39], v[140:143], v[208:211], v[36:39]
	v_mfma_f32_16x16x32_bf16 v[32:35], v[152:155], v[208:211], v[32:35]
	v_mfma_f32_16x16x32_bf16 v[60:63], v[144:147], v[164:167], v[60:63]
	v_mfma_f32_16x16x32_bf16 v[56:59], v[156:159], v[164:167], v[56:59]
	v_mfma_f32_16x16x32_bf16 v[52:55], v[144:147], v[172:175], v[52:55]
	v_mfma_f32_16x16x32_bf16 v[48:51], v[156:159], v[172:175], v[48:51]
	v_mfma_f32_16x16x32_bf16 v[44:47], v[144:147], v[204:207], v[44:47]
	v_mfma_f32_16x16x32_bf16 v[40:43], v[156:159], v[204:207], v[40:43]
	v_mfma_f32_16x16x32_bf16 v[36:39], v[144:147], v[212:215], v[36:39]
	v_mfma_f32_16x16x32_bf16 v[32:35], v[156:159], v[212:215], v[32:35]
	v_mfma_f32_16x16x32_bf16 v[28:31], v[216:219], v[160:163], v[28:31]
	v_mfma_f32_16x16x32_bf16 v[24:27], v[224:227], v[160:163], v[24:27]
	v_mfma_f32_16x16x32_bf16 v[20:23], v[216:219], v[168:171], v[20:23]
	v_mfma_f32_16x16x32_bf16 v[16:19], v[224:227], v[168:171], v[16:19]
	v_mfma_f32_16x16x32_bf16 v[12:15], v[216:219], v[176:179], v[12:15]
	v_mfma_f32_16x16x32_bf16 v[8:11], v[224:227], v[176:179], v[8:11]
	v_mfma_f32_16x16x32_bf16 v[4:7], v[216:219], v[208:211], v[4:7]
	v_mfma_f32_16x16x32_bf16 v[0:3], v[224:227], v[208:211], v[0:3]
	v_mfma_f32_16x16x32_bf16 v[28:31], v[220:223], v[164:167], v[28:31]
	v_mfma_f32_16x16x32_bf16 v[24:27], v[228:231], v[164:167], v[24:27]
	v_mfma_f32_16x16x32_bf16 v[20:23], v[220:223], v[172:175], v[20:23]
	v_mfma_f32_16x16x32_bf16 v[16:19], v[228:231], v[172:175], v[16:19]
	v_mfma_f32_16x16x32_bf16 v[12:15], v[220:223], v[204:207], v[12:15]
	v_mfma_f32_16x16x32_bf16 v[8:11], v[228:231], v[204:207], v[8:11]
	v_mfma_f32_16x16x32_bf16 v[4:7], v[220:223], v[212:215], v[4:7]
	v_mfma_f32_16x16x32_bf16 v[0:3], v[228:231], v[212:215], v[0:3]
	s_barrier
	s_and_saveexec_b64 s[8:9], s[4:5]
	s_cbranch_execz .LBB0_1838
	s_barrier

.LBB0_1965:
	s_add_i32 s35, 32, 0x10000
	v_add_u32_e32 v153, s35, v151
	ds_read_b128 v[154:157], v153
	ds_read_b128 v[158:161], v153 offset:1024
	ds_read_b128 v[162:165], v153 offset:2048
	ds_read_b128 v[166:169], v153 offset:3072
	v_lshl_add_u64 v[178:179], v[144:145], 0, s[10:11]
	s_add_i32 s34, s17, 0xc000
	v_lshl_add_u64 v[188:189], v[178:179], 0, s[48:49]
	s_mov_b32 m0, s34
	ds_read_b128 v[170:173], v152
	ds_read_b128 v[174:177], v152 offset:1024
	ds_read_b128 v[204:207], v152 offset:2048
	ds_read_b128 v[208:211], v152 offset:3072
	ds_read_b128 v[212:215], v152 offset:4096
	ds_read_b128 v[216:219], v152 offset:5120
	ds_read_b128 v[220:223], v152 offset:6144
	ds_read_b128 v[224:227], v152 offset:7168
	global_load_lds_dwordx4 v[188:189], off
	v_lshl_add_u64 v[188:189], v[142:143], 0, s[10:11]
	s_add_i32 s15, s17, 0xe000
	v_lshl_add_u64 v[228:229], v[188:189], 0, s[48:49]
	s_mov_b32 m0, s15
	s_nop 0
	global_load_lds_dwordx4 v[228:229], off
	s_waitcnt lgkmcnt(8)
	s_barrier
	s_waitcnt lgkmcnt(0)
	s_waitcnt lgkmcnt(0)
	v_mfma_f32_16x16x32_bf16 v[124:127], v[154:157], v[170:173], v[124:127]
	v_mfma_f32_16x16x32_bf16 v[120:123], v[162:165], v[170:173], v[120:123]
	v_mfma_f32_16x16x32_bf16 v[116:119], v[154:157], v[204:207], v[116:119]
	v_mfma_f32_16x16x32_bf16 v[112:115], v[162:165], v[204:207], v[112:115]
	v_mfma_f32_16x16x32_bf16 v[108:111], v[154:157], v[212:215], v[108:111]
	v_mfma_f32_16x16x32_bf16 v[104:107], v[162:165], v[212:215], v[104:107]
	v_mfma_f32_16x16x32_bf16 v[100:103], v[154:157], v[220:223], v[100:103]
	v_mfma_f32_16x16x32_bf16 v[96:99], v[162:165], v[220:223], v[96:99]
	v_mfma_f32_16x16x32_bf16 v[124:127], v[158:161], v[174:177], v[124:127]
	v_mfma_f32_16x16x32_bf16 v[120:123], v[166:169], v[174:177], v[120:123]
	v_mfma_f32_16x16x32_bf16 v[116:119], v[158:161], v[208:211], v[116:119]
	v_mfma_f32_16x16x32_bf16 v[112:115], v[166:169], v[208:211], v[112:115]
	v_mfma_f32_16x16x32_bf16 v[108:111], v[158:161], v[216:219], v[108:111]
	v_mfma_f32_16x16x32_bf16 v[104:107], v[166:169], v[216:219], v[104:107]
	v_mfma_f32_16x16x32_bf16 v[100:103], v[158:161], v[224:227], v[100:103]
	v_mfma_f32_16x16x32_bf16 v[96:99], v[166:169], v[224:227], v[96:99]
	s_barrier
	s_add_i32 s36, 32, 0x14000
	v_lshl_add_u64 v[244:245], v[148:149], 0, s[10:11]
	s_add_i32 s35, s35, s22
	v_add_u32_e32 v153, s36, v151
	v_lshl_add_u64 v[246:247], v[244:245], 0, s[88:89]
	s_mov_b32 m0, s35
	ds_read_b128 v[228:231], v153
	ds_read_b128 v[232:235], v153 offset:1024
	ds_read_b128 v[236:239], v153 offset:2048
	ds_read_b128 v[240:243], v153 offset:3072
	global_load_lds_dwordx4 v[246:247], off
	v_lshl_add_u64 v[246:247], v[146:147], 0, s[10:11]
	v_lshl_add_u64 v[248:249], v[246:247], 0, s[88:89]
	s_add_i32 m0, s35, 0x2000
	s_nop 0
	global_load_lds_dwordx4 v[248:249], off
	s_barrier
	s_waitcnt lgkmcnt(0)
	s_waitcnt lgkmcnt(0)
	v_mfma_f32_16x16x32_bf16 v[92:95], v[228:231], v[170:173], v[92:95]
	v_mfma_f32_16x16x32_bf16 v[88:91], v[236:239], v[170:173], v[88:91]
	v_mfma_f32_16x16x32_bf16 v[84:87], v[228:231], v[204:207], v[84:87]
	v_mfma_f32_16x16x32_bf16 v[80:83], v[236:239], v[204:207], v[80:83]
	v_mfma_f32_16x16x32_bf16 v[76:79], v[228:231], v[212:215], v[76:79]
	v_mfma_f32_16x16x32_bf16 v[72:75], v[236:239], v[212:215], v[72:75]
	v_mfma_f32_16x16x32_bf16 v[68:71], v[228:231], v[220:223], v[68:71]
	v_mfma_f32_16x16x32_bf16 v[64:67], v[236:239], v[220:223], v[64:67]
	v_mfma_f32_16x16x32_bf16 v[92:95], v[232:235], v[174:177], v[92:95]
	v_mfma_f32_16x16x32_bf16 v[88:91], v[240:243], v[174:177], v[88:91]
	v_mfma_f32_16x16x32_bf16 v[84:87], v[232:235], v[208:211], v[84:87]
	v_mfma_f32_16x16x32_bf16 v[80:83], v[240:243], v[208:211], v[80:83]
	v_mfma_f32_16x16x32_bf16 v[76:79], v[232:235], v[216:219], v[76:79]
	v_mfma_f32_16x16x32_bf16 v[72:75], v[240:243], v[216:219], v[72:75]
	v_mfma_f32_16x16x32_bf16 v[68:71], v[232:235], v[224:227], v[68:71]
	v_mfma_f32_16x16x32_bf16 v[64:67], v[240:243], v[224:227], v[64:67]
	s_mov_b32 m0, s17
	v_lshl_add_u64 v[248:249], v[178:179], 0, s[88:89]
	s_barrier
	ds_read_b128 v[170:173], v152 offset:16384
	ds_read_b128 v[174:177], v152 offset:17408
	ds_read_b128 v[204:207], v152 offset:18432
	ds_read_b128 v[208:211], v152 offset:19456
	ds_read_b128 v[212:215], v152 offset:20480
	ds_read_b128 v[216:219], v152 offset:21504
	ds_read_b128 v[220:223], v152 offset:22528
	ds_read_b128 v[224:227], v152 offset:23552
	global_load_lds_dwordx4 v[248:249], off
	v_lshl_add_u64 v[248:249], v[188:189], 0, s[88:89]
	s_mov_b32 m0, s26
	s_nop 0
	global_load_lds_dwordx4 v[248:249], off
	s_barrier
	s_waitcnt lgkmcnt(0)
	s_waitcnt lgkmcnt(0)
	v_mfma_f32_16x16x32_bf16 v[60:63], v[154:157], v[170:173], v[60:63]
	v_mfma_f32_16x16x32_bf16 v[56:59], v[162:165], v[170:173], v[56:59]
	v_mfma_f32_16x16x32_bf16 v[52:55], v[154:157], v[204:207], v[52:55]
	v_mfma_f32_16x16x32_bf16 v[48:51], v[162:165], v[204:207], v[48:51]
	v_mfma_f32_16x16x32_bf16 v[44:47], v[154:157], v[212:215], v[44:47]
	v_mfma_f32_16x16x32_bf16 v[40:43], v[162:165], v[212:215], v[40:43]
	v_mfma_f32_16x16x32_bf16 v[36:39], v[154:157], v[220:223], v[36:39]
	v_mfma_f32_16x16x32_bf16 v[32:35], v[162:165], v[220:223], v[32:35]
	v_mfma_f32_16x16x32_bf16 v[60:63], v[158:161], v[174:177], v[60:63]
	v_mfma_f32_16x16x32_bf16 v[56:59], v[166:169], v[174:177], v[56:59]
	v_mfma_f32_16x16x32_bf16 v[52:55], v[158:161], v[208:211], v[52:55]
	v_mfma_f32_16x16x32_bf16 v[48:51], v[166:169], v[208:211], v[48:51]
	v_mfma_f32_16x16x32_bf16 v[44:47], v[158:161], v[216:219], v[44:47]
	v_mfma_f32_16x16x32_bf16 v[40:43], v[166:169], v[216:219], v[40:43]
	v_mfma_f32_16x16x32_bf16 v[36:39], v[158:161], v[224:227], v[36:39]
	v_mfma_f32_16x16x32_bf16 v[32:35], v[166:169], v[224:227], v[32:35]
	s_barrier
	s_add_i32 s35, s36, s22
	v_lshl_add_u64 v[154:155], v[244:245], 0, s[92:93]
	s_mov_b32 m0, s35
	s_nop 0
	global_load_lds_dwordx4 v[154:155], off
	v_lshl_add_u64 v[154:155], v[246:247], 0, s[92:93]
	s_add_i32 m0, s35, 0x2000
	s_nop 0
	global_load_lds_dwordx4 v[154:155], off
	s_waitcnt vmcnt(6)
	s_barrier
	v_mfma_f32_16x16x32_bf16 v[28:31], v[228:231], v[170:173], v[28:31]
	v_mfma_f32_16x16x32_bf16 v[24:27], v[236:239], v[170:173], v[24:27]
	v_mfma_f32_16x16x32_bf16 v[20:23], v[228:231], v[204:207], v[20:23]
	v_mfma_f32_16x16x32_bf16 v[16:19], v[236:239], v[204:207], v[16:19]
	v_mfma_f32_16x16x32_bf16 v[12:15], v[228:231], v[212:215], v[12:15]
	v_mfma_f32_16x16x32_bf16 v[8:11], v[236:239], v[212:215], v[8:11]
	v_mfma_f32_16x16x32_bf16 v[4:7], v[228:231], v[220:223], v[4:7]
	v_mfma_f32_16x16x32_bf16 v[0:3], v[236:239], v[220:223], v[0:3]
	v_mfma_f32_16x16x32_bf16 v[28:31], v[232:235], v[174:177], v[28:31]
	v_mfma_f32_16x16x32_bf16 v[24:27], v[240:243], v[174:177], v[24:27]
	v_mfma_f32_16x16x32_bf16 v[20:23], v[232:235], v[208:211], v[20:23]
	v_mfma_f32_16x16x32_bf16 v[16:19], v[240:243], v[208:211], v[16:19]
	v_mfma_f32_16x16x32_bf16 v[12:15], v[232:235], v[216:219], v[12:15]
	v_mfma_f32_16x16x32_bf16 v[8:11], v[240:243], v[216:219], v[8:11]
	v_mfma_f32_16x16x32_bf16 v[4:7], v[232:235], v[224:227], v[4:7]
	v_mfma_f32_16x16x32_bf16 v[0:3], v[240:243], v[224:227], v[0:3]
	s_add_i32 s35, 32, 0x18000
	v_add_u32_e32 v153, s35, v151
	s_barrier
	ds_read_b128 v[154:157], v153
	ds_read_b128 v[158:161], v153 offset:1024
	ds_read_b128 v[162:165], v153 offset:2048
	ds_read_b128 v[166:169], v153 offset:3072
	s_mov_b32 m0, s29
	v_lshl_add_u64 v[228:229], v[178:179], 0, s[92:93]
	ds_read_b128 v[170:173], v152 offset:32768
	ds_read_b128 v[174:177], v152 offset:33792
	ds_read_b128 v[204:207], v152 offset:34816
	ds_read_b128 v[208:211], v152 offset:35840
	ds_read_b128 v[212:215], v152 offset:36864
	ds_read_b128 v[216:219], v152 offset:37888
	ds_read_b128 v[220:223], v152 offset:38912
	ds_read_b128 v[224:227], v152 offset:39936
	global_load_lds_dwordx4 v[228:229], off
	v_lshl_add_u64 v[228:229], v[188:189], 0, s[92:93]
	s_mov_b32 m0, s30
	s_nop 0
	global_load_lds_dwordx4 v[228:229], off
	s_waitcnt lgkmcnt(8)
	s_barrier
	s_waitcnt lgkmcnt(0)
	s_waitcnt lgkmcnt(0)
	v_mfma_f32_16x16x32_bf16 v[124:127], v[154:157], v[170:173], v[124:127]
	v_mfma_f32_16x16x32_bf16 v[120:123], v[162:165], v[170:173], v[120:123]
	v_mfma_f32_16x16x32_bf16 v[116:119], v[154:157], v[204:207], v[116:119]
	v_mfma_f32_16x16x32_bf16 v[112:115], v[162:165], v[204:207], v[112:115]
	v_mfma_f32_16x16x32_bf16 v[108:111], v[154:157], v[212:215], v[108:111]
	v_mfma_f32_16x16x32_bf16 v[104:107], v[162:165], v[212:215], v[104:107]
	v_mfma_f32_16x16x32_bf16 v[100:103], v[154:157], v[220:223], v[100:103]
	v_mfma_f32_16x16x32_bf16 v[96:99], v[162:165], v[220:223], v[96:99]
	v_mfma_f32_16x16x32_bf16 v[124:127], v[158:161], v[174:177], v[124:127]
	v_mfma_f32_16x16x32_bf16 v[120:123], v[166:169], v[174:177], v[120:123]
	v_mfma_f32_16x16x32_bf16 v[116:119], v[158:161], v[208:211], v[116:119]
	v_mfma_f32_16x16x32_bf16 v[112:115], v[166:169], v[208:211], v[112:115]
	v_mfma_f32_16x16x32_bf16 v[108:111], v[158:161], v[216:219], v[108:111]
	v_mfma_f32_16x16x32_bf16 v[104:107], v[166:169], v[216:219], v[104:107]
	v_mfma_f32_16x16x32_bf16 v[100:103], v[158:161], v[224:227], v[100:103]
	v_mfma_f32_16x16x32_bf16 v[96:99], v[166:169], v[224:227], v[96:99]
	s_barrier
	s_add_i32 s36, 32, 0x1c000
	s_add_i32 s35, s35, s22
	v_add_u32_e32 v153, s36, v151
	v_lshl_add_u64 v[248:249], v[244:245], 0, s[90:91]
	s_mov_b32 m0, s35
	ds_read_b128 v[228:231], v153
	ds_read_b128 v[232:235], v153 offset:1024
	ds_read_b128 v[236:239], v153 offset:2048
	ds_read_b128 v[240:243], v153 offset:3072
	global_load_lds_dwordx4 v[248:249], off
	v_lshl_add_u64 v[248:249], v[246:247], 0, s[90:91]
	s_add_i32 m0, s35, 0x2000
	s_nop 0
	global_load_lds_dwordx4 v[248:249], off
	s_barrier
	s_waitcnt lgkmcnt(0)
	s_waitcnt lgkmcnt(0)
	v_mfma_f32_16x16x32_bf16 v[92:95], v[228:231], v[170:173], v[92:95]
	v_mfma_f32_16x16x32_bf16 v[88:91], v[236:239], v[170:173], v[88:91]
	v_mfma_f32_16x16x32_bf16 v[84:87], v[228:231], v[204:207], v[84:87]
	v_mfma_f32_16x16x32_bf16 v[80:83], v[236:239], v[204:207], v[80:83]
	v_mfma_f32_16x16x32_bf16 v[76:79], v[228:231], v[212:215], v[76:79]
	v_mfma_f32_16x16x32_bf16 v[72:75], v[236:239], v[212:215], v[72:75]
	v_mfma_f32_16x16x32_bf16 v[68:71], v[228:231], v[220:223], v[68:71]
	v_mfma_f32_16x16x32_bf16 v[64:67], v[236:239], v[220:223], v[64:67]
	v_mfma_f32_16x16x32_bf16 v[92:95], v[232:235], v[174:177], v[92:95]
	v_mfma_f32_16x16x32_bf16 v[88:91], v[240:243], v[174:177], v[88:91]
	v_mfma_f32_16x16x32_bf16 v[84:87], v[232:235], v[208:211], v[84:87]
	v_mfma_f32_16x16x32_bf16 v[80:83], v[240:243], v[208:211], v[80:83]
	v_mfma_f32_16x16x32_bf16 v[76:79], v[232:235], v[216:219], v[76:79]
	v_mfma_f32_16x16x32_bf16 v[72:75], v[240:243], v[216:219], v[72:75]
	v_mfma_f32_16x16x32_bf16 v[68:71], v[232:235], v[224:227], v[68:71]
	v_mfma_f32_16x16x32_bf16 v[64:67], v[240:243], v[224:227], v[64:67]
	s_mov_b32 m0, s12
	v_lshl_add_u64 v[178:179], v[178:179], 0, s[90:91]
	s_barrier
	ds_read_b128 v[170:173], v152 offset:49152
	ds_read_b128 v[174:177], v152 offset:50176
	ds_read_b128 v[204:207], v152 offset:51200
	ds_read_b128 v[208:211], v152 offset:52224
	ds_read_b128 v[212:215], v152 offset:53248
	ds_read_b128 v[216:219], v152 offset:54272
	ds_read_b128 v[220:223], v152 offset:55296
	ds_read_b128 v[224:227], v152 offset:56320
	global_load_lds_dwordx4 v[178:179], off
	v_lshl_add_u64 v[178:179], v[188:189], 0, s[90:91]
	s_mov_b32 m0, s13
	s_nop 0
	global_load_lds_dwordx4 v[178:179], off
	s_barrier
	s_waitcnt lgkmcnt(0)
	s_waitcnt lgkmcnt(0)
	v_mfma_f32_16x16x32_bf16 v[60:63], v[154:157], v[170:173], v[60:63]
	v_mfma_f32_16x16x32_bf16 v[56:59], v[162:165], v[170:173], v[56:59]
	v_mfma_f32_16x16x32_bf16 v[52:55], v[154:157], v[204:207], v[52:55]
	v_mfma_f32_16x16x32_bf16 v[48:51], v[162:165], v[204:207], v[48:51]
	v_mfma_f32_16x16x32_bf16 v[44:47], v[154:157], v[212:215], v[44:47]
	v_mfma_f32_16x16x32_bf16 v[40:43], v[162:165], v[212:215], v[40:43]
	v_mfma_f32_16x16x32_bf16 v[36:39], v[154:157], v[220:223], v[36:39]
	v_mfma_f32_16x16x32_bf16 v[32:35], v[162:165], v[220:223], v[32:35]
	v_mfma_f32_16x16x32_bf16 v[60:63], v[158:161], v[174:177], v[60:63]
	v_mfma_f32_16x16x32_bf16 v[56:59], v[166:169], v[174:177], v[56:59]
	v_mfma_f32_16x16x32_bf16 v[52:55], v[158:161], v[208:211], v[52:55]
	v_mfma_f32_16x16x32_bf16 v[48:51], v[166:169], v[208:211], v[48:51]
	v_mfma_f32_16x16x32_bf16 v[44:47], v[158:161], v[216:219], v[44:47]
	v_mfma_f32_16x16x32_bf16 v[40:43], v[166:169], v[216:219], v[40:43]
	v_mfma_f32_16x16x32_bf16 v[36:39], v[158:161], v[224:227], v[36:39]
	v_mfma_f32_16x16x32_bf16 v[32:35], v[166:169], v[224:227], v[32:35]
	s_barrier
	s_add_i32 s35, s36, s22
	v_lshl_add_u64 v[154:155], v[244:245], 0, s[50:51]
	s_mov_b32 m0, s35
	s_nop 0
	global_load_lds_dwordx4 v[154:155], off
	v_lshl_add_u64 v[154:155], v[246:247], 0, s[50:51]
	s_add_i32 m0, s35, 0x2000
	s_nop 0
	global_load_lds_dwordx4 v[154:155], off
	s_waitcnt vmcnt(6)
	s_barrier
	v_mfma_f32_16x16x32_bf16 v[28:31], v[228:231], v[170:173], v[28:31]
	v_mfma_f32_16x16x32_bf16 v[24:27], v[236:239], v[170:173], v[24:27]
	v_mfma_f32_16x16x32_bf16 v[20:23], v[228:231], v[204:207], v[20:23]
	v_mfma_f32_16x16x32_bf16 v[16:19], v[236:239], v[204:207], v[16:19]
	v_mfma_f32_16x16x32_bf16 v[12:15], v[228:231], v[212:215], v[12:15]
	v_mfma_f32_16x16x32_bf16 v[8:11], v[236:239], v[212:215], v[8:11]
	v_mfma_f32_16x16x32_bf16 v[4:7], v[228:231], v[220:223], v[4:7]
	v_mfma_f32_16x16x32_bf16 v[0:3], v[236:239], v[220:223], v[0:3]
	v_mfma_f32_16x16x32_bf16 v[28:31], v[232:235], v[174:177], v[28:31]
	v_mfma_f32_16x16x32_bf16 v[24:27], v[240:243], v[174:177], v[24:27]
	v_mfma_f32_16x16x32_bf16 v[20:23], v[232:235], v[208:211], v[20:23]
	v_mfma_f32_16x16x32_bf16 v[16:19], v[240:243], v[208:211], v[16:19]
	v_mfma_f32_16x16x32_bf16 v[12:15], v[232:235], v[216:219], v[12:15]
	v_mfma_f32_16x16x32_bf16 v[8:11], v[240:243], v[216:219], v[8:11]
	v_mfma_f32_16x16x32_bf16 v[4:7], v[232:235], v[224:227], v[4:7]
	v_mfma_f32_16x16x32_bf16 v[0:3], v[240:243], v[224:227], v[0:3]
	s_add_i32 s14, s14, 2
	s_add_u32 s10, s10, 0x100
	s_addc_u32 s11, s11, 0
	s_cmp_lt_u32 s14, 12
	s_barrier
	s_cbranch_scc1 .LBB0_1965
	s_add_u32 s10, s8, 0x40780
	v_add_u32_e32 v153, 32, v151
	s_addc_u32 s11, s9, 0
	s_mov_b32 m0, s34
	v_add_u32_e32 v158, 0x10000, v153
	v_lshl_add_u64 v[178:179], s[10:11], 0, v[128:129]
	ds_read_b128 v[142:145], v158
	ds_read_b128 v[146:149], v158 offset:1024
	ds_read_b128 v[154:157], v158 offset:2048
	ds_read_b128 v[158:161], v158 offset:3072
	ds_read_b128 v[162:165], v152
	ds_read_b128 v[166:169], v152 offset:1024
	ds_read_b128 v[170:173], v152 offset:2048
	ds_read_b128 v[174:177], v152 offset:3072
	ds_read_b128 v[204:207], v152 offset:4096
	ds_read_b128 v[208:211], v152 offset:5120
	ds_read_b128 v[212:215], v152 offset:6144
	ds_read_b128 v[216:219], v152 offset:7168
	global_load_lds_dwordx4 v[178:179], off
	v_lshl_add_u64 v[178:179], s[10:11], 0, v[134:135]
	s_mov_b32 m0, s15
	s_nop 0
	global_load_lds_dwordx4 v[178:179], off
	s_barrier
	s_waitcnt lgkmcnt(0)
	s_waitcnt lgkmcnt(0)
	v_mfma_f32_16x16x32_bf16 v[124:127], v[142:145], v[162:165], v[124:127]
	v_mfma_f32_16x16x32_bf16 v[120:123], v[154:157], v[162:165], v[120:123]
	v_mfma_f32_16x16x32_bf16 v[116:119], v[142:145], v[170:173], v[116:119]
	v_mfma_f32_16x16x32_bf16 v[112:115], v[154:157], v[170:173], v[112:115]
	v_mfma_f32_16x16x32_bf16 v[108:111], v[142:145], v[204:207], v[108:111]
	v_mfma_f32_16x16x32_bf16 v[104:107], v[154:157], v[204:207], v[104:107]
	v_mfma_f32_16x16x32_bf16 v[100:103], v[142:145], v[212:215], v[100:103]
	v_mfma_f32_16x16x32_bf16 v[96:99], v[154:157], v[212:215], v[96:99]
	v_mfma_f32_16x16x32_bf16 v[124:127], v[146:149], v[166:169], v[124:127]
	v_mfma_f32_16x16x32_bf16 v[120:123], v[158:161], v[166:169], v[120:123]
	v_mfma_f32_16x16x32_bf16 v[116:119], v[146:149], v[174:177], v[116:119]
	v_mfma_f32_16x16x32_bf16 v[112:115], v[158:161], v[174:177], v[112:115]
	v_mfma_f32_16x16x32_bf16 v[108:111], v[146:149], v[208:211], v[108:111]
	v_mfma_f32_16x16x32_bf16 v[104:107], v[158:161], v[208:211], v[104:107]
	v_mfma_f32_16x16x32_bf16 v[100:103], v[146:149], v[216:219], v[100:103]
	v_mfma_f32_16x16x32_bf16 v[96:99], v[158:161], v[216:219], v[96:99]
	v_add_u32_e32 v178, 0x14000, v153
	s_barrier
	ds_read_b128 v[220:223], v178
	ds_read_b128 v[224:227], v178 offset:1024
	ds_read_b128 v[228:231], v178 offset:2048
	ds_read_b128 v[232:235], v178 offset:3072
	s_barrier
	s_waitcnt lgkmcnt(0)
	s_waitcnt lgkmcnt(0)
	v_mfma_f32_16x16x32_bf16 v[92:95], v[220:223], v[162:165], v[92:95]
	v_mfma_f32_16x16x32_bf16 v[88:91], v[228:231], v[162:165], v[88:91]
	v_mfma_f32_16x16x32_bf16 v[84:87], v[220:223], v[170:173], v[84:87]
	v_mfma_f32_16x16x32_bf16 v[80:83], v[228:231], v[170:173], v[80:83]
	v_mfma_f32_16x16x32_bf16 v[76:79], v[220:223], v[204:207], v[76:79]
	v_mfma_f32_16x16x32_bf16 v[72:75], v[228:231], v[204:207], v[72:75]
	v_mfma_f32_16x16x32_bf16 v[68:71], v[220:223], v[212:215], v[68:71]
	v_mfma_f32_16x16x32_bf16 v[64:67], v[228:231], v[212:215], v[64:67]
	v_mfma_f32_16x16x32_bf16 v[92:95], v[224:227], v[166:169], v[92:95]
	v_mfma_f32_16x16x32_bf16 v[88:91], v[232:235], v[166:169], v[88:91]
	v_mfma_f32_16x16x32_bf16 v[84:87], v[224:227], v[174:177], v[84:87]
	v_mfma_f32_16x16x32_bf16 v[80:83], v[232:235], v[174:177], v[80:83]
	v_mfma_f32_16x16x32_bf16 v[76:79], v[224:227], v[208:211], v[76:79]
	v_mfma_f32_16x16x32_bf16 v[72:75], v[232:235], v[208:211], v[72:75]
	v_mfma_f32_16x16x32_bf16 v[68:71], v[224:227], v[216:219], v[68:71]
	v_mfma_f32_16x16x32_bf16 v[64:67], v[232:235], v[216:219], v[64:67]
	s_barrier
	ds_read_b128 v[162:165], v152 offset:16384
	ds_read_b128 v[166:169], v152 offset:17408
	ds_read_b128 v[170:173], v152 offset:18432
	ds_read_b128 v[174:177], v152 offset:19456
	ds_read_b128 v[204:207], v152 offset:20480
	ds_read_b128 v[208:211], v152 offset:21504
	ds_read_b128 v[212:215], v152 offset:22528
	ds_read_b128 v[216:219], v152 offset:23552
	s_waitcnt vmcnt(4)
	s_barrier
	s_waitcnt lgkmcnt(0)
	s_waitcnt lgkmcnt(0)
	v_mfma_f32_16x16x32_bf16 v[60:63], v[142:145], v[162:165], v[60:63]
	v_mfma_f32_16x16x32_bf16 v[56:59], v[154:157], v[162:165], v[56:59]
	v_mfma_f32_16x16x32_bf16 v[52:55], v[142:145], v[170:173], v[52:55]
	v_mfma_f32_16x16x32_bf16 v[48:51], v[154:157], v[170:173], v[48:51]
	v_mfma_f32_16x16x32_bf16 v[44:47], v[142:145], v[204:207], v[44:47]
	v_mfma_f32_16x16x32_bf16 v[40:43], v[154:157], v[204:207], v[40:43]
	v_mfma_f32_16x16x32_bf16 v[36:39], v[142:145], v[212:215], v[36:39]
	v_mfma_f32_16x16x32_bf16 v[32:35], v[154:157], v[212:215], v[32:35]
	v_mfma_f32_16x16x32_bf16 v[60:63], v[146:149], v[166:169], v[60:63]
	v_mfma_f32_16x16x32_bf16 v[56:59], v[158:161], v[166:169], v[56:59]
	v_mfma_f32_16x16x32_bf16 v[52:55], v[146:149], v[174:177], v[52:55]
	v_mfma_f32_16x16x32_bf16 v[48:51], v[158:161], v[174:177], v[48:51]
	v_mfma_f32_16x16x32_bf16 v[44:47], v[146:149], v[208:211], v[44:47]
	v_mfma_f32_16x16x32_bf16 v[40:43], v[158:161], v[208:211], v[40:43]
	v_mfma_f32_16x16x32_bf16 v[36:39], v[146:149], v[216:219], v[36:39]
	v_mfma_f32_16x16x32_bf16 v[32:35], v[158:161], v[216:219], v[32:35]
	v_mfma_f32_16x16x32_bf16 v[28:31], v[220:223], v[162:165], v[28:31]
	v_mfma_f32_16x16x32_bf16 v[24:27], v[228:231], v[162:165], v[24:27]
	v_mfma_f32_16x16x32_bf16 v[20:23], v[220:223], v[170:173], v[20:23]
	v_mfma_f32_16x16x32_bf16 v[16:19], v[228:231], v[170:173], v[16:19]
	v_mfma_f32_16x16x32_bf16 v[12:15], v[220:223], v[204:207], v[12:15]
	v_mfma_f32_16x16x32_bf16 v[8:11], v[228:231], v[204:207], v[8:11]
	v_mfma_f32_16x16x32_bf16 v[4:7], v[220:223], v[212:215], v[4:7]
	v_mfma_f32_16x16x32_bf16 v[0:3], v[228:231], v[212:215], v[0:3]
	v_mfma_f32_16x16x32_bf16 v[28:31], v[224:227], v[166:169], v[28:31]
	v_mfma_f32_16x16x32_bf16 v[24:27], v[232:235], v[166:169], v[24:27]
	v_mfma_f32_16x16x32_bf16 v[20:23], v[224:227], v[174:177], v[20:23]
	v_mfma_f32_16x16x32_bf16 v[16:19], v[232:235], v[174:177], v[16:19]
	v_mfma_f32_16x16x32_bf16 v[12:15], v[224:227], v[208:211], v[12:15]
	v_mfma_f32_16x16x32_bf16 v[8:11], v[232:235], v[208:211], v[8:11]
	v_mfma_f32_16x16x32_bf16 v[4:7], v[224:227], v[216:219], v[4:7]
	v_mfma_f32_16x16x32_bf16 v[0:3], v[232:235], v[216:219], v[0:3]
	v_add_u32_e32 v158, 0x18000, v153
	s_barrier
	ds_read_b128 v[142:145], v158
	ds_read_b128 v[146:149], v158 offset:1024
	ds_read_b128 v[154:157], v158 offset:2048
	ds_read_b128 v[158:161], v158 offset:3072
	ds_read_b128 v[162:165], v152 offset:32768
	ds_read_b128 v[166:169], v152 offset:33792
	ds_read_b128 v[170:173], v152 offset:34816
	ds_read_b128 v[174:177], v152 offset:35840
	ds_read_b128 v[204:207], v152 offset:36864
	ds_read_b128 v[208:211], v152 offset:37888
	ds_read_b128 v[212:215], v152 offset:38912
	ds_read_b128 v[216:219], v152 offset:39936
	s_waitcnt vmcnt(2)
	s_barrier
	s_waitcnt lgkmcnt(0)
	s_waitcnt lgkmcnt(0)
	v_mfma_f32_16x16x32_bf16 v[124:127], v[142:145], v[162:165], v[124:127]
	v_mfma_f32_16x16x32_bf16 v[120:123], v[154:157], v[162:165], v[120:123]
	v_mfma_f32_16x16x32_bf16 v[116:119], v[142:145], v[170:173], v[116:119]
	v_mfma_f32_16x16x32_bf16 v[112:115], v[154:157], v[170:173], v[112:115]
	v_mfma_f32_16x16x32_bf16 v[108:111], v[142:145], v[204:207], v[108:111]
	v_mfma_f32_16x16x32_bf16 v[104:107], v[154:157], v[204:207], v[104:107]
	v_mfma_f32_16x16x32_bf16 v[100:103], v[142:145], v[212:215], v[100:103]
	v_mfma_f32_16x16x32_bf16 v[96:99], v[154:157], v[212:215], v[96:99]
	v_mfma_f32_16x16x32_bf16 v[124:127], v[146:149], v[166:169], v[124:127]
	v_mfma_f32_16x16x32_bf16 v[120:123], v[158:161], v[166:169], v[120:123]
	v_mfma_f32_16x16x32_bf16 v[116:119], v[146:149], v[174:177], v[116:119]
	v_mfma_f32_16x16x32_bf16 v[112:115], v[158:161], v[174:177], v[112:115]
	v_mfma_f32_16x16x32_bf16 v[108:111], v[146:149], v[208:211], v[108:111]
	v_mfma_f32_16x16x32_bf16 v[104:107], v[158:161], v[208:211], v[104:107]
	v_mfma_f32_16x16x32_bf16 v[100:103], v[146:149], v[216:219], v[100:103]
	v_mfma_f32_16x16x32_bf16 v[96:99], v[158:161], v[216:219], v[96:99]
	v_add_u32_e32 v153, 0x1c000, v153
	s_barrier
	ds_read_b128 v[220:223], v153
	ds_read_b128 v[224:227], v153 offset:1024
	ds_read_b128 v[228:231], v153 offset:2048
	ds_read_b128 v[232:235], v153 offset:3072
	s_waitcnt vmcnt(0)
	s_barrier
	s_waitcnt lgkmcnt(0)
	s_waitcnt lgkmcnt(0)
	v_mfma_f32_16x16x32_bf16 v[92:95], v[220:223], v[162:165], v[92:95]
	v_mfma_f32_16x16x32_bf16 v[88:91], v[228:231], v[162:165], v[88:91]
	v_mfma_f32_16x16x32_bf16 v[84:87], v[220:223], v[170:173], v[84:87]
	v_mfma_f32_16x16x32_bf16 v[80:83], v[228:231], v[170:173], v[80:83]
	v_mfma_f32_16x16x32_bf16 v[76:79], v[220:223], v[204:207], v[76:79]
	v_mfma_f32_16x16x32_bf16 v[72:75], v[228:231], v[204:207], v[72:75]
	v_mfma_f32_16x16x32_bf16 v[68:71], v[220:223], v[212:215], v[68:71]
	v_mfma_f32_16x16x32_bf16 v[64:67], v[228:231], v[212:215], v[64:67]
	v_mfma_f32_16x16x32_bf16 v[92:95], v[224:227], v[166:169], v[92:95]
	v_mfma_f32_16x16x32_bf16 v[88:91], v[232:235], v[166:169], v[88:91]
	v_mfma_f32_16x16x32_bf16 v[84:87], v[224:227], v[174:177], v[84:87]
	v_mfma_f32_16x16x32_bf16 v[80:83], v[232:235], v[174:177], v[80:83]
	v_mfma_f32_16x16x32_bf16 v[76:79], v[224:227], v[208:211], v[76:79]
	v_mfma_f32_16x16x32_bf16 v[72:75], v[232:235], v[208:211], v[72:75]
	v_mfma_f32_16x16x32_bf16 v[68:71], v[224:227], v[216:219], v[68:71]
	v_mfma_f32_16x16x32_bf16 v[64:67], v[232:235], v[216:219], v[64:67]
	s_barrier
	ds_read_b128 v[162:165], v152 offset:49152
	ds_read_b128 v[166:169], v152 offset:50176
	ds_read_b128 v[170:173], v152 offset:51200
	ds_read_b128 v[174:177], v152 offset:52224
	ds_read_b128 v[204:207], v152 offset:53248
	ds_read_b128 v[208:211], v152 offset:54272
	ds_read_b128 v[212:215], v152 offset:55296
	ds_read_b128 v[216:219], v152 offset:56320
	s_barrier
	s_waitcnt lgkmcnt(0)
	s_waitcnt lgkmcnt(0)
	v_mfma_f32_16x16x32_bf16 v[60:63], v[142:145], v[162:165], v[60:63]
	v_mfma_f32_16x16x32_bf16 v[56:59], v[154:157], v[162:165], v[56:59]
	v_mfma_f32_16x16x32_bf16 v[52:55], v[142:145], v[170:173], v[52:55]
	v_mfma_f32_16x16x32_bf16 v[48:51], v[154:157], v[170:173], v[48:51]
	v_mfma_f32_16x16x32_bf16 v[44:47], v[142:145], v[204:207], v[44:47]
	v_mfma_f32_16x16x32_bf16 v[40:43], v[154:157], v[204:207], v[40:43]
	v_mfma_f32_16x16x32_bf16 v[36:39], v[142:145], v[212:215], v[36:39]
	v_mfma_f32_16x16x32_bf16 v[32:35], v[154:157], v[212:215], v[32:35]
	v_mfma_f32_16x16x32_bf16 v[60:63], v[146:149], v[166:169], v[60:63]
	v_mfma_f32_16x16x32_bf16 v[56:59], v[158:161], v[166:169], v[56:59]
	v_mfma_f32_16x16x32_bf16 v[52:55], v[146:149], v[174:177], v[52:55]
	v_mfma_f32_16x16x32_bf16 v[48:51], v[158:161], v[174:177], v[48:51]
	v_mfma_f32_16x16x32_bf16 v[44:47], v[146:149], v[208:211], v[44:47]
	v_mfma_f32_16x16x32_bf16 v[40:43], v[158:161], v[208:211], v[40:43]
	v_mfma_f32_16x16x32_bf16 v[36:39], v[146:149], v[216:219], v[36:39]
	v_mfma_f32_16x16x32_bf16 v[32:35], v[158:161], v[216:219], v[32:35]
	v_mfma_f32_16x16x32_bf16 v[28:31], v[220:223], v[162:165], v[28:31]
	v_mfma_f32_16x16x32_bf16 v[24:27], v[228:231], v[162:165], v[24:27]
	v_mfma_f32_16x16x32_bf16 v[20:23], v[220:223], v[170:173], v[20:23]
	v_mfma_f32_16x16x32_bf16 v[16:19], v[228:231], v[170:173], v[16:19]
	v_mfma_f32_16x16x32_bf16 v[12:15], v[220:223], v[204:207], v[12:15]
	v_mfma_f32_16x16x32_bf16 v[8:11], v[228:231], v[204:207], v[8:11]
	v_mfma_f32_16x16x32_bf16 v[4:7], v[220:223], v[212:215], v[4:7]
	v_mfma_f32_16x16x32_bf16 v[0:3], v[228:231], v[212:215], v[0:3]
	v_mfma_f32_16x16x32_bf16 v[28:31], v[224:227], v[166:169], v[28:31]
	v_mfma_f32_16x16x32_bf16 v[24:27], v[232:235], v[166:169], v[24:27]
	v_mfma_f32_16x16x32_bf16 v[20:23], v[224:227], v[174:177], v[20:23]
	v_mfma_f32_16x16x32_bf16 v[16:19], v[232:235], v[174:177], v[16:19]
	v_mfma_f32_16x16x32_bf16 v[12:15], v[224:227], v[208:211], v[12:15]
	v_mfma_f32_16x16x32_bf16 v[8:11], v[232:235], v[208:211], v[8:11]
	v_mfma_f32_16x16x32_bf16 v[4:7], v[224:227], v[216:219], v[4:7]
	v_mfma_f32_16x16x32_bf16 v[0:3], v[232:235], v[216:219], v[0:3]
	s_barrier
	s_and_saveexec_b64 s[10:11], s[6:7]
	s_cbranch_execz .LBB0_1968
	s_barrier

.LBB0_2030:
	s_add_i32 s29, 32, 0x10000
	v_add_u32_e32 v151, s29, v148
	ds_read_b128 v[152:155], v151
	ds_read_b128 v[156:159], v151 offset:1024
	ds_read_b128 v[160:163], v151 offset:2048
	ds_read_b128 v[164:167], v151 offset:3072
	v_lshl_add_u64 v[188:189], v[144:145], 0, s[10:11]
	s_add_i32 s28, s13, 0xc000
	v_lshl_add_u64 v[224:225], v[188:189], 0, s[34:35]
	s_mov_b32 m0, s28
	v_lshl_add_u64 v[240:241], v[146:147], 0, s[10:11]
	s_add_i32 s27, s13, 0xe000
	ds_read_b128 v[168:171], v150
	ds_read_b128 v[172:175], v150 offset:1024
	ds_read_b128 v[176:179], v150 offset:2048
	ds_read_b128 v[204:207], v150 offset:3072
	ds_read_b128 v[208:211], v150 offset:4096
	ds_read_b128 v[212:215], v150 offset:5120
	ds_read_b128 v[216:219], v150 offset:6144
	ds_read_b128 v[220:223], v150 offset:7168
	global_load_lds_dwordx4 v[224:225], off
	v_lshl_add_u64 v[224:225], v[240:241], 0, s[34:35]
	s_mov_b32 m0, s27
	s_nop 0
	global_load_lds_dwordx4 v[224:225], off
	s_waitcnt lgkmcnt(8)
	s_barrier
	s_waitcnt lgkmcnt(0)
	s_waitcnt lgkmcnt(0)
	v_mfma_f32_16x16x32_bf16 v[124:127], v[152:155], v[168:171], v[124:127]
	v_mfma_f32_16x16x32_bf16 v[120:123], v[160:163], v[168:171], v[120:123]
	v_mfma_f32_16x16x32_bf16 v[116:119], v[152:155], v[176:179], v[116:119]
	v_mfma_f32_16x16x32_bf16 v[112:115], v[160:163], v[176:179], v[112:115]
	v_mfma_f32_16x16x32_bf16 v[108:111], v[152:155], v[208:211], v[108:111]
	v_mfma_f32_16x16x32_bf16 v[104:107], v[160:163], v[208:211], v[104:107]
	v_mfma_f32_16x16x32_bf16 v[100:103], v[152:155], v[216:219], v[100:103]
	v_mfma_f32_16x16x32_bf16 v[96:99], v[160:163], v[216:219], v[96:99]
	v_mfma_f32_16x16x32_bf16 v[124:127], v[156:159], v[172:175], v[124:127]
	v_mfma_f32_16x16x32_bf16 v[120:123], v[164:167], v[172:175], v[120:123]
	v_mfma_f32_16x16x32_bf16 v[116:119], v[156:159], v[204:207], v[116:119]
	v_mfma_f32_16x16x32_bf16 v[112:115], v[164:167], v[204:207], v[112:115]
	v_mfma_f32_16x16x32_bf16 v[108:111], v[156:159], v[212:215], v[108:111]
	v_mfma_f32_16x16x32_bf16 v[104:107], v[164:167], v[212:215], v[104:107]
	v_mfma_f32_16x16x32_bf16 v[100:103], v[156:159], v[220:223], v[100:103]
	v_mfma_f32_16x16x32_bf16 v[96:99], v[164:167], v[220:223], v[96:99]
	s_barrier
	s_add_i32 s30, 32, 0x14000
	v_lshl_add_u64 v[242:243], v[140:141], 0, s[10:11]
	s_add_i32 s29, s29, s12
	v_add_u32_e32 v151, s30, v148
	v_lshl_add_u64 v[244:245], v[242:243], 0, s[88:89]
	s_mov_b32 m0, s29
	ds_read_b128 v[224:227], v151
	ds_read_b128 v[228:231], v151 offset:1024
	ds_read_b128 v[232:235], v151 offset:2048
	ds_read_b128 v[236:239], v151 offset:3072
	global_load_lds_dwordx4 v[244:245], off
	v_lshl_add_u64 v[244:245], v[142:143], 0, s[10:11]
	v_lshl_add_u64 v[246:247], v[244:245], 0, s[88:89]
	s_add_i32 m0, s29, 0x2000
	s_nop 0
	global_load_lds_dwordx4 v[246:247], off
	s_barrier
	s_waitcnt lgkmcnt(0)
	s_waitcnt lgkmcnt(0)
	v_mfma_f32_16x16x32_bf16 v[92:95], v[224:227], v[168:171], v[92:95]
	v_mfma_f32_16x16x32_bf16 v[88:91], v[232:235], v[168:171], v[88:91]
	v_mfma_f32_16x16x32_bf16 v[84:87], v[224:227], v[176:179], v[84:87]
	v_mfma_f32_16x16x32_bf16 v[80:83], v[232:235], v[176:179], v[80:83]
	v_mfma_f32_16x16x32_bf16 v[76:79], v[224:227], v[208:211], v[76:79]
	v_mfma_f32_16x16x32_bf16 v[72:75], v[232:235], v[208:211], v[72:75]
	v_mfma_f32_16x16x32_bf16 v[68:71], v[224:227], v[216:219], v[68:71]
	v_mfma_f32_16x16x32_bf16 v[64:67], v[232:235], v[216:219], v[64:67]
	v_mfma_f32_16x16x32_bf16 v[92:95], v[228:231], v[172:175], v[92:95]
	v_mfma_f32_16x16x32_bf16 v[88:91], v[236:239], v[172:175], v[88:91]
	v_mfma_f32_16x16x32_bf16 v[84:87], v[228:231], v[204:207], v[84:87]
	v_mfma_f32_16x16x32_bf16 v[80:83], v[236:239], v[204:207], v[80:83]
	v_mfma_f32_16x16x32_bf16 v[76:79], v[228:231], v[212:215], v[76:79]
	v_mfma_f32_16x16x32_bf16 v[72:75], v[236:239], v[212:215], v[72:75]
	v_mfma_f32_16x16x32_bf16 v[68:71], v[228:231], v[220:223], v[68:71]
	v_mfma_f32_16x16x32_bf16 v[64:67], v[236:239], v[220:223], v[64:67]
	s_mov_b32 m0, s13
	v_lshl_add_u64 v[246:247], v[188:189], 0, s[88:89]
	s_barrier
	ds_read_b128 v[168:171], v150 offset:16384
	ds_read_b128 v[172:175], v150 offset:17408
	ds_read_b128 v[176:179], v150 offset:18432
	ds_read_b128 v[204:207], v150 offset:19456
	ds_read_b128 v[208:211], v150 offset:20480
	ds_read_b128 v[212:215], v150 offset:21504
	ds_read_b128 v[216:219], v150 offset:22528
	ds_read_b128 v[220:223], v150 offset:23552
	global_load_lds_dwordx4 v[246:247], off
	v_lshl_add_u64 v[246:247], v[240:241], 0, s[88:89]
	s_mov_b32 m0, s16
	s_nop 0
	global_load_lds_dwordx4 v[246:247], off
	s_barrier
	s_waitcnt lgkmcnt(0)
	s_waitcnt lgkmcnt(0)
	v_mfma_f32_16x16x32_bf16 v[60:63], v[152:155], v[168:171], v[60:63]
	v_mfma_f32_16x16x32_bf16 v[56:59], v[160:163], v[168:171], v[56:59]
	v_mfma_f32_16x16x32_bf16 v[52:55], v[152:155], v[176:179], v[52:55]
	v_mfma_f32_16x16x32_bf16 v[48:51], v[160:163], v[176:179], v[48:51]
	v_mfma_f32_16x16x32_bf16 v[44:47], v[152:155], v[208:211], v[44:47]
	v_mfma_f32_16x16x32_bf16 v[40:43], v[160:163], v[208:211], v[40:43]
	v_mfma_f32_16x16x32_bf16 v[36:39], v[152:155], v[216:219], v[36:39]
	v_mfma_f32_16x16x32_bf16 v[32:35], v[160:163], v[216:219], v[32:35]
	v_mfma_f32_16x16x32_bf16 v[60:63], v[156:159], v[172:175], v[60:63]
	v_mfma_f32_16x16x32_bf16 v[56:59], v[164:167], v[172:175], v[56:59]
	v_mfma_f32_16x16x32_bf16 v[52:55], v[156:159], v[204:207], v[52:55]
	v_mfma_f32_16x16x32_bf16 v[48:51], v[164:167], v[204:207], v[48:51]
	v_mfma_f32_16x16x32_bf16 v[44:47], v[156:159], v[212:215], v[44:47]
	v_mfma_f32_16x16x32_bf16 v[40:43], v[164:167], v[212:215], v[40:43]
	v_mfma_f32_16x16x32_bf16 v[36:39], v[156:159], v[220:223], v[36:39]
	v_mfma_f32_16x16x32_bf16 v[32:35], v[164:167], v[220:223], v[32:35]
	s_barrier
	s_add_i32 s29, s30, s12
	v_lshl_add_u64 v[152:153], v[242:243], 0, s[36:37]
	s_mov_b32 m0, s29
	s_nop 0
	global_load_lds_dwordx4 v[152:153], off
	v_lshl_add_u64 v[152:153], v[244:245], 0, s[36:37]
	s_add_i32 m0, s29, 0x2000
	s_nop 0
	global_load_lds_dwordx4 v[152:153], off
	s_waitcnt vmcnt(6)
	s_barrier
	v_mfma_f32_16x16x32_bf16 v[28:31], v[224:227], v[168:171], v[28:31]
	v_mfma_f32_16x16x32_bf16 v[24:27], v[232:235], v[168:171], v[24:27]
	v_mfma_f32_16x16x32_bf16 v[20:23], v[224:227], v[176:179], v[20:23]
	v_mfma_f32_16x16x32_bf16 v[16:19], v[232:235], v[176:179], v[16:19]
	v_mfma_f32_16x16x32_bf16 v[12:15], v[224:227], v[208:211], v[12:15]
	v_mfma_f32_16x16x32_bf16 v[8:11], v[232:235], v[208:211], v[8:11]
	v_mfma_f32_16x16x32_bf16 v[4:7], v[224:227], v[216:219], v[4:7]
	v_mfma_f32_16x16x32_bf16 v[0:3], v[232:235], v[216:219], v[0:3]
	v_mfma_f32_16x16x32_bf16 v[28:31], v[228:231], v[172:175], v[28:31]
	v_mfma_f32_16x16x32_bf16 v[24:27], v[236:239], v[172:175], v[24:27]
	v_mfma_f32_16x16x32_bf16 v[20:23], v[228:231], v[204:207], v[20:23]
	v_mfma_f32_16x16x32_bf16 v[16:19], v[236:239], v[204:207], v[16:19]
	v_mfma_f32_16x16x32_bf16 v[12:15], v[228:231], v[212:215], v[12:15]
	v_mfma_f32_16x16x32_bf16 v[8:11], v[236:239], v[212:215], v[8:11]
	v_mfma_f32_16x16x32_bf16 v[4:7], v[228:231], v[220:223], v[4:7]
	v_mfma_f32_16x16x32_bf16 v[0:3], v[236:239], v[220:223], v[0:3]
	s_add_i32 s29, 32, 0x18000
	v_add_u32_e32 v151, s29, v148
	s_barrier
	ds_read_b128 v[152:155], v151
	ds_read_b128 v[156:159], v151 offset:1024
	ds_read_b128 v[160:163], v151 offset:2048
	ds_read_b128 v[164:167], v151 offset:3072
	s_mov_b32 m0, s19
	v_lshl_add_u64 v[224:225], v[188:189], 0, s[36:37]
	ds_read_b128 v[168:171], v150 offset:32768
	ds_read_b128 v[172:175], v150 offset:33792
	ds_read_b128 v[176:179], v150 offset:34816
	ds_read_b128 v[204:207], v150 offset:35840
	ds_read_b128 v[208:211], v150 offset:36864
	ds_read_b128 v[212:215], v150 offset:37888
	ds_read_b128 v[216:219], v150 offset:38912
	ds_read_b128 v[220:223], v150 offset:39936
	global_load_lds_dwordx4 v[224:225], off
	v_lshl_add_u64 v[224:225], v[240:241], 0, s[36:37]
	s_mov_b32 m0, s20
	s_nop 0
	global_load_lds_dwordx4 v[224:225], off
	s_waitcnt lgkmcnt(8)
	s_barrier
	s_waitcnt lgkmcnt(0)
	s_waitcnt lgkmcnt(0)
	v_mfma_f32_16x16x32_bf16 v[124:127], v[152:155], v[168:171], v[124:127]
	v_mfma_f32_16x16x32_bf16 v[120:123], v[160:163], v[168:171], v[120:123]
	v_mfma_f32_16x16x32_bf16 v[116:119], v[152:155], v[176:179], v[116:119]
	v_mfma_f32_16x16x32_bf16 v[112:115], v[160:163], v[176:179], v[112:115]
	v_mfma_f32_16x16x32_bf16 v[108:111], v[152:155], v[208:211], v[108:111]
	v_mfma_f32_16x16x32_bf16 v[104:107], v[160:163], v[208:211], v[104:107]
	v_mfma_f32_16x16x32_bf16 v[100:103], v[152:155], v[216:219], v[100:103]
	v_mfma_f32_16x16x32_bf16 v[96:99], v[160:163], v[216:219], v[96:99]
	v_mfma_f32_16x16x32_bf16 v[124:127], v[156:159], v[172:175], v[124:127]
	v_mfma_f32_16x16x32_bf16 v[120:123], v[164:167], v[172:175], v[120:123]
	v_mfma_f32_16x16x32_bf16 v[116:119], v[156:159], v[204:207], v[116:119]
	v_mfma_f32_16x16x32_bf16 v[112:115], v[164:167], v[204:207], v[112:115]
	v_mfma_f32_16x16x32_bf16 v[108:111], v[156:159], v[212:215], v[108:111]
	v_mfma_f32_16x16x32_bf16 v[104:107], v[164:167], v[212:215], v[104:107]
	v_mfma_f32_16x16x32_bf16 v[100:103], v[156:159], v[220:223], v[100:103]
	v_mfma_f32_16x16x32_bf16 v[96:99], v[164:167], v[220:223], v[96:99]
	s_barrier
	s_add_i32 s30, 32, 0x1c000
	s_add_i32 s29, s29, s12
	v_add_u32_e32 v151, s30, v148
	v_lshl_add_u64 v[246:247], v[242:243], 0, s[90:91]
	s_mov_b32 m0, s29
	ds_read_b128 v[224:227], v151
	ds_read_b128 v[228:231], v151 offset:1024
	ds_read_b128 v[232:235], v151 offset:2048
	ds_read_b128 v[236:239], v151 offset:3072
	global_load_lds_dwordx4 v[246:247], off
	v_lshl_add_u64 v[246:247], v[244:245], 0, s[90:91]
	s_add_i32 m0, s29, 0x2000
	s_nop 0
	global_load_lds_dwordx4 v[246:247], off
	s_barrier
	s_waitcnt lgkmcnt(0)
	s_waitcnt lgkmcnt(0)
	v_mfma_f32_16x16x32_bf16 v[92:95], v[224:227], v[168:171], v[92:95]
	v_mfma_f32_16x16x32_bf16 v[88:91], v[232:235], v[168:171], v[88:91]
	v_mfma_f32_16x16x32_bf16 v[84:87], v[224:227], v[176:179], v[84:87]
	v_mfma_f32_16x16x32_bf16 v[80:83], v[232:235], v[176:179], v[80:83]
	v_mfma_f32_16x16x32_bf16 v[76:79], v[224:227], v[208:211], v[76:79]
	v_mfma_f32_16x16x32_bf16 v[72:75], v[232:235], v[208:211], v[72:75]
	v_mfma_f32_16x16x32_bf16 v[68:71], v[224:227], v[216:219], v[68:71]
	v_mfma_f32_16x16x32_bf16 v[64:67], v[232:235], v[216:219], v[64:67]
	v_mfma_f32_16x16x32_bf16 v[92:95], v[228:231], v[172:175], v[92:95]
	v_mfma_f32_16x16x32_bf16 v[88:91], v[236:239], v[172:175], v[88:91]
	v_mfma_f32_16x16x32_bf16 v[84:87], v[228:231], v[204:207], v[84:87]
	v_mfma_f32_16x16x32_bf16 v[80:83], v[236:239], v[204:207], v[80:83]
	v_mfma_f32_16x16x32_bf16 v[76:79], v[228:231], v[212:215], v[76:79]
	v_mfma_f32_16x16x32_bf16 v[72:75], v[236:239], v[212:215], v[72:75]
	v_mfma_f32_16x16x32_bf16 v[68:71], v[228:231], v[220:223], v[68:71]
	v_mfma_f32_16x16x32_bf16 v[64:67], v[236:239], v[220:223], v[64:67]
	s_mov_b32 m0, s22
	v_lshl_add_u64 v[188:189], v[188:189], 0, s[90:91]
	s_barrier
	ds_read_b128 v[168:171], v150 offset:49152
	ds_read_b128 v[172:175], v150 offset:50176
	ds_read_b128 v[176:179], v150 offset:51200
	ds_read_b128 v[204:207], v150 offset:52224
	ds_read_b128 v[208:211], v150 offset:53248
	ds_read_b128 v[212:215], v150 offset:54272
	ds_read_b128 v[216:219], v150 offset:55296
	ds_read_b128 v[220:223], v150 offset:56320
	global_load_lds_dwordx4 v[188:189], off
	v_lshl_add_u64 v[188:189], v[240:241], 0, s[90:91]
	s_mov_b32 m0, s23
	s_nop 0
	global_load_lds_dwordx4 v[188:189], off
	s_barrier
	s_waitcnt lgkmcnt(0)
	s_waitcnt lgkmcnt(0)
	v_mfma_f32_16x16x32_bf16 v[60:63], v[152:155], v[168:171], v[60:63]
	v_mfma_f32_16x16x32_bf16 v[56:59], v[160:163], v[168:171], v[56:59]
	v_mfma_f32_16x16x32_bf16 v[52:55], v[152:155], v[176:179], v[52:55]
	v_mfma_f32_16x16x32_bf16 v[48:51], v[160:163], v[176:179], v[48:51]
	v_mfma_f32_16x16x32_bf16 v[44:47], v[152:155], v[208:211], v[44:47]
	v_mfma_f32_16x16x32_bf16 v[40:43], v[160:163], v[208:211], v[40:43]
	v_mfma_f32_16x16x32_bf16 v[36:39], v[152:155], v[216:219], v[36:39]
	v_mfma_f32_16x16x32_bf16 v[32:35], v[160:163], v[216:219], v[32:35]
	v_mfma_f32_16x16x32_bf16 v[60:63], v[156:159], v[172:175], v[60:63]
	v_mfma_f32_16x16x32_bf16 v[56:59], v[164:167], v[172:175], v[56:59]
	v_mfma_f32_16x16x32_bf16 v[52:55], v[156:159], v[204:207], v[52:55]
	v_mfma_f32_16x16x32_bf16 v[48:51], v[164:167], v[204:207], v[48:51]
	v_mfma_f32_16x16x32_bf16 v[44:47], v[156:159], v[212:215], v[44:47]
	v_mfma_f32_16x16x32_bf16 v[40:43], v[164:167], v[212:215], v[40:43]
	v_mfma_f32_16x16x32_bf16 v[36:39], v[156:159], v[220:223], v[36:39]
	v_mfma_f32_16x16x32_bf16 v[32:35], v[164:167], v[220:223], v[32:35]
	s_barrier
	s_add_i32 s29, s30, s12
	v_lshl_add_u64 v[152:153], v[242:243], 0, s[48:49]
	s_mov_b32 m0, s29
	s_nop 0
	global_load_lds_dwordx4 v[152:153], off
	v_lshl_add_u64 v[152:153], v[244:245], 0, s[48:49]
	s_add_i32 m0, s29, 0x2000
	s_nop 0
	global_load_lds_dwordx4 v[152:153], off
	s_waitcnt vmcnt(6)
	s_barrier
	v_mfma_f32_16x16x32_bf16 v[28:31], v[224:227], v[168:171], v[28:31]
	v_mfma_f32_16x16x32_bf16 v[24:27], v[232:235], v[168:171], v[24:27]
	v_mfma_f32_16x16x32_bf16 v[20:23], v[224:227], v[176:179], v[20:23]
	v_mfma_f32_16x16x32_bf16 v[16:19], v[232:235], v[176:179], v[16:19]
	v_mfma_f32_16x16x32_bf16 v[12:15], v[224:227], v[208:211], v[12:15]
	v_mfma_f32_16x16x32_bf16 v[8:11], v[232:235], v[208:211], v[8:11]
	v_mfma_f32_16x16x32_bf16 v[4:7], v[224:227], v[216:219], v[4:7]
	v_mfma_f32_16x16x32_bf16 v[0:3], v[232:235], v[216:219], v[0:3]
	v_mfma_f32_16x16x32_bf16 v[28:31], v[228:231], v[172:175], v[28:31]
	v_mfma_f32_16x16x32_bf16 v[24:27], v[236:239], v[172:175], v[24:27]
	v_mfma_f32_16x16x32_bf16 v[20:23], v[228:231], v[204:207], v[20:23]
	v_mfma_f32_16x16x32_bf16 v[16:19], v[236:239], v[204:207], v[16:19]
	v_mfma_f32_16x16x32_bf16 v[12:15], v[228:231], v[212:215], v[12:15]
	v_mfma_f32_16x16x32_bf16 v[8:11], v[236:239], v[212:215], v[8:11]
	v_mfma_f32_16x16x32_bf16 v[4:7], v[228:231], v[220:223], v[4:7]
	v_mfma_f32_16x16x32_bf16 v[0:3], v[236:239], v[220:223], v[0:3]
	s_add_i32 s26, s26, 2
	s_add_u32 s10, s10, 0x100
	s_addc_u32 s11, s11, 0
	s_cmp_gt_u32 s26, 39
	s_barrier
	s_cbranch_scc0 .LBB0_2030
	s_add_u32 s10, s8, 0xb1580
	v_add_u32_e32 v151, 32, v148
	s_addc_u32 s11, s9, 0
	s_mov_b32 m0, s28
	v_add_u32_e32 v156, 0x10000, v151
	v_lshl_add_u64 v[188:189], s[10:11], 0, v[128:129]
	ds_read_b128 v[140:143], v156
	ds_read_b128 v[144:147], v156 offset:1024
	ds_read_b128 v[152:155], v156 offset:2048
	ds_read_b128 v[156:159], v156 offset:3072
	ds_read_b128 v[160:163], v150
	ds_read_b128 v[164:167], v150 offset:1024
	ds_read_b128 v[168:171], v150 offset:2048
	ds_read_b128 v[172:175], v150 offset:3072
	ds_read_b128 v[176:179], v150 offset:4096
	ds_read_b128 v[204:207], v150 offset:5120
	ds_read_b128 v[208:211], v150 offset:6144
	ds_read_b128 v[212:215], v150 offset:7168
	global_load_lds_dwordx4 v[188:189], off
	v_lshl_add_u64 v[188:189], s[10:11], 0, v[134:135]
	s_mov_b32 m0, s27
	s_nop 0
	global_load_lds_dwordx4 v[188:189], off
	s_barrier
	s_waitcnt lgkmcnt(0)
	s_waitcnt lgkmcnt(0)
	v_mfma_f32_16x16x32_bf16 v[124:127], v[140:143], v[160:163], v[124:127]
	v_mfma_f32_16x16x32_bf16 v[120:123], v[152:155], v[160:163], v[120:123]
	v_mfma_f32_16x16x32_bf16 v[116:119], v[140:143], v[168:171], v[116:119]
	v_mfma_f32_16x16x32_bf16 v[112:115], v[152:155], v[168:171], v[112:115]
	v_mfma_f32_16x16x32_bf16 v[108:111], v[140:143], v[176:179], v[108:111]
	v_mfma_f32_16x16x32_bf16 v[104:107], v[152:155], v[176:179], v[104:107]
	v_mfma_f32_16x16x32_bf16 v[100:103], v[140:143], v[208:211], v[100:103]
	v_mfma_f32_16x16x32_bf16 v[96:99], v[152:155], v[208:211], v[96:99]
	v_mfma_f32_16x16x32_bf16 v[124:127], v[144:147], v[164:167], v[124:127]
	v_mfma_f32_16x16x32_bf16 v[120:123], v[156:159], v[164:167], v[120:123]
	v_mfma_f32_16x16x32_bf16 v[116:119], v[144:147], v[172:175], v[116:119]
	v_mfma_f32_16x16x32_bf16 v[112:115], v[156:159], v[172:175], v[112:115]
	v_mfma_f32_16x16x32_bf16 v[108:111], v[144:147], v[204:207], v[108:111]
	v_mfma_f32_16x16x32_bf16 v[104:107], v[156:159], v[204:207], v[104:107]
	v_mfma_f32_16x16x32_bf16 v[100:103], v[144:147], v[212:215], v[100:103]
	v_mfma_f32_16x16x32_bf16 v[96:99], v[156:159], v[212:215], v[96:99]
	v_add_u32_e32 v188, 0x14000, v151
	s_barrier
	ds_read_b128 v[216:219], v188
	ds_read_b128 v[220:223], v188 offset:1024
	ds_read_b128 v[224:227], v188 offset:2048
	ds_read_b128 v[228:231], v188 offset:3072
	s_barrier
	s_waitcnt lgkmcnt(0)
	s_waitcnt lgkmcnt(0)
	v_mfma_f32_16x16x32_bf16 v[88:91], v[224:227], v[160:163], v[88:91]
	v_mfma_f32_16x16x32_bf16 v[84:87], v[216:219], v[168:171], v[84:87]
	v_mfma_f32_16x16x32_bf16 v[80:83], v[224:227], v[168:171], v[80:83]
	v_mfma_f32_16x16x32_bf16 v[76:79], v[216:219], v[176:179], v[76:79]
	v_mfma_f32_16x16x32_bf16 v[72:75], v[224:227], v[176:179], v[72:75]
	v_mfma_f32_16x16x32_bf16 v[68:71], v[216:219], v[208:211], v[68:71]
	v_mfma_f32_16x16x32_bf16 v[64:67], v[224:227], v[208:211], v[64:67]
	v_mfma_f32_16x16x32_bf16 v[92:95], v[216:219], v[160:163], v[92:95]
	v_mfma_f32_16x16x32_bf16 v[88:91], v[228:231], v[164:167], v[88:91]
	v_mfma_f32_16x16x32_bf16 v[84:87], v[220:223], v[172:175], v[84:87]
	v_mfma_f32_16x16x32_bf16 v[80:83], v[228:231], v[172:175], v[80:83]
	v_mfma_f32_16x16x32_bf16 v[76:79], v[220:223], v[204:207], v[76:79]
	v_mfma_f32_16x16x32_bf16 v[72:75], v[228:231], v[204:207], v[72:75]
	v_mfma_f32_16x16x32_bf16 v[68:71], v[220:223], v[212:215], v[68:71]
	v_mfma_f32_16x16x32_bf16 v[64:67], v[228:231], v[212:215], v[64:67]
	v_mfma_f32_16x16x32_bf16 v[232:235], v[220:223], v[164:167], v[92:95]
	s_barrier
	s_nop 0
	ds_read_b128 v[92:95], v150 offset:16384
	ds_read_b128 v[160:163], v150 offset:17408
	ds_read_b128 v[164:167], v150 offset:18432
	ds_read_b128 v[168:171], v150 offset:19456
	ds_read_b128 v[172:175], v150 offset:20480
	ds_read_b128 v[176:179], v150 offset:21504
	ds_read_b128 v[204:207], v150 offset:22528
	ds_read_b128 v[208:211], v150 offset:23552
	s_waitcnt vmcnt(4)
	s_barrier
	s_waitcnt lgkmcnt(0)
	s_waitcnt lgkmcnt(0)
	v_mfma_f32_16x16x32_bf16 v[56:59], v[152:155], v[92:95], v[56:59]
	v_mfma_f32_16x16x32_bf16 v[52:55], v[140:143], v[164:167], v[52:55]
	v_mfma_f32_16x16x32_bf16 v[48:51], v[152:155], v[164:167], v[48:51]
	v_mfma_f32_16x16x32_bf16 v[44:47], v[140:143], v[172:175], v[44:47]
	v_mfma_f32_16x16x32_bf16 v[40:43], v[152:155], v[172:175], v[40:43]
	v_mfma_f32_16x16x32_bf16 v[36:39], v[140:143], v[204:207], v[36:39]
	v_mfma_f32_16x16x32_bf16 v[32:35], v[152:155], v[204:207], v[32:35]
	v_mfma_f32_16x16x32_bf16 v[60:63], v[140:143], v[92:95], v[60:63]
	v_mfma_f32_16x16x32_bf16 v[56:59], v[156:159], v[160:163], v[56:59]
	v_mfma_f32_16x16x32_bf16 v[52:55], v[144:147], v[168:171], v[52:55]
	v_mfma_f32_16x16x32_bf16 v[48:51], v[156:159], v[168:171], v[48:51]
	v_mfma_f32_16x16x32_bf16 v[44:47], v[144:147], v[176:179], v[44:47]
	v_mfma_f32_16x16x32_bf16 v[40:43], v[156:159], v[176:179], v[40:43]
	v_mfma_f32_16x16x32_bf16 v[36:39], v[144:147], v[208:211], v[36:39]
	v_mfma_f32_16x16x32_bf16 v[32:35], v[156:159], v[208:211], v[32:35]
	v_mfma_f32_16x16x32_bf16 v[212:215], v[144:147], v[160:163], v[60:63]
	v_mfma_f32_16x16x32_bf16 v[28:31], v[216:219], v[92:95], v[28:31]
	v_mfma_f32_16x16x32_bf16 v[24:27], v[224:227], v[92:95], v[24:27]
	v_mfma_f32_16x16x32_bf16 v[20:23], v[216:219], v[164:167], v[20:23]
	v_mfma_f32_16x16x32_bf16 v[16:19], v[224:227], v[164:167], v[16:19]
	v_mfma_f32_16x16x32_bf16 v[12:15], v[216:219], v[172:175], v[12:15]
	v_mfma_f32_16x16x32_bf16 v[8:11], v[224:227], v[172:175], v[8:11]
	v_mfma_f32_16x16x32_bf16 v[4:7], v[216:219], v[204:207], v[4:7]
	v_mfma_f32_16x16x32_bf16 v[0:3], v[224:227], v[204:207], v[0:3]
	v_mfma_f32_16x16x32_bf16 v[28:31], v[220:223], v[160:163], v[28:31]
	v_mfma_f32_16x16x32_bf16 v[24:27], v[228:231], v[160:163], v[24:27]
	v_mfma_f32_16x16x32_bf16 v[20:23], v[220:223], v[168:171], v[20:23]
	v_mfma_f32_16x16x32_bf16 v[16:19], v[228:231], v[168:171], v[16:19]
	v_mfma_f32_16x16x32_bf16 v[12:15], v[220:223], v[176:179], v[12:15]
	v_mfma_f32_16x16x32_bf16 v[8:11], v[228:231], v[176:179], v[8:11]
	v_mfma_f32_16x16x32_bf16 v[4:7], v[220:223], v[208:211], v[4:7]
	v_mfma_f32_16x16x32_bf16 v[0:3], v[228:231], v[208:211], v[0:3]
	v_add_u32_e32 v60, 0x18000, v151
	s_barrier
	ds_read_b128 v[140:143], v60
	ds_read_b128 v[144:147], v60 offset:1024
	ds_read_b128 v[152:155], v60 offset:2048
	ds_read_b128 v[156:159], v60 offset:3072
	ds_read_b128 v[60:63], v150 offset:32768
	ds_read_b128 v[160:163], v150 offset:33792
	ds_read_b128 v[164:167], v150 offset:34816
	ds_read_b128 v[168:171], v150 offset:35840
	ds_read_b128 v[172:175], v150 offset:36864
	ds_read_b128 v[176:179], v150 offset:37888
	ds_read_b128 v[204:207], v150 offset:38912
	ds_read_b128 v[208:211], v150 offset:39936
	s_waitcnt vmcnt(2)
	s_barrier
	s_waitcnt lgkmcnt(0)
	s_waitcnt lgkmcnt(0)
	v_mfma_f32_16x16x32_bf16 v[92:95], v[140:143], v[60:63], v[124:127]
	v_mfma_f32_16x16x32_bf16 v[124:127], v[144:147], v[160:163], v[92:95]
	v_mfma_f32_16x16x32_bf16 v[92:95], v[152:155], v[60:63], v[120:123]
	v_mfma_f32_16x16x32_bf16 v[120:123], v[156:159], v[160:163], v[92:95]
	v_mfma_f32_16x16x32_bf16 v[92:95], v[140:143], v[164:167], v[116:119]
	v_mfma_f32_16x16x32_bf16 v[116:119], v[144:147], v[168:171], v[92:95]
	v_mfma_f32_16x16x32_bf16 v[92:95], v[152:155], v[164:167], v[112:115]
	v_mfma_f32_16x16x32_bf16 v[112:115], v[156:159], v[168:171], v[92:95]
	v_mfma_f32_16x16x32_bf16 v[92:95], v[140:143], v[172:175], v[108:111]
	v_mfma_f32_16x16x32_bf16 v[108:111], v[144:147], v[176:179], v[92:95]
	v_mfma_f32_16x16x32_bf16 v[92:95], v[152:155], v[172:175], v[104:107]
	v_mfma_f32_16x16x32_bf16 v[104:107], v[156:159], v[176:179], v[92:95]
	v_mfma_f32_16x16x32_bf16 v[92:95], v[140:143], v[204:207], v[100:103]
	v_mfma_f32_16x16x32_bf16 v[100:103], v[144:147], v[208:211], v[92:95]
	v_mfma_f32_16x16x32_bf16 v[92:95], v[152:155], v[204:207], v[96:99]
	v_mfma_f32_16x16x32_bf16 v[92:95], v[156:159], v[208:211], v[92:95]
	s_nop 0
	v_add_u32_e32 v96, 0x1c000, v151
	s_barrier
	ds_read_b128 v[216:219], v96
	ds_read_b128 v[220:223], v96 offset:1024
	ds_read_b128 v[224:227], v96 offset:2048
	ds_read_b128 v[228:231], v96 offset:3072
	s_waitcnt vmcnt(0)
	s_barrier
	s_waitcnt lgkmcnt(0)
	s_waitcnt lgkmcnt(0)
	v_mfma_f32_16x16x32_bf16 v[96:99], v[216:219], v[60:63], v[232:235]
	v_mfma_f32_16x16x32_bf16 v[60:63], v[224:227], v[60:63], v[88:91]
	v_mfma_f32_16x16x32_bf16 v[88:91], v[228:231], v[160:163], v[60:63]
	v_mfma_f32_16x16x32_bf16 v[60:63], v[216:219], v[164:167], v[84:87]
	v_mfma_f32_16x16x32_bf16 v[84:87], v[220:223], v[168:171], v[60:63]
	v_mfma_f32_16x16x32_bf16 v[60:63], v[224:227], v[164:167], v[80:83]
	v_mfma_f32_16x16x32_bf16 v[80:83], v[228:231], v[168:171], v[60:63]
	v_mfma_f32_16x16x32_bf16 v[60:63], v[216:219], v[172:175], v[76:79]
	v_mfma_f32_16x16x32_bf16 v[76:79], v[220:223], v[176:179], v[60:63]
	v_mfma_f32_16x16x32_bf16 v[60:63], v[224:227], v[172:175], v[72:75]
	v_mfma_f32_16x16x32_bf16 v[72:75], v[228:231], v[176:179], v[60:63]
	v_mfma_f32_16x16x32_bf16 v[60:63], v[216:219], v[204:207], v[68:71]
	v_mfma_f32_16x16x32_bf16 v[68:71], v[220:223], v[208:211], v[60:63]
	v_mfma_f32_16x16x32_bf16 v[60:63], v[224:227], v[204:207], v[64:67]
	v_mfma_f32_16x16x32_bf16 v[96:99], v[220:223], v[160:163], v[96:99]
	v_mfma_f32_16x16x32_bf16 v[60:63], v[228:231], v[208:211], v[60:63]
	s_barrier
	ds_read_b128 v[160:163], v150 offset:49152
	ds_read_b128 v[164:167], v150 offset:50176
	ds_read_b128 v[168:171], v150 offset:51200
	ds_read_b128 v[172:175], v150 offset:52224
	ds_read_b128 v[176:179], v150 offset:53248
	ds_read_b128 v[204:207], v150 offset:54272
	ds_read_b128 v[208:211], v150 offset:55296
	ds_read_b128 v[232:235], v150 offset:56320
	s_barrier
	s_waitcnt lgkmcnt(0)
	s_waitcnt lgkmcnt(0)
	v_mfma_f32_16x16x32_bf16 v[64:67], v[140:143], v[160:163], v[212:215]
	v_mfma_f32_16x16x32_bf16 v[56:59], v[152:155], v[160:163], v[56:59]
	v_mfma_f32_16x16x32_bf16 v[52:55], v[140:143], v[168:171], v[52:55]
	v_mfma_f32_16x16x32_bf16 v[48:51], v[152:155], v[168:171], v[48:51]
	v_mfma_f32_16x16x32_bf16 v[44:47], v[140:143], v[176:179], v[44:47]
	v_mfma_f32_16x16x32_bf16 v[40:43], v[152:155], v[176:179], v[40:43]
	v_mfma_f32_16x16x32_bf16 v[36:39], v[140:143], v[208:211], v[36:39]
	v_mfma_f32_16x16x32_bf16 v[32:35], v[152:155], v[208:211], v[32:35]
	v_mfma_f32_16x16x32_bf16 v[64:67], v[144:147], v[164:167], v[64:67]
	v_mfma_f32_16x16x32_bf16 v[56:59], v[156:159], v[164:167], v[56:59]
	v_mfma_f32_16x16x32_bf16 v[52:55], v[144:147], v[172:175], v[52:55]
	v_mfma_f32_16x16x32_bf16 v[48:51], v[156:159], v[172:175], v[48:51]
	v_mfma_f32_16x16x32_bf16 v[44:47], v[144:147], v[204:207], v[44:47]
	v_mfma_f32_16x16x32_bf16 v[40:43], v[156:159], v[204:207], v[40:43]
	v_mfma_f32_16x16x32_bf16 v[36:39], v[144:147], v[232:235], v[36:39]
	v_mfma_f32_16x16x32_bf16 v[32:35], v[156:159], v[232:235], v[32:35]
	v_mfma_f32_16x16x32_bf16 v[28:31], v[216:219], v[160:163], v[28:31]
	v_mfma_f32_16x16x32_bf16 v[24:27], v[224:227], v[160:163], v[24:27]
	v_mfma_f32_16x16x32_bf16 v[20:23], v[216:219], v[168:171], v[20:23]
	v_mfma_f32_16x16x32_bf16 v[16:19], v[224:227], v[168:171], v[16:19]
	v_mfma_f32_16x16x32_bf16 v[12:15], v[216:219], v[176:179], v[12:15]
	v_mfma_f32_16x16x32_bf16 v[8:11], v[224:227], v[176:179], v[8:11]
	v_mfma_f32_16x16x32_bf16 v[4:7], v[216:219], v[208:211], v[4:7]
	v_mfma_f32_16x16x32_bf16 v[0:3], v[224:227], v[208:211], v[0:3]
	v_mfma_f32_16x16x32_bf16 v[28:31], v[220:223], v[164:167], v[28:31]
	v_mfma_f32_16x16x32_bf16 v[24:27], v[228:231], v[164:167], v[24:27]
	v_mfma_f32_16x16x32_bf16 v[20:23], v[220:223], v[172:175], v[20:23]
	v_mfma_f32_16x16x32_bf16 v[16:19], v[228:231], v[172:175], v[16:19]
	v_mfma_f32_16x16x32_bf16 v[12:15], v[220:223], v[204:207], v[12:15]
	v_mfma_f32_16x16x32_bf16 v[8:11], v[228:231], v[204:207], v[8:11]
	v_mfma_f32_16x16x32_bf16 v[4:7], v[220:223], v[232:235], v[4:7]
	v_mfma_f32_16x16x32_bf16 v[0:3], v[228:231], v[232:235], v[0:3]
	s_barrier
	s_and_saveexec_b64 s[10:11], s[4:5]
	s_cbranch_execz .LBB0_2033
	s_barrier
